# GEMM main loops: in each load segment the LDS-DMA staging loads are issued before the ds_read fragment reads (same barrier epoch)
# baseline (speedup 1.0000x reference)
.LBB1_93:
	s_ashr_i32 s19, s18, 31
	s_lshl_b64 s[20:21], s[18:19], 19
	s_add_u32 s20, s33, s20
	s_addc_u32 s21, s34, s21
	s_and_b64 s[22:23], s[0:1], exec
	s_cselect_b32 s5, s21, s27
	s_cselect_b32 s19, s20, s26
	s_ashr_i32 s17, s16, 31
	s_lshl_b64 s[22:23], s[16:17], 19
	s_add_u32 s22, s35, s22
	s_addc_u32 s23, s36, s23
	s_and_b64 s[30:31], s[0:1], exec
	s_cselect_b32 s17, s23, s29
	s_cselect_b32 s25, s22, s28
	s_add_u32 s26, s26, 0x40080
	s_addc_u32 s27, s27, 0
	s_add_u32 s52, s28, 0x100
	s_addc_u32 s53, s29, 0
	s_mov_b32 s54, -2
	s_add_u32 s28, s26, 0xfffc0080
	s_addc_u32 s29, s27, -1
	s_cmp_eq_u32 s54, 12
	s_cselect_b32 s31, s5, s29
	s_cselect_b32 s30, s19, s28
	s_cselect_b32 s29, s17, s53
	s_cselect_b32 s28, s25, s52
	v_lshl_add_u64 v[216:217], s[26:27], 0, v[140:141]
	s_add_i32 m0, s38, 0xc000
	s_nop 0
	global_load_lds_dwordx4 v[216:217], off
	v_lshl_add_u64 v[216:217], s[26:27], 0, v[142:143]
	s_add_i32 m0, s38, 0xe000
	s_nop 0
	global_load_lds_dwordx4 v[216:217], off
	ds_read_b128 v[148:151], v153
	ds_read_b128 v[156:159], v153 offset:1024
	ds_read_b128 v[160:163], v153 offset:2048
	ds_read_b128 v[164:167], v153 offset:3072
	ds_read_b128 v[168:171], v154
	ds_read_b128 v[172:175], v154 offset:1024
	ds_read_b128 v[176:179], v154 offset:2048
	ds_read_b128 v[180:183], v154 offset:3072
	ds_read_b128 v[184:187], v155
	ds_read_b128 v[188:191], v155 offset:1024
	ds_read_b128 v[192:195], v155 offset:2048
	ds_read_b128 v[196:199], v155 offset:3072
	ds_read_b128 v[200:203], v155 offset:4096
	ds_read_b128 v[204:207], v155 offset:5120
	ds_read_b128 v[208:211], v155 offset:6144
	ds_read_b128 v[212:215], v155 offset:7168
	s_waitcnt vmcnt(8)
	s_waitcnt lgkmcnt(0)
	s_barrier
	s_setprio 1
	s_waitcnt lgkmcnt(0)
	v_mfma_f32_16x16x32_bf16 v[124:127], v[148:151], v[184:187], 0
	v_mfma_f32_16x16x32_bf16 v[120:123], v[160:163], v[184:187], 0
	v_mfma_f32_16x16x32_bf16 v[108:111], v[148:151], v[192:195], 0
	v_mfma_f32_16x16x32_bf16 v[104:107], v[160:163], v[192:195], 0
	v_mfma_f32_16x16x32_bf16 v[92:95], v[148:151], v[200:203], 0
	v_mfma_f32_16x16x32_bf16 v[88:91], v[160:163], v[200:203], 0
	v_mfma_f32_16x16x32_bf16 v[76:79], v[148:151], v[208:211], 0
	v_mfma_f32_16x16x32_bf16 v[72:75], v[160:163], v[208:211], 0
	v_mfma_f32_16x16x32_bf16 v[124:127], v[156:159], v[188:191], v[124:127]
	v_mfma_f32_16x16x32_bf16 v[120:123], v[164:167], v[188:191], v[120:123]
	v_mfma_f32_16x16x32_bf16 v[108:111], v[156:159], v[196:199], v[108:111]
	v_mfma_f32_16x16x32_bf16 v[104:107], v[164:167], v[196:199], v[104:107]
	v_mfma_f32_16x16x32_bf16 v[92:95], v[156:159], v[204:207], v[92:95]
	v_mfma_f32_16x16x32_bf16 v[88:91], v[164:167], v[204:207], v[88:91]
	v_mfma_f32_16x16x32_bf16 v[76:79], v[156:159], v[212:215], v[76:79]
	v_mfma_f32_16x16x32_bf16 v[72:75], v[164:167], v[212:215], v[72:75]
	s_setprio 0
	s_setprio 1
	v_mfma_f32_16x16x32_bf16 v[116:119], v[168:171], v[184:187], 0
	v_mfma_f32_16x16x32_bf16 v[112:115], v[176:179], v[184:187], 0
	v_mfma_f32_16x16x32_bf16 v[100:103], v[168:171], v[192:195], 0
	v_mfma_f32_16x16x32_bf16 v[96:99], v[176:179], v[192:195], 0
	v_mfma_f32_16x16x32_bf16 v[84:87], v[168:171], v[200:203], 0
	v_mfma_f32_16x16x32_bf16 v[80:83], v[176:179], v[200:203], 0
	v_mfma_f32_16x16x32_bf16 v[68:71], v[168:171], v[208:211], 0
	v_mfma_f32_16x16x32_bf16 v[64:67], v[176:179], v[208:211], 0
	v_mfma_f32_16x16x32_bf16 v[116:119], v[172:175], v[188:191], v[116:119]
	v_mfma_f32_16x16x32_bf16 v[112:115], v[180:183], v[188:191], v[112:115]
	v_mfma_f32_16x16x32_bf16 v[100:103], v[172:175], v[196:199], v[100:103]
	v_mfma_f32_16x16x32_bf16 v[96:99], v[180:183], v[196:199], v[96:99]
	v_mfma_f32_16x16x32_bf16 v[84:87], v[172:175], v[204:207], v[84:87]
	v_mfma_f32_16x16x32_bf16 v[80:83], v[180:183], v[204:207], v[80:83]
	v_mfma_f32_16x16x32_bf16 v[68:71], v[172:175], v[212:215], v[68:71]
	v_mfma_f32_16x16x32_bf16 v[64:67], v[180:183], v[212:215], v[64:67]
	s_setprio 0
	s_barrier
	s_add_i32 s55, s48, s37
	v_lshl_add_u64 v[216:217], s[28:29], 0, v[130:131]
	s_mov_b32 m0, s55
	s_nop 0
	global_load_lds_dwordx4 v[216:217], off
	s_add_i32 m0, s55, 0x2000
	s_add_u32 s56, s28, 0x40000
	v_lshl_add_u64 v[218:219], s[28:29], 0, v[134:135]
	s_addc_u32 s57, s29, 0
	s_add_i32 s55, s49, s37
	global_load_lds_dwordx4 v[218:219], off
	v_lshl_add_u64 v[220:221], s[56:57], 0, v[130:131]
	s_mov_b32 m0, s55
	v_lshl_add_u64 v[222:223], s[30:31], 0, v[132:133]
	global_load_lds_dwordx4 v[220:221], off
	v_lshl_add_u64 v[220:221], s[56:57], 0, v[134:135]
	s_add_i32 m0, s55, 0x2000
	s_nop 0
	global_load_lds_dwordx4 v[220:221], off
	v_lshl_add_u64 v[220:221], s[30:31], 0, v[128:129]
	s_mov_b32 m0, s38
	s_nop 0
	global_load_lds_dwordx4 v[220:221], off
	s_mov_b32 m0, s39
	s_nop 0
	global_load_lds_dwordx4 v[222:223], off
	ds_read_b128 v[184:187], v155 offset:16384
	ds_read_b128 v[188:191], v155 offset:17408
	ds_read_b128 v[192:195], v155 offset:18432
	ds_read_b128 v[196:199], v155 offset:19456
	ds_read_b128 v[200:203], v155 offset:20480
	ds_read_b128 v[204:207], v155 offset:21504
	ds_read_b128 v[208:211], v155 offset:22528
	ds_read_b128 v[212:215], v155 offset:23552
	s_waitcnt vmcnt(8)
	s_waitcnt lgkmcnt(0)
	s_barrier
	s_setprio 1
	s_waitcnt lgkmcnt(0)
	v_mfma_f32_16x16x32_bf16 v[60:63], v[148:151], v[184:187], 0
	v_mfma_f32_16x16x32_bf16 v[56:59], v[160:163], v[184:187], 0
	v_mfma_f32_16x16x32_bf16 v[44:47], v[148:151], v[192:195], 0
	v_mfma_f32_16x16x32_bf16 v[40:43], v[160:163], v[192:195], 0
	v_mfma_f32_16x16x32_bf16 v[28:31], v[148:151], v[200:203], 0
	v_mfma_f32_16x16x32_bf16 v[24:27], v[160:163], v[200:203], 0
	v_mfma_f32_16x16x32_bf16 v[12:15], v[148:151], v[208:211], 0
	v_mfma_f32_16x16x32_bf16 v[8:11], v[160:163], v[208:211], 0
	v_mfma_f32_16x16x32_bf16 v[60:63], v[156:159], v[188:191], v[60:63]
	v_mfma_f32_16x16x32_bf16 v[56:59], v[164:167], v[188:191], v[56:59]
	v_mfma_f32_16x16x32_bf16 v[44:47], v[156:159], v[196:199], v[44:47]
	v_mfma_f32_16x16x32_bf16 v[40:43], v[164:167], v[196:199], v[40:43]
	v_mfma_f32_16x16x32_bf16 v[28:31], v[156:159], v[204:207], v[28:31]
	v_mfma_f32_16x16x32_bf16 v[24:27], v[164:167], v[204:207], v[24:27]
	v_mfma_f32_16x16x32_bf16 v[12:15], v[156:159], v[212:215], v[12:15]
	v_mfma_f32_16x16x32_bf16 v[8:11], v[164:167], v[212:215], v[8:11]
	s_setprio 0
	s_setprio 1
	v_mfma_f32_16x16x32_bf16 v[52:55], v[168:171], v[184:187], 0
	v_mfma_f32_16x16x32_bf16 v[48:51], v[176:179], v[184:187], 0
	v_mfma_f32_16x16x32_bf16 v[36:39], v[168:171], v[192:195], 0
	v_mfma_f32_16x16x32_bf16 v[32:35], v[176:179], v[192:195], 0
	v_mfma_f32_16x16x32_bf16 v[20:23], v[168:171], v[200:203], 0
	v_mfma_f32_16x16x32_bf16 v[16:19], v[176:179], v[200:203], 0
	v_mfma_f32_16x16x32_bf16 v[4:7], v[168:171], v[208:211], 0
	v_mfma_f32_16x16x32_bf16 v[0:3], v[176:179], v[208:211], 0
	v_mfma_f32_16x16x32_bf16 v[52:55], v[172:175], v[188:191], v[52:55]
	v_mfma_f32_16x16x32_bf16 v[48:51], v[180:183], v[188:191], v[48:51]
	v_mfma_f32_16x16x32_bf16 v[36:39], v[172:175], v[196:199], v[36:39]
	v_mfma_f32_16x16x32_bf16 v[32:35], v[180:183], v[196:199], v[32:35]
	v_mfma_f32_16x16x32_bf16 v[20:23], v[172:175], v[204:207], v[20:23]
	v_mfma_f32_16x16x32_bf16 v[16:19], v[180:183], v[204:207], v[16:19]
	v_mfma_f32_16x16x32_bf16 v[4:7], v[172:175], v[212:215], v[4:7]
	v_mfma_f32_16x16x32_bf16 v[0:3], v[180:183], v[212:215], v[0:3]
	s_setprio 0
	s_barrier
	s_add_i32 s55, 0, 0x18000
	s_add_i32 s56, 0, 0x1c000
	v_add_u32_e32 v164, s55, v152
	v_add_u32_e32 v180, s56, v152
	s_add_u32 s30, s30, 0x40000
	s_addc_u32 s31, s31, 0
	s_mov_b32 m0, s40
	v_lshl_add_u64 v[224:225], s[30:31], 0, v[128:129]
	global_load_lds_dwordx4 v[224:225], off
	v_lshl_add_u64 v[224:225], s[30:31], 0, v[132:133]
	s_mov_b32 m0, s41
	s_nop 0
	global_load_lds_dwordx4 v[224:225], off
	ds_read_b128 v[148:151], v164
	ds_read_b128 v[156:159], v164 offset:1024
	ds_read_b128 v[160:163], v164 offset:2048
	ds_read_b128 v[164:167], v164 offset:3072
	ds_read_b128 v[168:171], v180
	ds_read_b128 v[172:175], v180 offset:1024
	ds_read_b128 v[176:179], v180 offset:2048
	ds_read_b128 v[180:183], v180 offset:3072
	ds_read_b128 v[184:187], v155 offset:32768
	ds_read_b128 v[188:191], v155 offset:33792
	ds_read_b128 v[192:195], v155 offset:34816
	ds_read_b128 v[196:199], v155 offset:35840
	ds_read_b128 v[200:203], v155 offset:36864
	ds_read_b128 v[204:207], v155 offset:37888
	ds_read_b128 v[208:211], v155 offset:38912
	ds_read_b128 v[212:215], v155 offset:39936
	s_waitcnt vmcnt(8)
	s_waitcnt lgkmcnt(0)
	s_barrier
	s_setprio 1
	s_waitcnt lgkmcnt(0)
	v_mfma_f32_16x16x32_bf16 v[124:127], v[148:151], v[184:187], v[124:127]
	v_mfma_f32_16x16x32_bf16 v[120:123], v[160:163], v[184:187], v[120:123]
	v_mfma_f32_16x16x32_bf16 v[108:111], v[148:151], v[192:195], v[108:111]
	v_mfma_f32_16x16x32_bf16 v[104:107], v[160:163], v[192:195], v[104:107]
	v_mfma_f32_16x16x32_bf16 v[92:95], v[148:151], v[200:203], v[92:95]
	v_mfma_f32_16x16x32_bf16 v[88:91], v[160:163], v[200:203], v[88:91]
	v_mfma_f32_16x16x32_bf16 v[76:79], v[148:151], v[208:211], v[76:79]
	v_mfma_f32_16x16x32_bf16 v[72:75], v[160:163], v[208:211], v[72:75]
	v_mfma_f32_16x16x32_bf16 v[124:127], v[156:159], v[188:191], v[124:127]
	v_mfma_f32_16x16x32_bf16 v[120:123], v[164:167], v[188:191], v[120:123]
	v_mfma_f32_16x16x32_bf16 v[108:111], v[156:159], v[196:199], v[108:111]
	v_mfma_f32_16x16x32_bf16 v[104:107], v[164:167], v[196:199], v[104:107]
	v_mfma_f32_16x16x32_bf16 v[92:95], v[156:159], v[204:207], v[92:95]
	v_mfma_f32_16x16x32_bf16 v[88:91], v[164:167], v[204:207], v[88:91]
	v_mfma_f32_16x16x32_bf16 v[76:79], v[156:159], v[212:215], v[76:79]
	v_mfma_f32_16x16x32_bf16 v[72:75], v[164:167], v[212:215], v[72:75]
	s_setprio 0
	s_setprio 1
	v_mfma_f32_16x16x32_bf16 v[116:119], v[168:171], v[184:187], v[116:119]
	v_mfma_f32_16x16x32_bf16 v[112:115], v[176:179], v[184:187], v[112:115]
	v_mfma_f32_16x16x32_bf16 v[100:103], v[168:171], v[192:195], v[100:103]
	v_mfma_f32_16x16x32_bf16 v[96:99], v[176:179], v[192:195], v[96:99]
	v_mfma_f32_16x16x32_bf16 v[84:87], v[168:171], v[200:203], v[84:87]
	v_mfma_f32_16x16x32_bf16 v[80:83], v[176:179], v[200:203], v[80:83]
	v_mfma_f32_16x16x32_bf16 v[68:71], v[168:171], v[208:211], v[68:71]
	v_mfma_f32_16x16x32_bf16 v[64:67], v[176:179], v[208:211], v[64:67]
	v_mfma_f32_16x16x32_bf16 v[116:119], v[172:175], v[188:191], v[116:119]
	v_mfma_f32_16x16x32_bf16 v[112:115], v[180:183], v[188:191], v[112:115]
	v_mfma_f32_16x16x32_bf16 v[100:103], v[172:175], v[196:199], v[100:103]
	v_mfma_f32_16x16x32_bf16 v[96:99], v[180:183], v[196:199], v[96:99]
	v_mfma_f32_16x16x32_bf16 v[84:87], v[172:175], v[204:207], v[84:87]
	v_mfma_f32_16x16x32_bf16 v[80:83], v[180:183], v[204:207], v[80:83]
	v_mfma_f32_16x16x32_bf16 v[68:71], v[172:175], v[212:215], v[68:71]
	v_mfma_f32_16x16x32_bf16 v[64:67], v[180:183], v[212:215], v[64:67]
	s_setprio 0
	s_barrier
	s_add_i32 s30, s55, s37
	v_lshl_add_u64 v[216:217], v[216:217], 0, s[12:13]
	s_mov_b32 m0, s30
	s_nop 0
	global_load_lds_dwordx4 v[216:217], off
	s_add_i32 m0, s30, 0x2000
	s_add_u32 s28, s28, 0x40080
	v_lshl_add_u64 v[216:217], v[218:219], 0, s[12:13]
	s_addc_u32 s29, s29, 0
	s_add_i32 s30, s56, s37
	global_load_lds_dwordx4 v[216:217], off
	v_lshl_add_u64 v[216:217], s[28:29], 0, v[130:131]
	s_mov_b32 m0, s30
	s_nop 0
	global_load_lds_dwordx4 v[216:217], off
	v_lshl_add_u64 v[216:217], s[28:29], 0, v[134:135]
	s_add_i32 m0, s30, 0x2000
	s_nop 0
	global_load_lds_dwordx4 v[216:217], off
	v_lshl_add_u64 v[216:217], v[220:221], 0, s[12:13]
	s_mov_b32 m0, s43
	s_nop 0
	global_load_lds_dwordx4 v[216:217], off
	v_lshl_add_u64 v[216:217], v[222:223], 0, s[12:13]
	s_mov_b32 m0, s44
	s_nop 0
	global_load_lds_dwordx4 v[216:217], off
	ds_read_b128 v[184:187], v155 offset:49152
	ds_read_b128 v[188:191], v155 offset:50176
	ds_read_b128 v[192:195], v155 offset:51200
	ds_read_b128 v[196:199], v155 offset:52224
	ds_read_b128 v[200:203], v155 offset:53248
	ds_read_b128 v[204:207], v155 offset:54272
	ds_read_b128 v[208:211], v155 offset:55296
	ds_read_b128 v[212:215], v155 offset:56320
	s_waitcnt vmcnt(8)
	s_waitcnt lgkmcnt(0)
	s_barrier
	s_setprio 1
	s_waitcnt lgkmcnt(0)
	v_mfma_f32_16x16x32_bf16 v[60:63], v[148:151], v[184:187], v[60:63]
	v_mfma_f32_16x16x32_bf16 v[56:59], v[160:163], v[184:187], v[56:59]
	v_mfma_f32_16x16x32_bf16 v[44:47], v[148:151], v[192:195], v[44:47]
	v_mfma_f32_16x16x32_bf16 v[40:43], v[160:163], v[192:195], v[40:43]
	v_mfma_f32_16x16x32_bf16 v[28:31], v[148:151], v[200:203], v[28:31]
	v_mfma_f32_16x16x32_bf16 v[24:27], v[160:163], v[200:203], v[24:27]
	v_mfma_f32_16x16x32_bf16 v[12:15], v[148:151], v[208:211], v[12:15]
	v_mfma_f32_16x16x32_bf16 v[8:11], v[160:163], v[208:211], v[8:11]
	v_mfma_f32_16x16x32_bf16 v[60:63], v[156:159], v[188:191], v[60:63]
	v_mfma_f32_16x16x32_bf16 v[56:59], v[164:167], v[188:191], v[56:59]
	v_mfma_f32_16x16x32_bf16 v[44:47], v[156:159], v[196:199], v[44:47]
	v_mfma_f32_16x16x32_bf16 v[40:43], v[164:167], v[196:199], v[40:43]
	v_mfma_f32_16x16x32_bf16 v[28:31], v[156:159], v[204:207], v[28:31]
	v_mfma_f32_16x16x32_bf16 v[24:27], v[164:167], v[204:207], v[24:27]
	v_mfma_f32_16x16x32_bf16 v[12:15], v[156:159], v[212:215], v[12:15]
	v_mfma_f32_16x16x32_bf16 v[8:11], v[164:167], v[212:215], v[8:11]
	s_setprio 0
	s_setprio 1
	v_mfma_f32_16x16x32_bf16 v[52:55], v[168:171], v[184:187], v[52:55]
	v_mfma_f32_16x16x32_bf16 v[48:51], v[176:179], v[184:187], v[48:51]
	v_mfma_f32_16x16x32_bf16 v[36:39], v[168:171], v[192:195], v[36:39]
	v_mfma_f32_16x16x32_bf16 v[32:35], v[176:179], v[192:195], v[32:35]
	v_mfma_f32_16x16x32_bf16 v[20:23], v[168:171], v[200:203], v[20:23]
	v_mfma_f32_16x16x32_bf16 v[16:19], v[176:179], v[200:203], v[16:19]
	v_mfma_f32_16x16x32_bf16 v[4:7], v[168:171], v[208:211], v[4:7]
	v_mfma_f32_16x16x32_bf16 v[0:3], v[176:179], v[208:211], v[0:3]
	v_mfma_f32_16x16x32_bf16 v[52:55], v[172:175], v[188:191], v[52:55]
	v_mfma_f32_16x16x32_bf16 v[48:51], v[180:183], v[188:191], v[48:51]
	v_mfma_f32_16x16x32_bf16 v[36:39], v[172:175], v[196:199], v[36:39]
	v_mfma_f32_16x16x32_bf16 v[32:35], v[180:183], v[196:199], v[32:35]
	v_mfma_f32_16x16x32_bf16 v[20:23], v[172:175], v[204:207], v[20:23]
	v_mfma_f32_16x16x32_bf16 v[16:19], v[180:183], v[204:207], v[16:19]
	v_mfma_f32_16x16x32_bf16 v[4:7], v[172:175], v[212:215], v[4:7]
	v_mfma_f32_16x16x32_bf16 v[0:3], v[180:183], v[212:215], v[0:3]
	s_setprio 0
	s_barrier
	s_add_i32 s54, s54, 2
	s_add_u32 s26, s26, 0x100
	s_addc_u32 s27, s27, 0
	s_add_u32 s52, s52, 0x100
	s_addc_u32 s53, s53, 0
	s_cmp_gt_u32 s54, 13
.LBB1_94:
	s_add_u32 s28, s26, 0xfffc0080
	s_addc_u32 s29, s27, -1
	s_cmp_eq_u32 s54, 12
	s_cselect_b32 s31, s5, s29
	s_cselect_b32 s30, s19, s28
	s_cselect_b32 s29, s17, s53
	s_cselect_b32 s28, s25, s52
	v_lshl_add_u64 v[216:217], s[26:27], 0, v[140:141]
	s_add_i32 m0, s38, 0xc000
	s_nop 0
	global_load_lds_dwordx4 v[216:217], off
	v_lshl_add_u64 v[216:217], s[26:27], 0, v[142:143]
	s_add_i32 m0, s38, 0xe000
	s_nop 0
	global_load_lds_dwordx4 v[216:217], off
	ds_read_b128 v[148:151], v153
	ds_read_b128 v[156:159], v153 offset:1024
	ds_read_b128 v[160:163], v153 offset:2048
	ds_read_b128 v[164:167], v153 offset:3072
	ds_read_b128 v[168:171], v154
	ds_read_b128 v[172:175], v154 offset:1024
	ds_read_b128 v[176:179], v154 offset:2048
	ds_read_b128 v[180:183], v154 offset:3072
	ds_read_b128 v[184:187], v155
	ds_read_b128 v[188:191], v155 offset:1024
	ds_read_b128 v[192:195], v155 offset:2048
	ds_read_b128 v[196:199], v155 offset:3072
	ds_read_b128 v[200:203], v155 offset:4096
	ds_read_b128 v[204:207], v155 offset:5120
	ds_read_b128 v[208:211], v155 offset:6144
	ds_read_b128 v[212:215], v155 offset:7168
	s_waitcnt vmcnt(8)
	s_waitcnt lgkmcnt(0)
	s_barrier
	s_setprio 1
	s_waitcnt lgkmcnt(0)
	v_mfma_f32_16x16x32_bf16 v[124:127], v[148:151], v[184:187], v[124:127]
	v_mfma_f32_16x16x32_bf16 v[120:123], v[160:163], v[184:187], v[120:123]
	v_mfma_f32_16x16x32_bf16 v[108:111], v[148:151], v[192:195], v[108:111]
	v_mfma_f32_16x16x32_bf16 v[104:107], v[160:163], v[192:195], v[104:107]
	v_mfma_f32_16x16x32_bf16 v[92:95], v[148:151], v[200:203], v[92:95]
	v_mfma_f32_16x16x32_bf16 v[88:91], v[160:163], v[200:203], v[88:91]
	v_mfma_f32_16x16x32_bf16 v[76:79], v[148:151], v[208:211], v[76:79]
	v_mfma_f32_16x16x32_bf16 v[72:75], v[160:163], v[208:211], v[72:75]
	v_mfma_f32_16x16x32_bf16 v[124:127], v[156:159], v[188:191], v[124:127]
	v_mfma_f32_16x16x32_bf16 v[120:123], v[164:167], v[188:191], v[120:123]
	v_mfma_f32_16x16x32_bf16 v[108:111], v[156:159], v[196:199], v[108:111]
	v_mfma_f32_16x16x32_bf16 v[104:107], v[164:167], v[196:199], v[104:107]
	v_mfma_f32_16x16x32_bf16 v[92:95], v[156:159], v[204:207], v[92:95]
	v_mfma_f32_16x16x32_bf16 v[88:91], v[164:167], v[204:207], v[88:91]
	v_mfma_f32_16x16x32_bf16 v[76:79], v[156:159], v[212:215], v[76:79]
	v_mfma_f32_16x16x32_bf16 v[72:75], v[164:167], v[212:215], v[72:75]
	s_setprio 0
	s_setprio 1
	v_mfma_f32_16x16x32_bf16 v[116:119], v[168:171], v[184:187], v[116:119]
	v_mfma_f32_16x16x32_bf16 v[112:115], v[176:179], v[184:187], v[112:115]
	v_mfma_f32_16x16x32_bf16 v[100:103], v[168:171], v[192:195], v[100:103]
	v_mfma_f32_16x16x32_bf16 v[96:99], v[176:179], v[192:195], v[96:99]
	v_mfma_f32_16x16x32_bf16 v[84:87], v[168:171], v[200:203], v[84:87]
	v_mfma_f32_16x16x32_bf16 v[80:83], v[176:179], v[200:203], v[80:83]
	v_mfma_f32_16x16x32_bf16 v[68:71], v[168:171], v[208:211], v[68:71]
	v_mfma_f32_16x16x32_bf16 v[64:67], v[176:179], v[208:211], v[64:67]
	v_mfma_f32_16x16x32_bf16 v[116:119], v[172:175], v[188:191], v[116:119]
	v_mfma_f32_16x16x32_bf16 v[112:115], v[180:183], v[188:191], v[112:115]
	v_mfma_f32_16x16x32_bf16 v[100:103], v[172:175], v[196:199], v[100:103]
	v_mfma_f32_16x16x32_bf16 v[96:99], v[180:183], v[196:199], v[96:99]
	v_mfma_f32_16x16x32_bf16 v[84:87], v[172:175], v[204:207], v[84:87]
	v_mfma_f32_16x16x32_bf16 v[80:83], v[180:183], v[204:207], v[80:83]
	v_mfma_f32_16x16x32_bf16 v[68:71], v[172:175], v[212:215], v[68:71]
	v_mfma_f32_16x16x32_bf16 v[64:67], v[180:183], v[212:215], v[64:67]
	s_setprio 0
	s_barrier
	s_add_i32 s55, s48, s37
	v_lshl_add_u64 v[216:217], s[28:29], 0, v[130:131]
	s_mov_b32 m0, s55
	s_nop 0
	global_load_lds_dwordx4 v[216:217], off
	s_add_i32 m0, s55, 0x2000
	s_add_u32 s56, s28, 0x40000
	v_lshl_add_u64 v[218:219], s[28:29], 0, v[134:135]
	s_addc_u32 s57, s29, 0
	s_add_i32 s55, s49, s37
	global_load_lds_dwordx4 v[218:219], off
	v_lshl_add_u64 v[220:221], s[56:57], 0, v[130:131]
	s_mov_b32 m0, s55
	v_lshl_add_u64 v[222:223], s[30:31], 0, v[132:133]
	global_load_lds_dwordx4 v[220:221], off
	v_lshl_add_u64 v[220:221], s[56:57], 0, v[134:135]
	s_add_i32 m0, s55, 0x2000
	s_nop 0
	global_load_lds_dwordx4 v[220:221], off
	v_lshl_add_u64 v[220:221], s[30:31], 0, v[128:129]
	s_mov_b32 m0, s38
	s_nop 0
	global_load_lds_dwordx4 v[220:221], off
	s_mov_b32 m0, s39
	s_nop 0
	global_load_lds_dwordx4 v[222:223], off
	ds_read_b128 v[184:187], v155 offset:16384
	ds_read_b128 v[188:191], v155 offset:17408
	ds_read_b128 v[192:195], v155 offset:18432
	ds_read_b128 v[196:199], v155 offset:19456
	ds_read_b128 v[200:203], v155 offset:20480
	ds_read_b128 v[204:207], v155 offset:21504
	ds_read_b128 v[208:211], v155 offset:22528
	ds_read_b128 v[212:215], v155 offset:23552
	s_waitcnt vmcnt(8)
	s_waitcnt lgkmcnt(0)
	s_barrier
	s_setprio 1
	s_waitcnt lgkmcnt(0)
	v_mfma_f32_16x16x32_bf16 v[60:63], v[148:151], v[184:187], v[60:63]
	v_mfma_f32_16x16x32_bf16 v[56:59], v[160:163], v[184:187], v[56:59]
	v_mfma_f32_16x16x32_bf16 v[44:47], v[148:151], v[192:195], v[44:47]
	v_mfma_f32_16x16x32_bf16 v[40:43], v[160:163], v[192:195], v[40:43]
	v_mfma_f32_16x16x32_bf16 v[28:31], v[148:151], v[200:203], v[28:31]
	v_mfma_f32_16x16x32_bf16 v[24:27], v[160:163], v[200:203], v[24:27]
	v_mfma_f32_16x16x32_bf16 v[12:15], v[148:151], v[208:211], v[12:15]
	v_mfma_f32_16x16x32_bf16 v[8:11], v[160:163], v[208:211], v[8:11]
	v_mfma_f32_16x16x32_bf16 v[60:63], v[156:159], v[188:191], v[60:63]
	v_mfma_f32_16x16x32_bf16 v[56:59], v[164:167], v[188:191], v[56:59]
	v_mfma_f32_16x16x32_bf16 v[44:47], v[156:159], v[196:199], v[44:47]
	v_mfma_f32_16x16x32_bf16 v[40:43], v[164:167], v[196:199], v[40:43]
	v_mfma_f32_16x16x32_bf16 v[28:31], v[156:159], v[204:207], v[28:31]
	v_mfma_f32_16x16x32_bf16 v[24:27], v[164:167], v[204:207], v[24:27]
	v_mfma_f32_16x16x32_bf16 v[12:15], v[156:159], v[212:215], v[12:15]
	v_mfma_f32_16x16x32_bf16 v[8:11], v[164:167], v[212:215], v[8:11]
	s_setprio 0
	s_setprio 1
	v_mfma_f32_16x16x32_bf16 v[52:55], v[168:171], v[184:187], v[52:55]
	v_mfma_f32_16x16x32_bf16 v[48:51], v[176:179], v[184:187], v[48:51]
	v_mfma_f32_16x16x32_bf16 v[36:39], v[168:171], v[192:195], v[36:39]
	v_mfma_f32_16x16x32_bf16 v[32:35], v[176:179], v[192:195], v[32:35]
	v_mfma_f32_16x16x32_bf16 v[20:23], v[168:171], v[200:203], v[20:23]
	v_mfma_f32_16x16x32_bf16 v[16:19], v[176:179], v[200:203], v[16:19]
	v_mfma_f32_16x16x32_bf16 v[4:7], v[168:171], v[208:211], v[4:7]
	v_mfma_f32_16x16x32_bf16 v[0:3], v[176:179], v[208:211], v[0:3]
	v_mfma_f32_16x16x32_bf16 v[52:55], v[172:175], v[188:191], v[52:55]
	v_mfma_f32_16x16x32_bf16 v[48:51], v[180:183], v[188:191], v[48:51]
	v_mfma_f32_16x16x32_bf16 v[36:39], v[172:175], v[196:199], v[36:39]
	v_mfma_f32_16x16x32_bf16 v[32:35], v[180:183], v[196:199], v[32:35]
	v_mfma_f32_16x16x32_bf16 v[20:23], v[172:175], v[204:207], v[20:23]
	v_mfma_f32_16x16x32_bf16 v[16:19], v[180:183], v[204:207], v[16:19]
	v_mfma_f32_16x16x32_bf16 v[4:7], v[172:175], v[212:215], v[4:7]
	v_mfma_f32_16x16x32_bf16 v[0:3], v[180:183], v[212:215], v[0:3]
	s_setprio 0
	s_barrier
	s_add_i32 s55, 0, 0x18000
	s_add_i32 s56, 0, 0x1c000
	v_add_u32_e32 v164, s55, v152
	v_add_u32_e32 v180, s56, v152
	s_add_u32 s30, s30, 0x40000
	s_addc_u32 s31, s31, 0
	s_mov_b32 m0, s40
	v_lshl_add_u64 v[224:225], s[30:31], 0, v[128:129]
	global_load_lds_dwordx4 v[224:225], off
	v_lshl_add_u64 v[224:225], s[30:31], 0, v[132:133]
	s_mov_b32 m0, s41
	s_nop 0
	global_load_lds_dwordx4 v[224:225], off
	ds_read_b128 v[148:151], v164
	ds_read_b128 v[156:159], v164 offset:1024
	ds_read_b128 v[160:163], v164 offset:2048
	ds_read_b128 v[164:167], v164 offset:3072
	ds_read_b128 v[168:171], v180
	ds_read_b128 v[172:175], v180 offset:1024
	ds_read_b128 v[176:179], v180 offset:2048
	ds_read_b128 v[180:183], v180 offset:3072
	ds_read_b128 v[184:187], v155 offset:32768
	ds_read_b128 v[188:191], v155 offset:33792
	ds_read_b128 v[192:195], v155 offset:34816
	ds_read_b128 v[196:199], v155 offset:35840
	ds_read_b128 v[200:203], v155 offset:36864
	ds_read_b128 v[204:207], v155 offset:37888
	ds_read_b128 v[208:211], v155 offset:38912
	ds_read_b128 v[212:215], v155 offset:39936
	s_waitcnt vmcnt(8)
	s_waitcnt lgkmcnt(0)
	s_barrier
	s_setprio 1
	s_waitcnt lgkmcnt(0)
	v_mfma_f32_16x16x32_bf16 v[124:127], v[148:151], v[184:187], v[124:127]
	v_mfma_f32_16x16x32_bf16 v[120:123], v[160:163], v[184:187], v[120:123]
	v_mfma_f32_16x16x32_bf16 v[108:111], v[148:151], v[192:195], v[108:111]
	v_mfma_f32_16x16x32_bf16 v[104:107], v[160:163], v[192:195], v[104:107]
	v_mfma_f32_16x16x32_bf16 v[92:95], v[148:151], v[200:203], v[92:95]
	v_mfma_f32_16x16x32_bf16 v[88:91], v[160:163], v[200:203], v[88:91]
	v_mfma_f32_16x16x32_bf16 v[76:79], v[148:151], v[208:211], v[76:79]
	v_mfma_f32_16x16x32_bf16 v[72:75], v[160:163], v[208:211], v[72:75]
	v_mfma_f32_16x16x32_bf16 v[124:127], v[156:159], v[188:191], v[124:127]
	v_mfma_f32_16x16x32_bf16 v[120:123], v[164:167], v[188:191], v[120:123]
	v_mfma_f32_16x16x32_bf16 v[108:111], v[156:159], v[196:199], v[108:111]
	v_mfma_f32_16x16x32_bf16 v[104:107], v[164:167], v[196:199], v[104:107]
	v_mfma_f32_16x16x32_bf16 v[92:95], v[156:159], v[204:207], v[92:95]
	v_mfma_f32_16x16x32_bf16 v[88:91], v[164:167], v[204:207], v[88:91]
	v_mfma_f32_16x16x32_bf16 v[76:79], v[156:159], v[212:215], v[76:79]
	v_mfma_f32_16x16x32_bf16 v[72:75], v[164:167], v[212:215], v[72:75]
	s_setprio 0
	s_setprio 1
	v_mfma_f32_16x16x32_bf16 v[116:119], v[168:171], v[184:187], v[116:119]
	v_mfma_f32_16x16x32_bf16 v[112:115], v[176:179], v[184:187], v[112:115]
	v_mfma_f32_16x16x32_bf16 v[100:103], v[168:171], v[192:195], v[100:103]
	v_mfma_f32_16x16x32_bf16 v[96:99], v[176:179], v[192:195], v[96:99]
	v_mfma_f32_16x16x32_bf16 v[84:87], v[168:171], v[200:203], v[84:87]
	v_mfma_f32_16x16x32_bf16 v[80:83], v[176:179], v[200:203], v[80:83]
	v_mfma_f32_16x16x32_bf16 v[68:71], v[168:171], v[208:211], v[68:71]
	v_mfma_f32_16x16x32_bf16 v[64:67], v[176:179], v[208:211], v[64:67]
	v_mfma_f32_16x16x32_bf16 v[116:119], v[172:175], v[188:191], v[116:119]
	v_mfma_f32_16x16x32_bf16 v[112:115], v[180:183], v[188:191], v[112:115]
	v_mfma_f32_16x16x32_bf16 v[100:103], v[172:175], v[196:199], v[100:103]
	v_mfma_f32_16x16x32_bf16 v[96:99], v[180:183], v[196:199], v[96:99]
	v_mfma_f32_16x16x32_bf16 v[84:87], v[172:175], v[204:207], v[84:87]
	v_mfma_f32_16x16x32_bf16 v[80:83], v[180:183], v[204:207], v[80:83]
	v_mfma_f32_16x16x32_bf16 v[68:71], v[172:175], v[212:215], v[68:71]
	v_mfma_f32_16x16x32_bf16 v[64:67], v[180:183], v[212:215], v[64:67]
	s_setprio 0
	s_barrier
	s_add_i32 s30, s55, s37
	v_lshl_add_u64 v[216:217], v[216:217], 0, s[12:13]
	s_mov_b32 m0, s30
	s_nop 0
	global_load_lds_dwordx4 v[216:217], off
	s_add_i32 m0, s30, 0x2000
	s_add_u32 s28, s28, 0x40080
	v_lshl_add_u64 v[216:217], v[218:219], 0, s[12:13]
	s_addc_u32 s29, s29, 0
	s_add_i32 s30, s56, s37
	global_load_lds_dwordx4 v[216:217], off
	v_lshl_add_u64 v[216:217], s[28:29], 0, v[130:131]
	s_mov_b32 m0, s30
	s_nop 0
	global_load_lds_dwordx4 v[216:217], off
	v_lshl_add_u64 v[216:217], s[28:29], 0, v[134:135]
	s_add_i32 m0, s30, 0x2000
	s_nop 0
	global_load_lds_dwordx4 v[216:217], off
	v_lshl_add_u64 v[216:217], v[220:221], 0, s[12:13]
	s_mov_b32 m0, s43
	s_nop 0
	global_load_lds_dwordx4 v[216:217], off
	v_lshl_add_u64 v[216:217], v[222:223], 0, s[12:13]
	s_mov_b32 m0, s44
	s_nop 0
	global_load_lds_dwordx4 v[216:217], off
	ds_read_b128 v[184:187], v155 offset:49152
	ds_read_b128 v[188:191], v155 offset:50176
	ds_read_b128 v[192:195], v155 offset:51200
	ds_read_b128 v[196:199], v155 offset:52224
	ds_read_b128 v[200:203], v155 offset:53248
	ds_read_b128 v[204:207], v155 offset:54272
	ds_read_b128 v[208:211], v155 offset:55296
	ds_read_b128 v[212:215], v155 offset:56320
	s_waitcnt vmcnt(8)
	s_waitcnt lgkmcnt(0)
	s_barrier
	s_setprio 1
	s_waitcnt lgkmcnt(0)
	v_mfma_f32_16x16x32_bf16 v[60:63], v[148:151], v[184:187], v[60:63]
	v_mfma_f32_16x16x32_bf16 v[56:59], v[160:163], v[184:187], v[56:59]
	v_mfma_f32_16x16x32_bf16 v[44:47], v[148:151], v[192:195], v[44:47]
	v_mfma_f32_16x16x32_bf16 v[40:43], v[160:163], v[192:195], v[40:43]
	v_mfma_f32_16x16x32_bf16 v[28:31], v[148:151], v[200:203], v[28:31]
	v_mfma_f32_16x16x32_bf16 v[24:27], v[160:163], v[200:203], v[24:27]
	v_mfma_f32_16x16x32_bf16 v[12:15], v[148:151], v[208:211], v[12:15]
	v_mfma_f32_16x16x32_bf16 v[8:11], v[160:163], v[208:211], v[8:11]
	v_mfma_f32_16x16x32_bf16 v[60:63], v[156:159], v[188:191], v[60:63]
	v_mfma_f32_16x16x32_bf16 v[56:59], v[164:167], v[188:191], v[56:59]
	v_mfma_f32_16x16x32_bf16 v[44:47], v[156:159], v[196:199], v[44:47]
	v_mfma_f32_16x16x32_bf16 v[40:43], v[164:167], v[196:199], v[40:43]
	v_mfma_f32_16x16x32_bf16 v[28:31], v[156:159], v[204:207], v[28:31]
	v_mfma_f32_16x16x32_bf16 v[24:27], v[164:167], v[204:207], v[24:27]
	v_mfma_f32_16x16x32_bf16 v[12:15], v[156:159], v[212:215], v[12:15]
	v_mfma_f32_16x16x32_bf16 v[8:11], v[164:167], v[212:215], v[8:11]
	s_setprio 0
	s_setprio 1
	v_mfma_f32_16x16x32_bf16 v[52:55], v[168:171], v[184:187], v[52:55]
	v_mfma_f32_16x16x32_bf16 v[48:51], v[176:179], v[184:187], v[48:51]
	v_mfma_f32_16x16x32_bf16 v[36:39], v[168:171], v[192:195], v[36:39]
	v_mfma_f32_16x16x32_bf16 v[32:35], v[176:179], v[192:195], v[32:35]
	v_mfma_f32_16x16x32_bf16 v[20:23], v[168:171], v[200:203], v[20:23]
	v_mfma_f32_16x16x32_bf16 v[16:19], v[176:179], v[200:203], v[16:19]
	v_mfma_f32_16x16x32_bf16 v[4:7], v[168:171], v[208:211], v[4:7]
	v_mfma_f32_16x16x32_bf16 v[0:3], v[176:179], v[208:211], v[0:3]
	v_mfma_f32_16x16x32_bf16 v[52:55], v[172:175], v[188:191], v[52:55]
	v_mfma_f32_16x16x32_bf16 v[48:51], v[180:183], v[188:191], v[48:51]
	v_mfma_f32_16x16x32_bf16 v[36:39], v[172:175], v[196:199], v[36:39]
	v_mfma_f32_16x16x32_bf16 v[32:35], v[180:183], v[196:199], v[32:35]
	v_mfma_f32_16x16x32_bf16 v[20:23], v[172:175], v[204:207], v[20:23]
	v_mfma_f32_16x16x32_bf16 v[16:19], v[180:183], v[204:207], v[16:19]
	v_mfma_f32_16x16x32_bf16 v[4:7], v[172:175], v[212:215], v[4:7]
	v_mfma_f32_16x16x32_bf16 v[0:3], v[180:183], v[212:215], v[0:3]
	s_setprio 0
	s_barrier
	s_add_i32 s54, s54, 2
	s_add_u32 s26, s26, 0x100
	s_addc_u32 s27, s27, 0
	s_add_u32 s52, s52, 0x100
	s_addc_u32 s53, s53, 0
	s_cmp_gt_u32 s54, 13
	s_cbranch_scc0 .LBB1_94
	s_and_b64 vcc, exec, s[14:15]
	s_cbranch_vccz .LBB1_97
	s_barrier

.LBB3_19:
	s_ashr_i32 s17, s16, 31
	s_lshl_b64 s[18:19], s[16:17], 19
	s_add_u32 s18, s33, s18
	v_cmp_lt_i64_e64 s[4:5], s[4:5], v[142:143]
	s_addc_u32 s19, s34, s19
	s_and_b64 s[20:21], s[4:5], exec
	s_cselect_b32 s17, s19, s25
	s_cselect_b32 s53, s18, s24
	s_ashr_i32 s15, s14, 31
	s_lshl_b64 s[20:21], s[14:15], 19
	s_add_u32 s20, s6, s20
	s_addc_u32 s21, s7, s21
	s_and_b64 s[28:29], s[4:5], exec
	s_cselect_b32 s15, s21, s27
	s_cselect_b32 s54, s20, s26
	s_add_u32 s24, s24, 0x40080
	s_addc_u32 s25, s25, 0
	s_add_u32 s55, s26, 0x100
	s_addc_u32 s56, s27, 0
	s_mov_b32 s57, -2
	s_add_u32 s26, s24, 0xfffc0080
	s_addc_u32 s27, s25, -1
	s_cmp_eq_u32 s57, 12
	s_cselect_b32 s29, s17, s27
	s_cselect_b32 s28, s53, s26
	s_cselect_b32 s27, s15, s56
	s_cselect_b32 s26, s54, s55
	v_lshl_add_u64 v[146:147], s[24:25], 0, v[138:139]
	s_add_i32 m0, s23, 0xc000
	s_nop 0
	global_load_lds_dwordx4 v[146:147], off
	v_lshl_add_u64 v[146:147], s[24:25], 0, v[140:141]
	s_add_i32 m0, s23, 0xe000
	s_nop 0
	global_load_lds_dwordx4 v[146:147], off
	ds_read_b128 v[152:155], v149
	ds_read_b128 v[156:159], v149 offset:1024
	ds_read_b128 v[160:163], v149 offset:2048
	ds_read_b128 v[164:167], v149 offset:3072
	ds_read_b128 v[168:171], v150
	ds_read_b128 v[172:175], v150 offset:1024
	ds_read_b128 v[176:179], v150 offset:2048
	ds_read_b128 v[180:183], v150 offset:3072
	ds_read_b128 v[184:187], v151
	ds_read_b128 v[188:191], v151 offset:1024
	ds_read_b128 v[192:195], v151 offset:2048
	ds_read_b128 v[196:199], v151 offset:3072
	ds_read_b128 v[200:203], v151 offset:4096
	ds_read_b128 v[204:207], v151 offset:5120
	ds_read_b128 v[208:211], v151 offset:6144
	ds_read_b128 v[212:215], v151 offset:7168
	s_waitcnt vmcnt(8)
	s_waitcnt lgkmcnt(0)
	s_barrier
	s_setprio 1
	s_waitcnt lgkmcnt(0)
	v_mfma_f32_16x16x32_bf16 v[124:127], v[152:155], v[184:187], 0
	v_mfma_f32_16x16x32_bf16 v[120:123], v[160:163], v[184:187], 0
	v_mfma_f32_16x16x32_bf16 v[116:119], v[152:155], v[192:195], 0
	v_mfma_f32_16x16x32_bf16 v[108:111], v[160:163], v[192:195], 0
	v_mfma_f32_16x16x32_bf16 v[100:103], v[152:155], v[200:203], 0
	v_mfma_f32_16x16x32_bf16 v[92:95], v[160:163], v[200:203], 0
	v_mfma_f32_16x16x32_bf16 v[84:87], v[152:155], v[208:211], 0
	v_mfma_f32_16x16x32_bf16 v[76:79], v[160:163], v[208:211], 0
	v_mfma_f32_16x16x32_bf16 v[124:127], v[156:159], v[188:191], v[124:127]
	v_mfma_f32_16x16x32_bf16 v[120:123], v[164:167], v[188:191], v[120:123]
	v_mfma_f32_16x16x32_bf16 v[116:119], v[156:159], v[196:199], v[116:119]
	v_mfma_f32_16x16x32_bf16 v[108:111], v[164:167], v[196:199], v[108:111]
	v_mfma_f32_16x16x32_bf16 v[100:103], v[156:159], v[204:207], v[100:103]
	v_mfma_f32_16x16x32_bf16 v[92:95], v[164:167], v[204:207], v[92:95]
	v_mfma_f32_16x16x32_bf16 v[84:87], v[156:159], v[212:215], v[84:87]
	v_mfma_f32_16x16x32_bf16 v[76:79], v[164:167], v[212:215], v[76:79]
	s_setprio 0
	s_setprio 1
	v_mfma_f32_16x16x32_bf16 v[112:115], v[168:171], v[184:187], 0
	v_mfma_f32_16x16x32_bf16 v[104:107], v[176:179], v[184:187], 0
	v_mfma_f32_16x16x32_bf16 v[96:99], v[168:171], v[192:195], 0
	v_mfma_f32_16x16x32_bf16 v[88:91], v[176:179], v[192:195], 0
	v_mfma_f32_16x16x32_bf16 v[80:83], v[168:171], v[200:203], 0
	v_mfma_f32_16x16x32_bf16 v[72:75], v[176:179], v[200:203], 0
	v_mfma_f32_16x16x32_bf16 v[68:71], v[168:171], v[208:211], 0
	v_mfma_f32_16x16x32_bf16 v[64:67], v[176:179], v[208:211], 0
	v_mfma_f32_16x16x32_bf16 v[112:115], v[172:175], v[188:191], v[112:115]
	v_mfma_f32_16x16x32_bf16 v[104:107], v[180:183], v[188:191], v[104:107]
	v_mfma_f32_16x16x32_bf16 v[96:99], v[172:175], v[196:199], v[96:99]
	v_mfma_f32_16x16x32_bf16 v[88:91], v[180:183], v[196:199], v[88:91]
	v_mfma_f32_16x16x32_bf16 v[80:83], v[172:175], v[204:207], v[80:83]
	v_mfma_f32_16x16x32_bf16 v[72:75], v[180:183], v[204:207], v[72:75]
	v_mfma_f32_16x16x32_bf16 v[68:71], v[172:175], v[212:215], v[68:71]
	v_mfma_f32_16x16x32_bf16 v[64:67], v[180:183], v[212:215], v[64:67]
	s_setprio 0
	s_barrier
	s_add_i32 s58, s45, s31
	v_lshl_add_u64 v[146:147], s[26:27], 0, v[130:131]
	s_mov_b32 m0, s58
	s_nop 0
	global_load_lds_dwordx4 v[146:147], off
	s_add_i32 m0, s58, 0x2000
	s_add_u32 s58, s26, 0x40000
	v_lshl_add_u64 v[216:217], s[26:27], 0, v[134:135]
	s_addc_u32 s59, s27, 0
	s_add_i32 s60, s46, s31
	global_load_lds_dwordx4 v[216:217], off
	v_lshl_add_u64 v[218:219], s[58:59], 0, v[130:131]
	s_mov_b32 m0, s60
	v_lshl_add_u64 v[220:221], s[28:29], 0, v[132:133]
	global_load_lds_dwordx4 v[218:219], off
	v_lshl_add_u64 v[218:219], s[58:59], 0, v[134:135]
	s_add_i32 m0, s60, 0x2000
	s_nop 0
	global_load_lds_dwordx4 v[218:219], off
	v_lshl_add_u64 v[218:219], s[28:29], 0, v[128:129]
	s_mov_b32 m0, s23
	s_nop 0
	global_load_lds_dwordx4 v[218:219], off
	s_mov_b32 m0, s35
	s_nop 0
	global_load_lds_dwordx4 v[220:221], off
	ds_read_b128 v[184:187], v151 offset:16384
	ds_read_b128 v[188:191], v151 offset:17408
	ds_read_b128 v[192:195], v151 offset:18432
	ds_read_b128 v[196:199], v151 offset:19456
	ds_read_b128 v[200:203], v151 offset:20480
	ds_read_b128 v[204:207], v151 offset:21504
	ds_read_b128 v[208:211], v151 offset:22528
	ds_read_b128 v[212:215], v151 offset:23552
	s_waitcnt vmcnt(8)
	s_waitcnt lgkmcnt(0)
	s_barrier
	s_setprio 1
	s_waitcnt lgkmcnt(0)
	v_mfma_f32_16x16x32_bf16 v[60:63], v[152:155], v[184:187], 0
	v_mfma_f32_16x16x32_bf16 v[56:59], v[160:163], v[184:187], 0
	v_mfma_f32_16x16x32_bf16 v[52:55], v[152:155], v[192:195], 0
	v_mfma_f32_16x16x32_bf16 v[44:47], v[160:163], v[192:195], 0
	v_mfma_f32_16x16x32_bf16 v[36:39], v[152:155], v[200:203], 0
	v_mfma_f32_16x16x32_bf16 v[28:31], v[160:163], v[200:203], 0
	v_mfma_f32_16x16x32_bf16 v[20:23], v[152:155], v[208:211], 0
	v_mfma_f32_16x16x32_bf16 v[12:15], v[160:163], v[208:211], 0
	v_mfma_f32_16x16x32_bf16 v[60:63], v[156:159], v[188:191], v[60:63]
	v_mfma_f32_16x16x32_bf16 v[56:59], v[164:167], v[188:191], v[56:59]
	v_mfma_f32_16x16x32_bf16 v[52:55], v[156:159], v[196:199], v[52:55]
	v_mfma_f32_16x16x32_bf16 v[44:47], v[164:167], v[196:199], v[44:47]
	v_mfma_f32_16x16x32_bf16 v[36:39], v[156:159], v[204:207], v[36:39]
	v_mfma_f32_16x16x32_bf16 v[28:31], v[164:167], v[204:207], v[28:31]
	v_mfma_f32_16x16x32_bf16 v[20:23], v[156:159], v[212:215], v[20:23]
	v_mfma_f32_16x16x32_bf16 v[12:15], v[164:167], v[212:215], v[12:15]
	s_setprio 0
	s_setprio 1
	v_mfma_f32_16x16x32_bf16 v[48:51], v[168:171], v[184:187], 0
	v_mfma_f32_16x16x32_bf16 v[40:43], v[176:179], v[184:187], 0
	v_mfma_f32_16x16x32_bf16 v[32:35], v[168:171], v[192:195], 0
	v_mfma_f32_16x16x32_bf16 v[24:27], v[176:179], v[192:195], 0
	v_mfma_f32_16x16x32_bf16 v[16:19], v[168:171], v[200:203], 0
	v_mfma_f32_16x16x32_bf16 v[8:11], v[176:179], v[200:203], 0
	v_mfma_f32_16x16x32_bf16 v[4:7], v[168:171], v[208:211], 0
	v_mfma_f32_16x16x32_bf16 v[0:3], v[176:179], v[208:211], 0
	v_mfma_f32_16x16x32_bf16 v[48:51], v[172:175], v[188:191], v[48:51]
	v_mfma_f32_16x16x32_bf16 v[40:43], v[180:183], v[188:191], v[40:43]
	v_mfma_f32_16x16x32_bf16 v[32:35], v[172:175], v[196:199], v[32:35]
	v_mfma_f32_16x16x32_bf16 v[24:27], v[180:183], v[196:199], v[24:27]
	v_mfma_f32_16x16x32_bf16 v[16:19], v[172:175], v[204:207], v[16:19]
	v_mfma_f32_16x16x32_bf16 v[8:11], v[180:183], v[204:207], v[8:11]
	v_mfma_f32_16x16x32_bf16 v[4:7], v[172:175], v[212:215], v[4:7]
	v_mfma_f32_16x16x32_bf16 v[0:3], v[180:183], v[212:215], v[0:3]
	s_setprio 0
	s_barrier
	s_add_i32 s58, 0, 0x18000
	s_add_i32 s59, 0, 0x1c000
	v_add_u32_e32 v164, s58, v148
	v_add_u32_e32 v180, s59, v148
	s_add_u32 s28, s28, 0x40000
	s_addc_u32 s29, s29, 0
	s_mov_b32 m0, s36
	v_lshl_add_u64 v[222:223], s[28:29], 0, v[128:129]
	global_load_lds_dwordx4 v[222:223], off
	v_lshl_add_u64 v[222:223], s[28:29], 0, v[132:133]
	s_mov_b32 m0, s37
	s_nop 0
	global_load_lds_dwordx4 v[222:223], off
	ds_read_b128 v[152:155], v164
	ds_read_b128 v[156:159], v164 offset:1024
	ds_read_b128 v[160:163], v164 offset:2048
	ds_read_b128 v[164:167], v164 offset:3072
	ds_read_b128 v[168:171], v180
	ds_read_b128 v[172:175], v180 offset:1024
	ds_read_b128 v[176:179], v180 offset:2048
	ds_read_b128 v[180:183], v180 offset:3072
	ds_read_b128 v[184:187], v151 offset:32768
	ds_read_b128 v[188:191], v151 offset:33792
	ds_read_b128 v[192:195], v151 offset:34816
	ds_read_b128 v[196:199], v151 offset:35840
	ds_read_b128 v[200:203], v151 offset:36864
	ds_read_b128 v[204:207], v151 offset:37888
	ds_read_b128 v[208:211], v151 offset:38912
	ds_read_b128 v[212:215], v151 offset:39936
	s_waitcnt vmcnt(8)
	s_waitcnt lgkmcnt(0)
	s_barrier
	s_setprio 1
	s_waitcnt lgkmcnt(0)
	v_mfma_f32_16x16x32_bf16 v[124:127], v[152:155], v[184:187], v[124:127]
	v_mfma_f32_16x16x32_bf16 v[120:123], v[160:163], v[184:187], v[120:123]
	v_mfma_f32_16x16x32_bf16 v[116:119], v[152:155], v[192:195], v[116:119]
	v_mfma_f32_16x16x32_bf16 v[108:111], v[160:163], v[192:195], v[108:111]
	v_mfma_f32_16x16x32_bf16 v[100:103], v[152:155], v[200:203], v[100:103]
	v_mfma_f32_16x16x32_bf16 v[92:95], v[160:163], v[200:203], v[92:95]
	v_mfma_f32_16x16x32_bf16 v[84:87], v[152:155], v[208:211], v[84:87]
	v_mfma_f32_16x16x32_bf16 v[76:79], v[160:163], v[208:211], v[76:79]
	v_mfma_f32_16x16x32_bf16 v[124:127], v[156:159], v[188:191], v[124:127]
	v_mfma_f32_16x16x32_bf16 v[120:123], v[164:167], v[188:191], v[120:123]
	v_mfma_f32_16x16x32_bf16 v[116:119], v[156:159], v[196:199], v[116:119]
	v_mfma_f32_16x16x32_bf16 v[108:111], v[164:167], v[196:199], v[108:111]
	v_mfma_f32_16x16x32_bf16 v[100:103], v[156:159], v[204:207], v[100:103]
	v_mfma_f32_16x16x32_bf16 v[92:95], v[164:167], v[204:207], v[92:95]
	v_mfma_f32_16x16x32_bf16 v[84:87], v[156:159], v[212:215], v[84:87]
	v_mfma_f32_16x16x32_bf16 v[76:79], v[164:167], v[212:215], v[76:79]
	s_setprio 0
	s_setprio 1
	v_mfma_f32_16x16x32_bf16 v[112:115], v[168:171], v[184:187], v[112:115]
	v_mfma_f32_16x16x32_bf16 v[104:107], v[176:179], v[184:187], v[104:107]
	v_mfma_f32_16x16x32_bf16 v[96:99], v[168:171], v[192:195], v[96:99]
	v_mfma_f32_16x16x32_bf16 v[88:91], v[176:179], v[192:195], v[88:91]
	v_mfma_f32_16x16x32_bf16 v[80:83], v[168:171], v[200:203], v[80:83]
	v_mfma_f32_16x16x32_bf16 v[72:75], v[176:179], v[200:203], v[72:75]
	v_mfma_f32_16x16x32_bf16 v[68:71], v[168:171], v[208:211], v[68:71]
	v_mfma_f32_16x16x32_bf16 v[64:67], v[176:179], v[208:211], v[64:67]
	v_mfma_f32_16x16x32_bf16 v[112:115], v[172:175], v[188:191], v[112:115]
	v_mfma_f32_16x16x32_bf16 v[104:107], v[180:183], v[188:191], v[104:107]
	v_mfma_f32_16x16x32_bf16 v[96:99], v[172:175], v[196:199], v[96:99]
	v_mfma_f32_16x16x32_bf16 v[88:91], v[180:183], v[196:199], v[88:91]
	v_mfma_f32_16x16x32_bf16 v[80:83], v[172:175], v[204:207], v[80:83]
	v_mfma_f32_16x16x32_bf16 v[72:75], v[180:183], v[204:207], v[72:75]
	v_mfma_f32_16x16x32_bf16 v[68:71], v[172:175], v[212:215], v[68:71]
	v_mfma_f32_16x16x32_bf16 v[64:67], v[180:183], v[212:215], v[64:67]
	s_setprio 0
	s_barrier
	s_add_i32 s28, s58, s31
	v_lshl_add_u64 v[146:147], v[146:147], 0, s[12:13]
	s_mov_b32 m0, s28
	s_nop 0
	global_load_lds_dwordx4 v[146:147], off
	s_add_i32 m0, s28, 0x2000
	s_add_u32 s26, s26, 0x40080
	v_lshl_add_u64 v[146:147], v[216:217], 0, s[12:13]
	s_addc_u32 s27, s27, 0
	s_add_i32 s28, s59, s31
	global_load_lds_dwordx4 v[146:147], off
	v_lshl_add_u64 v[146:147], s[26:27], 0, v[130:131]
	s_mov_b32 m0, s28
	s_nop 0
	global_load_lds_dwordx4 v[146:147], off
	v_lshl_add_u64 v[146:147], s[26:27], 0, v[134:135]
	s_add_i32 m0, s28, 0x2000
	s_nop 0
	global_load_lds_dwordx4 v[146:147], off
	v_lshl_add_u64 v[146:147], v[218:219], 0, s[12:13]
	s_mov_b32 m0, s40
	s_nop 0
	global_load_lds_dwordx4 v[146:147], off
	v_lshl_add_u64 v[146:147], v[220:221], 0, s[12:13]
	s_mov_b32 m0, s41
	s_nop 0
	global_load_lds_dwordx4 v[146:147], off
	ds_read_b128 v[184:187], v151 offset:49152
	ds_read_b128 v[188:191], v151 offset:50176
	ds_read_b128 v[192:195], v151 offset:51200
	ds_read_b128 v[196:199], v151 offset:52224
	ds_read_b128 v[200:203], v151 offset:53248
	ds_read_b128 v[204:207], v151 offset:54272
	ds_read_b128 v[208:211], v151 offset:55296
	ds_read_b128 v[212:215], v151 offset:56320
	s_waitcnt vmcnt(8)
	s_waitcnt lgkmcnt(0)
	s_barrier
	s_setprio 1
	s_waitcnt lgkmcnt(0)
	v_mfma_f32_16x16x32_bf16 v[60:63], v[152:155], v[184:187], v[60:63]
	v_mfma_f32_16x16x32_bf16 v[56:59], v[160:163], v[184:187], v[56:59]
	v_mfma_f32_16x16x32_bf16 v[52:55], v[152:155], v[192:195], v[52:55]
	v_mfma_f32_16x16x32_bf16 v[44:47], v[160:163], v[192:195], v[44:47]
	v_mfma_f32_16x16x32_bf16 v[36:39], v[152:155], v[200:203], v[36:39]
	v_mfma_f32_16x16x32_bf16 v[28:31], v[160:163], v[200:203], v[28:31]
	v_mfma_f32_16x16x32_bf16 v[20:23], v[152:155], v[208:211], v[20:23]
	v_mfma_f32_16x16x32_bf16 v[12:15], v[160:163], v[208:211], v[12:15]
	v_mfma_f32_16x16x32_bf16 v[60:63], v[156:159], v[188:191], v[60:63]
	v_mfma_f32_16x16x32_bf16 v[56:59], v[164:167], v[188:191], v[56:59]
	v_mfma_f32_16x16x32_bf16 v[52:55], v[156:159], v[196:199], v[52:55]
	v_mfma_f32_16x16x32_bf16 v[44:47], v[164:167], v[196:199], v[44:47]
	v_mfma_f32_16x16x32_bf16 v[36:39], v[156:159], v[204:207], v[36:39]
	v_mfma_f32_16x16x32_bf16 v[28:31], v[164:167], v[204:207], v[28:31]
	v_mfma_f32_16x16x32_bf16 v[20:23], v[156:159], v[212:215], v[20:23]
	v_mfma_f32_16x16x32_bf16 v[12:15], v[164:167], v[212:215], v[12:15]
	s_setprio 0
	s_setprio 1
	v_mfma_f32_16x16x32_bf16 v[48:51], v[168:171], v[184:187], v[48:51]
	v_mfma_f32_16x16x32_bf16 v[40:43], v[176:179], v[184:187], v[40:43]
	v_mfma_f32_16x16x32_bf16 v[32:35], v[168:171], v[192:195], v[32:35]
	v_mfma_f32_16x16x32_bf16 v[24:27], v[176:179], v[192:195], v[24:27]
	v_mfma_f32_16x16x32_bf16 v[16:19], v[168:171], v[200:203], v[16:19]
	v_mfma_f32_16x16x32_bf16 v[8:11], v[176:179], v[200:203], v[8:11]
	v_mfma_f32_16x16x32_bf16 v[4:7], v[168:171], v[208:211], v[4:7]
	v_mfma_f32_16x16x32_bf16 v[0:3], v[176:179], v[208:211], v[0:3]
	v_mfma_f32_16x16x32_bf16 v[48:51], v[172:175], v[188:191], v[48:51]
	v_mfma_f32_16x16x32_bf16 v[40:43], v[180:183], v[188:191], v[40:43]
	v_mfma_f32_16x16x32_bf16 v[32:35], v[172:175], v[196:199], v[32:35]
	v_mfma_f32_16x16x32_bf16 v[24:27], v[180:183], v[196:199], v[24:27]
	v_mfma_f32_16x16x32_bf16 v[16:19], v[172:175], v[204:207], v[16:19]
	v_mfma_f32_16x16x32_bf16 v[8:11], v[180:183], v[204:207], v[8:11]
	v_mfma_f32_16x16x32_bf16 v[4:7], v[172:175], v[212:215], v[4:7]
	v_mfma_f32_16x16x32_bf16 v[0:3], v[180:183], v[212:215], v[0:3]
	s_setprio 0
	s_barrier
	s_add_i32 s57, s57, 2
	s_add_u32 s24, s24, 0x100
	s_addc_u32 s25, s25, 0
	s_add_u32 s55, s55, 0x100
	s_addc_u32 s56, s56, 0
	s_cmp_gt_u32 s57, 13
.LBB3_20:
	s_add_u32 s26, s24, 0xfffc0080
	s_addc_u32 s27, s25, -1
	s_cmp_eq_u32 s57, 12
	s_cselect_b32 s29, s17, s27
	s_cselect_b32 s28, s53, s26
	s_cselect_b32 s27, s15, s56
	s_cselect_b32 s26, s54, s55
	v_lshl_add_u64 v[146:147], s[24:25], 0, v[138:139]
	s_add_i32 m0, s23, 0xc000
	s_nop 0
	global_load_lds_dwordx4 v[146:147], off
	v_lshl_add_u64 v[146:147], s[24:25], 0, v[140:141]
	s_add_i32 m0, s23, 0xe000
	s_nop 0
	global_load_lds_dwordx4 v[146:147], off
	ds_read_b128 v[152:155], v149
	ds_read_b128 v[156:159], v149 offset:1024
	ds_read_b128 v[160:163], v149 offset:2048
	ds_read_b128 v[164:167], v149 offset:3072
	ds_read_b128 v[168:171], v150
	ds_read_b128 v[172:175], v150 offset:1024
	ds_read_b128 v[176:179], v150 offset:2048
	ds_read_b128 v[180:183], v150 offset:3072
	ds_read_b128 v[184:187], v151
	ds_read_b128 v[188:191], v151 offset:1024
	ds_read_b128 v[192:195], v151 offset:2048
	ds_read_b128 v[196:199], v151 offset:3072
	ds_read_b128 v[200:203], v151 offset:4096
	ds_read_b128 v[204:207], v151 offset:5120
	ds_read_b128 v[208:211], v151 offset:6144
	ds_read_b128 v[212:215], v151 offset:7168
	s_waitcnt vmcnt(8)
	s_waitcnt lgkmcnt(0)
	s_barrier
	s_setprio 1
	s_waitcnt lgkmcnt(0)
	v_mfma_f32_16x16x32_bf16 v[124:127], v[152:155], v[184:187], v[124:127]
	v_mfma_f32_16x16x32_bf16 v[120:123], v[160:163], v[184:187], v[120:123]
	v_mfma_f32_16x16x32_bf16 v[116:119], v[152:155], v[192:195], v[116:119]
	v_mfma_f32_16x16x32_bf16 v[108:111], v[160:163], v[192:195], v[108:111]
	v_mfma_f32_16x16x32_bf16 v[100:103], v[152:155], v[200:203], v[100:103]
	v_mfma_f32_16x16x32_bf16 v[92:95], v[160:163], v[200:203], v[92:95]
	v_mfma_f32_16x16x32_bf16 v[84:87], v[152:155], v[208:211], v[84:87]
	v_mfma_f32_16x16x32_bf16 v[76:79], v[160:163], v[208:211], v[76:79]
	v_mfma_f32_16x16x32_bf16 v[124:127], v[156:159], v[188:191], v[124:127]
	v_mfma_f32_16x16x32_bf16 v[120:123], v[164:167], v[188:191], v[120:123]
	v_mfma_f32_16x16x32_bf16 v[116:119], v[156:159], v[196:199], v[116:119]
	v_mfma_f32_16x16x32_bf16 v[108:111], v[164:167], v[196:199], v[108:111]
	v_mfma_f32_16x16x32_bf16 v[100:103], v[156:159], v[204:207], v[100:103]
	v_mfma_f32_16x16x32_bf16 v[92:95], v[164:167], v[204:207], v[92:95]
	v_mfma_f32_16x16x32_bf16 v[84:87], v[156:159], v[212:215], v[84:87]
	v_mfma_f32_16x16x32_bf16 v[76:79], v[164:167], v[212:215], v[76:79]
	s_setprio 0
	s_setprio 1
	v_mfma_f32_16x16x32_bf16 v[112:115], v[168:171], v[184:187], v[112:115]
	v_mfma_f32_16x16x32_bf16 v[104:107], v[176:179], v[184:187], v[104:107]
	v_mfma_f32_16x16x32_bf16 v[96:99], v[168:171], v[192:195], v[96:99]
	v_mfma_f32_16x16x32_bf16 v[88:91], v[176:179], v[192:195], v[88:91]
	v_mfma_f32_16x16x32_bf16 v[80:83], v[168:171], v[200:203], v[80:83]
	v_mfma_f32_16x16x32_bf16 v[72:75], v[176:179], v[200:203], v[72:75]
	v_mfma_f32_16x16x32_bf16 v[68:71], v[168:171], v[208:211], v[68:71]
	v_mfma_f32_16x16x32_bf16 v[64:67], v[176:179], v[208:211], v[64:67]
	v_mfma_f32_16x16x32_bf16 v[112:115], v[172:175], v[188:191], v[112:115]
	v_mfma_f32_16x16x32_bf16 v[104:107], v[180:183], v[188:191], v[104:107]
	v_mfma_f32_16x16x32_bf16 v[96:99], v[172:175], v[196:199], v[96:99]
	v_mfma_f32_16x16x32_bf16 v[88:91], v[180:183], v[196:199], v[88:91]
	v_mfma_f32_16x16x32_bf16 v[80:83], v[172:175], v[204:207], v[80:83]
	v_mfma_f32_16x16x32_bf16 v[72:75], v[180:183], v[204:207], v[72:75]
	v_mfma_f32_16x16x32_bf16 v[68:71], v[172:175], v[212:215], v[68:71]
	v_mfma_f32_16x16x32_bf16 v[64:67], v[180:183], v[212:215], v[64:67]
	s_setprio 0
	s_barrier
	s_add_i32 s58, s45, s31
	v_lshl_add_u64 v[146:147], s[26:27], 0, v[130:131]
	s_mov_b32 m0, s58
	s_nop 0
	global_load_lds_dwordx4 v[146:147], off
	s_add_i32 m0, s58, 0x2000
	s_add_u32 s58, s26, 0x40000
	v_lshl_add_u64 v[216:217], s[26:27], 0, v[134:135]
	s_addc_u32 s59, s27, 0
	s_add_i32 s60, s46, s31
	global_load_lds_dwordx4 v[216:217], off
	v_lshl_add_u64 v[218:219], s[58:59], 0, v[130:131]
	s_mov_b32 m0, s60
	v_lshl_add_u64 v[220:221], s[28:29], 0, v[132:133]
	global_load_lds_dwordx4 v[218:219], off
	v_lshl_add_u64 v[218:219], s[58:59], 0, v[134:135]
	s_add_i32 m0, s60, 0x2000
	s_nop 0
	global_load_lds_dwordx4 v[218:219], off
	v_lshl_add_u64 v[218:219], s[28:29], 0, v[128:129]
	s_mov_b32 m0, s23
	s_nop 0
	global_load_lds_dwordx4 v[218:219], off
	s_mov_b32 m0, s35
	s_nop 0
	global_load_lds_dwordx4 v[220:221], off
	ds_read_b128 v[184:187], v151 offset:16384
	ds_read_b128 v[188:191], v151 offset:17408
	ds_read_b128 v[192:195], v151 offset:18432
	ds_read_b128 v[196:199], v151 offset:19456
	ds_read_b128 v[200:203], v151 offset:20480
	ds_read_b128 v[204:207], v151 offset:21504
	ds_read_b128 v[208:211], v151 offset:22528
	ds_read_b128 v[212:215], v151 offset:23552
	s_waitcnt vmcnt(8)
	s_waitcnt lgkmcnt(0)
	s_barrier
	s_setprio 1
	s_waitcnt lgkmcnt(0)
	v_mfma_f32_16x16x32_bf16 v[60:63], v[152:155], v[184:187], v[60:63]
	v_mfma_f32_16x16x32_bf16 v[56:59], v[160:163], v[184:187], v[56:59]
	v_mfma_f32_16x16x32_bf16 v[52:55], v[152:155], v[192:195], v[52:55]
	v_mfma_f32_16x16x32_bf16 v[44:47], v[160:163], v[192:195], v[44:47]
	v_mfma_f32_16x16x32_bf16 v[36:39], v[152:155], v[200:203], v[36:39]
	v_mfma_f32_16x16x32_bf16 v[28:31], v[160:163], v[200:203], v[28:31]
	v_mfma_f32_16x16x32_bf16 v[20:23], v[152:155], v[208:211], v[20:23]
	v_mfma_f32_16x16x32_bf16 v[12:15], v[160:163], v[208:211], v[12:15]
	v_mfma_f32_16x16x32_bf16 v[60:63], v[156:159], v[188:191], v[60:63]
	v_mfma_f32_16x16x32_bf16 v[56:59], v[164:167], v[188:191], v[56:59]
	v_mfma_f32_16x16x32_bf16 v[52:55], v[156:159], v[196:199], v[52:55]
	v_mfma_f32_16x16x32_bf16 v[44:47], v[164:167], v[196:199], v[44:47]
	v_mfma_f32_16x16x32_bf16 v[36:39], v[156:159], v[204:207], v[36:39]
	v_mfma_f32_16x16x32_bf16 v[28:31], v[164:167], v[204:207], v[28:31]
	v_mfma_f32_16x16x32_bf16 v[20:23], v[156:159], v[212:215], v[20:23]
	v_mfma_f32_16x16x32_bf16 v[12:15], v[164:167], v[212:215], v[12:15]
	s_setprio 0
	s_setprio 1
	v_mfma_f32_16x16x32_bf16 v[48:51], v[168:171], v[184:187], v[48:51]
	v_mfma_f32_16x16x32_bf16 v[40:43], v[176:179], v[184:187], v[40:43]
	v_mfma_f32_16x16x32_bf16 v[32:35], v[168:171], v[192:195], v[32:35]
	v_mfma_f32_16x16x32_bf16 v[24:27], v[176:179], v[192:195], v[24:27]
	v_mfma_f32_16x16x32_bf16 v[16:19], v[168:171], v[200:203], v[16:19]
	v_mfma_f32_16x16x32_bf16 v[8:11], v[176:179], v[200:203], v[8:11]
	v_mfma_f32_16x16x32_bf16 v[4:7], v[168:171], v[208:211], v[4:7]
	v_mfma_f32_16x16x32_bf16 v[0:3], v[176:179], v[208:211], v[0:3]
	v_mfma_f32_16x16x32_bf16 v[48:51], v[172:175], v[188:191], v[48:51]
	v_mfma_f32_16x16x32_bf16 v[40:43], v[180:183], v[188:191], v[40:43]
	v_mfma_f32_16x16x32_bf16 v[32:35], v[172:175], v[196:199], v[32:35]
	v_mfma_f32_16x16x32_bf16 v[24:27], v[180:183], v[196:199], v[24:27]
	v_mfma_f32_16x16x32_bf16 v[16:19], v[172:175], v[204:207], v[16:19]
	v_mfma_f32_16x16x32_bf16 v[8:11], v[180:183], v[204:207], v[8:11]
	v_mfma_f32_16x16x32_bf16 v[4:7], v[172:175], v[212:215], v[4:7]
	v_mfma_f32_16x16x32_bf16 v[0:3], v[180:183], v[212:215], v[0:3]
	s_setprio 0
	s_barrier
	s_add_i32 s58, 0, 0x18000
	s_add_i32 s59, 0, 0x1c000
	v_add_u32_e32 v164, s58, v148
	v_add_u32_e32 v180, s59, v148
	s_add_u32 s28, s28, 0x40000
	s_addc_u32 s29, s29, 0
	s_mov_b32 m0, s36
	v_lshl_add_u64 v[222:223], s[28:29], 0, v[128:129]
	global_load_lds_dwordx4 v[222:223], off
	v_lshl_add_u64 v[222:223], s[28:29], 0, v[132:133]
	s_mov_b32 m0, s37
	s_nop 0
	global_load_lds_dwordx4 v[222:223], off
	ds_read_b128 v[152:155], v164
	ds_read_b128 v[156:159], v164 offset:1024
	ds_read_b128 v[160:163], v164 offset:2048
	ds_read_b128 v[164:167], v164 offset:3072
	ds_read_b128 v[168:171], v180
	ds_read_b128 v[172:175], v180 offset:1024
	ds_read_b128 v[176:179], v180 offset:2048
	ds_read_b128 v[180:183], v180 offset:3072
	ds_read_b128 v[184:187], v151 offset:32768
	ds_read_b128 v[188:191], v151 offset:33792
	ds_read_b128 v[192:195], v151 offset:34816
	ds_read_b128 v[196:199], v151 offset:35840
	ds_read_b128 v[200:203], v151 offset:36864
	ds_read_b128 v[204:207], v151 offset:37888
	ds_read_b128 v[208:211], v151 offset:38912
	ds_read_b128 v[212:215], v151 offset:39936
	s_waitcnt vmcnt(8)
	s_waitcnt lgkmcnt(0)
	s_barrier
	s_setprio 1
	s_waitcnt lgkmcnt(0)
	v_mfma_f32_16x16x32_bf16 v[124:127], v[152:155], v[184:187], v[124:127]
	v_mfma_f32_16x16x32_bf16 v[120:123], v[160:163], v[184:187], v[120:123]
	v_mfma_f32_16x16x32_bf16 v[116:119], v[152:155], v[192:195], v[116:119]
	v_mfma_f32_16x16x32_bf16 v[108:111], v[160:163], v[192:195], v[108:111]
	v_mfma_f32_16x16x32_bf16 v[100:103], v[152:155], v[200:203], v[100:103]
	v_mfma_f32_16x16x32_bf16 v[92:95], v[160:163], v[200:203], v[92:95]
	v_mfma_f32_16x16x32_bf16 v[84:87], v[152:155], v[208:211], v[84:87]
	v_mfma_f32_16x16x32_bf16 v[76:79], v[160:163], v[208:211], v[76:79]
	v_mfma_f32_16x16x32_bf16 v[124:127], v[156:159], v[188:191], v[124:127]
	v_mfma_f32_16x16x32_bf16 v[120:123], v[164:167], v[188:191], v[120:123]
	v_mfma_f32_16x16x32_bf16 v[116:119], v[156:159], v[196:199], v[116:119]
	v_mfma_f32_16x16x32_bf16 v[108:111], v[164:167], v[196:199], v[108:111]
	v_mfma_f32_16x16x32_bf16 v[100:103], v[156:159], v[204:207], v[100:103]
	v_mfma_f32_16x16x32_bf16 v[92:95], v[164:167], v[204:207], v[92:95]
	v_mfma_f32_16x16x32_bf16 v[84:87], v[156:159], v[212:215], v[84:87]
	v_mfma_f32_16x16x32_bf16 v[76:79], v[164:167], v[212:215], v[76:79]
	s_setprio 0
	s_setprio 1
	v_mfma_f32_16x16x32_bf16 v[112:115], v[168:171], v[184:187], v[112:115]
	v_mfma_f32_16x16x32_bf16 v[104:107], v[176:179], v[184:187], v[104:107]
	v_mfma_f32_16x16x32_bf16 v[96:99], v[168:171], v[192:195], v[96:99]
	v_mfma_f32_16x16x32_bf16 v[88:91], v[176:179], v[192:195], v[88:91]
	v_mfma_f32_16x16x32_bf16 v[80:83], v[168:171], v[200:203], v[80:83]
	v_mfma_f32_16x16x32_bf16 v[72:75], v[176:179], v[200:203], v[72:75]
	v_mfma_f32_16x16x32_bf16 v[68:71], v[168:171], v[208:211], v[68:71]
	v_mfma_f32_16x16x32_bf16 v[64:67], v[176:179], v[208:211], v[64:67]
	v_mfma_f32_16x16x32_bf16 v[112:115], v[172:175], v[188:191], v[112:115]
	v_mfma_f32_16x16x32_bf16 v[104:107], v[180:183], v[188:191], v[104:107]
	v_mfma_f32_16x16x32_bf16 v[96:99], v[172:175], v[196:199], v[96:99]
	v_mfma_f32_16x16x32_bf16 v[88:91], v[180:183], v[196:199], v[88:91]
	v_mfma_f32_16x16x32_bf16 v[80:83], v[172:175], v[204:207], v[80:83]
	v_mfma_f32_16x16x32_bf16 v[72:75], v[180:183], v[204:207], v[72:75]
	v_mfma_f32_16x16x32_bf16 v[68:71], v[172:175], v[212:215], v[68:71]
	v_mfma_f32_16x16x32_bf16 v[64:67], v[180:183], v[212:215], v[64:67]
	s_setprio 0
	s_barrier
	s_add_i32 s28, s58, s31
	v_lshl_add_u64 v[146:147], v[146:147], 0, s[12:13]
	s_mov_b32 m0, s28
	s_nop 0
	global_load_lds_dwordx4 v[146:147], off
	s_add_i32 m0, s28, 0x2000
	s_add_u32 s26, s26, 0x40080
	v_lshl_add_u64 v[146:147], v[216:217], 0, s[12:13]
	s_addc_u32 s27, s27, 0
	s_add_i32 s28, s59, s31
	global_load_lds_dwordx4 v[146:147], off
	v_lshl_add_u64 v[146:147], s[26:27], 0, v[130:131]
	s_mov_b32 m0, s28
	s_nop 0
	global_load_lds_dwordx4 v[146:147], off
	v_lshl_add_u64 v[146:147], s[26:27], 0, v[134:135]
	s_add_i32 m0, s28, 0x2000
	s_nop 0
	global_load_lds_dwordx4 v[146:147], off
	v_lshl_add_u64 v[146:147], v[218:219], 0, s[12:13]
	s_mov_b32 m0, s40
	s_nop 0
	global_load_lds_dwordx4 v[146:147], off
	v_lshl_add_u64 v[146:147], v[220:221], 0, s[12:13]
	s_mov_b32 m0, s41
	s_nop 0
	global_load_lds_dwordx4 v[146:147], off
	ds_read_b128 v[184:187], v151 offset:49152
	ds_read_b128 v[188:191], v151 offset:50176
	ds_read_b128 v[192:195], v151 offset:51200
	ds_read_b128 v[196:199], v151 offset:52224
	ds_read_b128 v[200:203], v151 offset:53248
	ds_read_b128 v[204:207], v151 offset:54272
	ds_read_b128 v[208:211], v151 offset:55296
	ds_read_b128 v[212:215], v151 offset:56320
	s_waitcnt vmcnt(8)
	s_waitcnt lgkmcnt(0)
	s_barrier
	s_setprio 1
	s_waitcnt lgkmcnt(0)
	v_mfma_f32_16x16x32_bf16 v[60:63], v[152:155], v[184:187], v[60:63]
	v_mfma_f32_16x16x32_bf16 v[56:59], v[160:163], v[184:187], v[56:59]
	v_mfma_f32_16x16x32_bf16 v[52:55], v[152:155], v[192:195], v[52:55]
	v_mfma_f32_16x16x32_bf16 v[44:47], v[160:163], v[192:195], v[44:47]
	v_mfma_f32_16x16x32_bf16 v[36:39], v[152:155], v[200:203], v[36:39]
	v_mfma_f32_16x16x32_bf16 v[28:31], v[160:163], v[200:203], v[28:31]
	v_mfma_f32_16x16x32_bf16 v[20:23], v[152:155], v[208:211], v[20:23]
	v_mfma_f32_16x16x32_bf16 v[12:15], v[160:163], v[208:211], v[12:15]
	v_mfma_f32_16x16x32_bf16 v[60:63], v[156:159], v[188:191], v[60:63]
	v_mfma_f32_16x16x32_bf16 v[56:59], v[164:167], v[188:191], v[56:59]
	v_mfma_f32_16x16x32_bf16 v[52:55], v[156:159], v[196:199], v[52:55]
	v_mfma_f32_16x16x32_bf16 v[44:47], v[164:167], v[196:199], v[44:47]
	v_mfma_f32_16x16x32_bf16 v[36:39], v[156:159], v[204:207], v[36:39]
	v_mfma_f32_16x16x32_bf16 v[28:31], v[164:167], v[204:207], v[28:31]
	v_mfma_f32_16x16x32_bf16 v[20:23], v[156:159], v[212:215], v[20:23]
	v_mfma_f32_16x16x32_bf16 v[12:15], v[164:167], v[212:215], v[12:15]
	s_setprio 0
	s_setprio 1
	v_mfma_f32_16x16x32_bf16 v[48:51], v[168:171], v[184:187], v[48:51]
	v_mfma_f32_16x16x32_bf16 v[40:43], v[176:179], v[184:187], v[40:43]
	v_mfma_f32_16x16x32_bf16 v[32:35], v[168:171], v[192:195], v[32:35]
	v_mfma_f32_16x16x32_bf16 v[24:27], v[176:179], v[192:195], v[24:27]
	v_mfma_f32_16x16x32_bf16 v[16:19], v[168:171], v[200:203], v[16:19]
	v_mfma_f32_16x16x32_bf16 v[8:11], v[176:179], v[200:203], v[8:11]
	v_mfma_f32_16x16x32_bf16 v[4:7], v[168:171], v[208:211], v[4:7]
	v_mfma_f32_16x16x32_bf16 v[0:3], v[176:179], v[208:211], v[0:3]
	v_mfma_f32_16x16x32_bf16 v[48:51], v[172:175], v[188:191], v[48:51]
	v_mfma_f32_16x16x32_bf16 v[40:43], v[180:183], v[188:191], v[40:43]
	v_mfma_f32_16x16x32_bf16 v[32:35], v[172:175], v[196:199], v[32:35]
	v_mfma_f32_16x16x32_bf16 v[24:27], v[180:183], v[196:199], v[24:27]
	v_mfma_f32_16x16x32_bf16 v[16:19], v[172:175], v[204:207], v[16:19]
	v_mfma_f32_16x16x32_bf16 v[8:11], v[180:183], v[204:207], v[8:11]
	v_mfma_f32_16x16x32_bf16 v[4:7], v[172:175], v[212:215], v[4:7]
	v_mfma_f32_16x16x32_bf16 v[0:3], v[180:183], v[212:215], v[0:3]
	s_setprio 0
	s_barrier
	s_add_i32 s57, s57, 2
	s_add_u32 s24, s24, 0x100
	s_addc_u32 s25, s25, 0
	s_add_u32 s55, s55, 0x100
	s_addc_u32 s56, s56, 0
	s_cmp_gt_u32 s57, 13
	s_cbranch_scc0 .LBB3_20
	s_mov_b64 vcc, s[0:1]
	s_cbranch_vccz .LBB3_23
	s_barrier

.LBB5_8:
	s_ashr_i32 s15, s14, 31
	s_lshl_b64 s[16:17], s[14:15], 19
	s_add_u32 s16, s28, s16
	v_cmp_lt_i64_e64 s[4:5], s[4:5], v[142:143]
	s_addc_u32 s17, s29, s17
	s_and_b64 s[18:19], s[4:5], exec
	s_cselect_b32 s15, s17, s23
	s_cselect_b32 s54, s16, s22
	s_ashr_i32 s13, s12, 31
	s_lshl_b64 s[18:19], s[12:13], 19
	s_add_u32 s18, s30, s18
	s_addc_u32 s19, s31, s19
	s_and_b64 s[26:27], s[4:5], exec
	s_cselect_b32 s13, s19, s25
	s_cselect_b32 s55, s18, s24
	s_add_u32 s22, s22, 0x40080
	s_addc_u32 s23, s23, 0
	s_add_u32 s56, s24, 0x100
	s_addc_u32 s57, s25, 0
	s_mov_b32 s58, -2
	s_add_u32 s24, s22, 0xfffc0080
	s_addc_u32 s25, s23, -1
	s_cmp_eq_u32 s58, 12
	s_cselect_b32 s27, s15, s25
	s_cselect_b32 s26, s54, s24
	s_cselect_b32 s25, s13, s57
	s_cselect_b32 s24, s55, s56
	v_lshl_add_u64 v[146:147], s[22:23], 0, v[138:139]
	s_add_i32 m0, s21, 0xc000
	s_nop 0
	global_load_lds_dwordx4 v[146:147], off
	v_lshl_add_u64 v[146:147], s[22:23], 0, v[140:141]
	s_add_i32 m0, s21, 0xe000
	s_nop 0
	global_load_lds_dwordx4 v[146:147], off
	ds_read_b128 v[152:155], v149
	ds_read_b128 v[156:159], v149 offset:1024
	ds_read_b128 v[160:163], v149 offset:2048
	ds_read_b128 v[164:167], v149 offset:3072
	ds_read_b128 v[168:171], v150
	ds_read_b128 v[172:175], v150 offset:1024
	ds_read_b128 v[176:179], v150 offset:2048
	ds_read_b128 v[180:183], v150 offset:3072
	ds_read_b128 v[184:187], v151
	ds_read_b128 v[188:191], v151 offset:1024
	ds_read_b128 v[192:195], v151 offset:2048
	ds_read_b128 v[196:199], v151 offset:3072
	ds_read_b128 v[200:203], v151 offset:4096
	ds_read_b128 v[204:207], v151 offset:5120
	ds_read_b128 v[208:211], v151 offset:6144
	ds_read_b128 v[212:215], v151 offset:7168
	s_waitcnt vmcnt(8)
	s_waitcnt lgkmcnt(0)
	s_barrier
	s_setprio 1
	s_waitcnt lgkmcnt(0)
	v_mfma_f32_16x16x32_bf16 v[124:127], v[152:155], v[184:187], 0
	v_mfma_f32_16x16x32_bf16 v[120:123], v[160:163], v[184:187], 0
	v_mfma_f32_16x16x32_bf16 v[108:111], v[152:155], v[192:195], 0
	v_mfma_f32_16x16x32_bf16 v[104:107], v[160:163], v[192:195], 0
	v_mfma_f32_16x16x32_bf16 v[92:95], v[152:155], v[200:203], 0
	v_mfma_f32_16x16x32_bf16 v[88:91], v[160:163], v[200:203], 0
	v_mfma_f32_16x16x32_bf16 v[76:79], v[152:155], v[208:211], 0
	v_mfma_f32_16x16x32_bf16 v[72:75], v[160:163], v[208:211], 0
	v_mfma_f32_16x16x32_bf16 v[124:127], v[156:159], v[188:191], v[124:127]
	v_mfma_f32_16x16x32_bf16 v[120:123], v[164:167], v[188:191], v[120:123]
	v_mfma_f32_16x16x32_bf16 v[108:111], v[156:159], v[196:199], v[108:111]
	v_mfma_f32_16x16x32_bf16 v[104:107], v[164:167], v[196:199], v[104:107]
	v_mfma_f32_16x16x32_bf16 v[92:95], v[156:159], v[204:207], v[92:95]
	v_mfma_f32_16x16x32_bf16 v[88:91], v[164:167], v[204:207], v[88:91]
	v_mfma_f32_16x16x32_bf16 v[76:79], v[156:159], v[212:215], v[76:79]
	v_mfma_f32_16x16x32_bf16 v[72:75], v[164:167], v[212:215], v[72:75]
	s_setprio 0
	s_setprio 1
	v_mfma_f32_16x16x32_bf16 v[116:119], v[168:171], v[184:187], 0
	v_mfma_f32_16x16x32_bf16 v[112:115], v[176:179], v[184:187], 0
	v_mfma_f32_16x16x32_bf16 v[100:103], v[168:171], v[192:195], 0
	v_mfma_f32_16x16x32_bf16 v[96:99], v[176:179], v[192:195], 0
	v_mfma_f32_16x16x32_bf16 v[84:87], v[168:171], v[200:203], 0
	v_mfma_f32_16x16x32_bf16 v[80:83], v[176:179], v[200:203], 0
	v_mfma_f32_16x16x32_bf16 v[68:71], v[168:171], v[208:211], 0
	v_mfma_f32_16x16x32_bf16 v[64:67], v[176:179], v[208:211], 0
	v_mfma_f32_16x16x32_bf16 v[116:119], v[172:175], v[188:191], v[116:119]
	v_mfma_f32_16x16x32_bf16 v[112:115], v[180:183], v[188:191], v[112:115]
	v_mfma_f32_16x16x32_bf16 v[100:103], v[172:175], v[196:199], v[100:103]
	v_mfma_f32_16x16x32_bf16 v[96:99], v[180:183], v[196:199], v[96:99]
	v_mfma_f32_16x16x32_bf16 v[84:87], v[172:175], v[204:207], v[84:87]
	v_mfma_f32_16x16x32_bf16 v[80:83], v[180:183], v[204:207], v[80:83]
	v_mfma_f32_16x16x32_bf16 v[68:71], v[172:175], v[212:215], v[68:71]
	v_mfma_f32_16x16x32_bf16 v[64:67], v[180:183], v[212:215], v[64:67]
	s_setprio 0
	s_barrier
	s_add_i32 s59, s43, s33
	v_lshl_add_u64 v[146:147], s[24:25], 0, v[132:133]
	s_mov_b32 m0, s59
	s_nop 0
	global_load_lds_dwordx4 v[146:147], off
	s_add_i32 m0, s59, 0x2000
	s_add_u32 s60, s24, 0x40000
	v_lshl_add_u64 v[216:217], s[24:25], 0, v[128:129]
	s_addc_u32 s61, s25, 0
	s_add_i32 s59, s44, s33
	global_load_lds_dwordx4 v[216:217], off
	v_lshl_add_u64 v[218:219], s[60:61], 0, v[132:133]
	s_mov_b32 m0, s59
	v_lshl_add_u64 v[220:221], s[26:27], 0, v[130:131]
	global_load_lds_dwordx4 v[218:219], off
	v_lshl_add_u64 v[218:219], s[60:61], 0, v[128:129]
	s_add_i32 m0, s59, 0x2000
	s_nop 0
	global_load_lds_dwordx4 v[218:219], off
	v_lshl_add_u64 v[218:219], s[26:27], 0, v[134:135]
	s_mov_b32 m0, s21
	s_nop 0
	global_load_lds_dwordx4 v[218:219], off
	s_mov_b32 m0, s36
	s_nop 0
	global_load_lds_dwordx4 v[220:221], off
	ds_read_b128 v[184:187], v151 offset:16384
	ds_read_b128 v[188:191], v151 offset:17408
	ds_read_b128 v[192:195], v151 offset:18432
	ds_read_b128 v[196:199], v151 offset:19456
	ds_read_b128 v[200:203], v151 offset:20480
	ds_read_b128 v[204:207], v151 offset:21504
	ds_read_b128 v[208:211], v151 offset:22528
	ds_read_b128 v[212:215], v151 offset:23552
	s_waitcnt vmcnt(8)
	s_waitcnt lgkmcnt(0)
	s_barrier
	s_setprio 1
	s_waitcnt lgkmcnt(0)
	v_mfma_f32_16x16x32_bf16 v[60:63], v[152:155], v[184:187], 0
	v_mfma_f32_16x16x32_bf16 v[56:59], v[160:163], v[184:187], 0
	v_mfma_f32_16x16x32_bf16 v[44:47], v[152:155], v[192:195], 0
	v_mfma_f32_16x16x32_bf16 v[40:43], v[160:163], v[192:195], 0
	v_mfma_f32_16x16x32_bf16 v[28:31], v[152:155], v[200:203], 0
	v_mfma_f32_16x16x32_bf16 v[24:27], v[160:163], v[200:203], 0
	v_mfma_f32_16x16x32_bf16 v[12:15], v[152:155], v[208:211], 0
	v_mfma_f32_16x16x32_bf16 v[8:11], v[160:163], v[208:211], 0
	v_mfma_f32_16x16x32_bf16 v[60:63], v[156:159], v[188:191], v[60:63]
	v_mfma_f32_16x16x32_bf16 v[56:59], v[164:167], v[188:191], v[56:59]
	v_mfma_f32_16x16x32_bf16 v[44:47], v[156:159], v[196:199], v[44:47]
	v_mfma_f32_16x16x32_bf16 v[40:43], v[164:167], v[196:199], v[40:43]
	v_mfma_f32_16x16x32_bf16 v[28:31], v[156:159], v[204:207], v[28:31]
	v_mfma_f32_16x16x32_bf16 v[24:27], v[164:167], v[204:207], v[24:27]
	v_mfma_f32_16x16x32_bf16 v[12:15], v[156:159], v[212:215], v[12:15]
	v_mfma_f32_16x16x32_bf16 v[8:11], v[164:167], v[212:215], v[8:11]
	s_setprio 0
	s_setprio 1
	v_mfma_f32_16x16x32_bf16 v[52:55], v[168:171], v[184:187], 0
	v_mfma_f32_16x16x32_bf16 v[48:51], v[176:179], v[184:187], 0
	v_mfma_f32_16x16x32_bf16 v[36:39], v[168:171], v[192:195], 0
	v_mfma_f32_16x16x32_bf16 v[32:35], v[176:179], v[192:195], 0
	v_mfma_f32_16x16x32_bf16 v[20:23], v[168:171], v[200:203], 0
	v_mfma_f32_16x16x32_bf16 v[16:19], v[176:179], v[200:203], 0
	v_mfma_f32_16x16x32_bf16 v[4:7], v[168:171], v[208:211], 0
	v_mfma_f32_16x16x32_bf16 v[0:3], v[176:179], v[208:211], 0
	v_mfma_f32_16x16x32_bf16 v[52:55], v[172:175], v[188:191], v[52:55]
	v_mfma_f32_16x16x32_bf16 v[48:51], v[180:183], v[188:191], v[48:51]
	v_mfma_f32_16x16x32_bf16 v[36:39], v[172:175], v[196:199], v[36:39]
	v_mfma_f32_16x16x32_bf16 v[32:35], v[180:183], v[196:199], v[32:35]
	v_mfma_f32_16x16x32_bf16 v[20:23], v[172:175], v[204:207], v[20:23]
	v_mfma_f32_16x16x32_bf16 v[16:19], v[180:183], v[204:207], v[16:19]
	v_mfma_f32_16x16x32_bf16 v[4:7], v[172:175], v[212:215], v[4:7]
	v_mfma_f32_16x16x32_bf16 v[0:3], v[180:183], v[212:215], v[0:3]
	s_setprio 0
	s_barrier
	s_add_i32 s59, 0, 0x18000
	s_add_i32 s60, 0, 0x1c000
	v_add_u32_e32 v164, s59, v148
	v_add_u32_e32 v180, s60, v148
	s_add_u32 s26, s26, 0x40000
	s_addc_u32 s27, s27, 0
	s_mov_b32 m0, s37
	v_lshl_add_u64 v[222:223], s[26:27], 0, v[134:135]
	global_load_lds_dwordx4 v[222:223], off
	v_lshl_add_u64 v[222:223], s[26:27], 0, v[130:131]
	s_mov_b32 m0, s38
	s_nop 0
	global_load_lds_dwordx4 v[222:223], off
	ds_read_b128 v[152:155], v164
	ds_read_b128 v[156:159], v164 offset:1024
	ds_read_b128 v[160:163], v164 offset:2048
	ds_read_b128 v[164:167], v164 offset:3072
	ds_read_b128 v[168:171], v180
	ds_read_b128 v[172:175], v180 offset:1024
	ds_read_b128 v[176:179], v180 offset:2048
	ds_read_b128 v[180:183], v180 offset:3072
	ds_read_b128 v[184:187], v151 offset:32768
	ds_read_b128 v[188:191], v151 offset:33792
	ds_read_b128 v[192:195], v151 offset:34816
	ds_read_b128 v[196:199], v151 offset:35840
	ds_read_b128 v[200:203], v151 offset:36864
	ds_read_b128 v[204:207], v151 offset:37888
	ds_read_b128 v[208:211], v151 offset:38912
	ds_read_b128 v[212:215], v151 offset:39936
	s_waitcnt vmcnt(8)
	s_waitcnt lgkmcnt(0)
	s_barrier
	s_setprio 1
	s_waitcnt lgkmcnt(0)
	v_mfma_f32_16x16x32_bf16 v[124:127], v[152:155], v[184:187], v[124:127]
	v_mfma_f32_16x16x32_bf16 v[120:123], v[160:163], v[184:187], v[120:123]
	v_mfma_f32_16x16x32_bf16 v[108:111], v[152:155], v[192:195], v[108:111]
	v_mfma_f32_16x16x32_bf16 v[104:107], v[160:163], v[192:195], v[104:107]
	v_mfma_f32_16x16x32_bf16 v[92:95], v[152:155], v[200:203], v[92:95]
	v_mfma_f32_16x16x32_bf16 v[88:91], v[160:163], v[200:203], v[88:91]
	v_mfma_f32_16x16x32_bf16 v[76:79], v[152:155], v[208:211], v[76:79]
	v_mfma_f32_16x16x32_bf16 v[72:75], v[160:163], v[208:211], v[72:75]
	v_mfma_f32_16x16x32_bf16 v[124:127], v[156:159], v[188:191], v[124:127]
	v_mfma_f32_16x16x32_bf16 v[120:123], v[164:167], v[188:191], v[120:123]
	v_mfma_f32_16x16x32_bf16 v[108:111], v[156:159], v[196:199], v[108:111]
	v_mfma_f32_16x16x32_bf16 v[104:107], v[164:167], v[196:199], v[104:107]
	v_mfma_f32_16x16x32_bf16 v[92:95], v[156:159], v[204:207], v[92:95]
	v_mfma_f32_16x16x32_bf16 v[88:91], v[164:167], v[204:207], v[88:91]
	v_mfma_f32_16x16x32_bf16 v[76:79], v[156:159], v[212:215], v[76:79]
	v_mfma_f32_16x16x32_bf16 v[72:75], v[164:167], v[212:215], v[72:75]
	s_setprio 0
	s_setprio 1
	v_mfma_f32_16x16x32_bf16 v[116:119], v[168:171], v[184:187], v[116:119]
	v_mfma_f32_16x16x32_bf16 v[112:115], v[176:179], v[184:187], v[112:115]
	v_mfma_f32_16x16x32_bf16 v[100:103], v[168:171], v[192:195], v[100:103]
	v_mfma_f32_16x16x32_bf16 v[96:99], v[176:179], v[192:195], v[96:99]
	v_mfma_f32_16x16x32_bf16 v[84:87], v[168:171], v[200:203], v[84:87]
	v_mfma_f32_16x16x32_bf16 v[80:83], v[176:179], v[200:203], v[80:83]
	v_mfma_f32_16x16x32_bf16 v[68:71], v[168:171], v[208:211], v[68:71]
	v_mfma_f32_16x16x32_bf16 v[64:67], v[176:179], v[208:211], v[64:67]
	v_mfma_f32_16x16x32_bf16 v[116:119], v[172:175], v[188:191], v[116:119]
	v_mfma_f32_16x16x32_bf16 v[112:115], v[180:183], v[188:191], v[112:115]
	v_mfma_f32_16x16x32_bf16 v[100:103], v[172:175], v[196:199], v[100:103]
	v_mfma_f32_16x16x32_bf16 v[96:99], v[180:183], v[196:199], v[96:99]
	v_mfma_f32_16x16x32_bf16 v[84:87], v[172:175], v[204:207], v[84:87]
	v_mfma_f32_16x16x32_bf16 v[80:83], v[180:183], v[204:207], v[80:83]
	v_mfma_f32_16x16x32_bf16 v[68:71], v[172:175], v[212:215], v[68:71]
	v_mfma_f32_16x16x32_bf16 v[64:67], v[180:183], v[212:215], v[64:67]
	s_setprio 0
	s_barrier
	s_add_i32 s26, s59, s33
	v_lshl_add_u64 v[146:147], v[146:147], 0, s[10:11]
	s_mov_b32 m0, s26
	s_nop 0
	global_load_lds_dwordx4 v[146:147], off
	s_add_i32 m0, s26, 0x2000
	s_add_u32 s24, s24, 0x40080
	v_lshl_add_u64 v[146:147], v[216:217], 0, s[10:11]
	s_addc_u32 s25, s25, 0
	s_add_i32 s26, s60, s33
	global_load_lds_dwordx4 v[146:147], off
	v_lshl_add_u64 v[146:147], s[24:25], 0, v[132:133]
	s_mov_b32 m0, s26
	s_nop 0
	global_load_lds_dwordx4 v[146:147], off
	v_lshl_add_u64 v[146:147], s[24:25], 0, v[128:129]
	s_add_i32 m0, s26, 0x2000
	s_nop 0
	global_load_lds_dwordx4 v[146:147], off
	v_lshl_add_u64 v[146:147], v[218:219], 0, s[10:11]
	s_mov_b32 m0, s40
	s_nop 0
	global_load_lds_dwordx4 v[146:147], off
	v_lshl_add_u64 v[146:147], v[220:221], 0, s[10:11]
	s_mov_b32 m0, s41
	s_nop 0
	global_load_lds_dwordx4 v[146:147], off
	ds_read_b128 v[184:187], v151 offset:49152
	ds_read_b128 v[188:191], v151 offset:50176
	ds_read_b128 v[192:195], v151 offset:51200
	ds_read_b128 v[196:199], v151 offset:52224
	ds_read_b128 v[200:203], v151 offset:53248
	ds_read_b128 v[204:207], v151 offset:54272
	ds_read_b128 v[208:211], v151 offset:55296
	ds_read_b128 v[212:215], v151 offset:56320
	s_waitcnt vmcnt(8)
	s_waitcnt lgkmcnt(0)
	s_barrier
	s_setprio 1
	s_waitcnt lgkmcnt(0)
	v_mfma_f32_16x16x32_bf16 v[60:63], v[152:155], v[184:187], v[60:63]
	v_mfma_f32_16x16x32_bf16 v[56:59], v[160:163], v[184:187], v[56:59]
	v_mfma_f32_16x16x32_bf16 v[44:47], v[152:155], v[192:195], v[44:47]
	v_mfma_f32_16x16x32_bf16 v[40:43], v[160:163], v[192:195], v[40:43]
	v_mfma_f32_16x16x32_bf16 v[28:31], v[152:155], v[200:203], v[28:31]
	v_mfma_f32_16x16x32_bf16 v[24:27], v[160:163], v[200:203], v[24:27]
	v_mfma_f32_16x16x32_bf16 v[12:15], v[152:155], v[208:211], v[12:15]
	v_mfma_f32_16x16x32_bf16 v[8:11], v[160:163], v[208:211], v[8:11]
	v_mfma_f32_16x16x32_bf16 v[60:63], v[156:159], v[188:191], v[60:63]
	v_mfma_f32_16x16x32_bf16 v[56:59], v[164:167], v[188:191], v[56:59]
	v_mfma_f32_16x16x32_bf16 v[44:47], v[156:159], v[196:199], v[44:47]
	v_mfma_f32_16x16x32_bf16 v[40:43], v[164:167], v[196:199], v[40:43]
	v_mfma_f32_16x16x32_bf16 v[28:31], v[156:159], v[204:207], v[28:31]
	v_mfma_f32_16x16x32_bf16 v[24:27], v[164:167], v[204:207], v[24:27]
	v_mfma_f32_16x16x32_bf16 v[12:15], v[156:159], v[212:215], v[12:15]
	v_mfma_f32_16x16x32_bf16 v[8:11], v[164:167], v[212:215], v[8:11]
	s_setprio 0
	s_setprio 1
	v_mfma_f32_16x16x32_bf16 v[52:55], v[168:171], v[184:187], v[52:55]
	v_mfma_f32_16x16x32_bf16 v[48:51], v[176:179], v[184:187], v[48:51]
	v_mfma_f32_16x16x32_bf16 v[36:39], v[168:171], v[192:195], v[36:39]
	v_mfma_f32_16x16x32_bf16 v[32:35], v[176:179], v[192:195], v[32:35]
	v_mfma_f32_16x16x32_bf16 v[20:23], v[168:171], v[200:203], v[20:23]
	v_mfma_f32_16x16x32_bf16 v[16:19], v[176:179], v[200:203], v[16:19]
	v_mfma_f32_16x16x32_bf16 v[4:7], v[168:171], v[208:211], v[4:7]
	v_mfma_f32_16x16x32_bf16 v[0:3], v[176:179], v[208:211], v[0:3]
	v_mfma_f32_16x16x32_bf16 v[52:55], v[172:175], v[188:191], v[52:55]
	v_mfma_f32_16x16x32_bf16 v[48:51], v[180:183], v[188:191], v[48:51]
	v_mfma_f32_16x16x32_bf16 v[36:39], v[172:175], v[196:199], v[36:39]
	v_mfma_f32_16x16x32_bf16 v[32:35], v[180:183], v[196:199], v[32:35]
	v_mfma_f32_16x16x32_bf16 v[20:23], v[172:175], v[204:207], v[20:23]
	v_mfma_f32_16x16x32_bf16 v[16:19], v[180:183], v[204:207], v[16:19]
	v_mfma_f32_16x16x32_bf16 v[4:7], v[172:175], v[212:215], v[4:7]
	v_mfma_f32_16x16x32_bf16 v[0:3], v[180:183], v[212:215], v[0:3]
	s_setprio 0
	s_barrier
	s_add_i32 s58, s58, 2
	s_add_u32 s22, s22, 0x100
	s_addc_u32 s23, s23, 0
	s_add_u32 s56, s56, 0x100
	s_addc_u32 s57, s57, 0
	s_cmp_gt_u32 s58, 13
.LBB5_9:
	s_add_u32 s24, s22, 0xfffc0080
	s_addc_u32 s25, s23, -1
	s_cmp_eq_u32 s58, 12
	s_cselect_b32 s27, s15, s25
	s_cselect_b32 s26, s54, s24
	s_cselect_b32 s25, s13, s57
	s_cselect_b32 s24, s55, s56
	v_lshl_add_u64 v[146:147], s[22:23], 0, v[138:139]
	s_add_i32 m0, s21, 0xc000
	s_nop 0
	global_load_lds_dwordx4 v[146:147], off
	v_lshl_add_u64 v[146:147], s[22:23], 0, v[140:141]
	s_add_i32 m0, s21, 0xe000
	s_nop 0
	global_load_lds_dwordx4 v[146:147], off
	ds_read_b128 v[152:155], v149
	ds_read_b128 v[156:159], v149 offset:1024
	ds_read_b128 v[160:163], v149 offset:2048
	ds_read_b128 v[164:167], v149 offset:3072
	ds_read_b128 v[168:171], v150
	ds_read_b128 v[172:175], v150 offset:1024
	ds_read_b128 v[176:179], v150 offset:2048
	ds_read_b128 v[180:183], v150 offset:3072
	ds_read_b128 v[184:187], v151
	ds_read_b128 v[188:191], v151 offset:1024
	ds_read_b128 v[192:195], v151 offset:2048
	ds_read_b128 v[196:199], v151 offset:3072
	ds_read_b128 v[200:203], v151 offset:4096
	ds_read_b128 v[204:207], v151 offset:5120
	ds_read_b128 v[208:211], v151 offset:6144
	ds_read_b128 v[212:215], v151 offset:7168
	s_waitcnt vmcnt(8)
	s_waitcnt lgkmcnt(0)
	s_barrier
	s_setprio 1
	s_waitcnt lgkmcnt(0)
	v_mfma_f32_16x16x32_bf16 v[124:127], v[152:155], v[184:187], v[124:127]
	v_mfma_f32_16x16x32_bf16 v[120:123], v[160:163], v[184:187], v[120:123]
	v_mfma_f32_16x16x32_bf16 v[108:111], v[152:155], v[192:195], v[108:111]
	v_mfma_f32_16x16x32_bf16 v[104:107], v[160:163], v[192:195], v[104:107]
	v_mfma_f32_16x16x32_bf16 v[92:95], v[152:155], v[200:203], v[92:95]
	v_mfma_f32_16x16x32_bf16 v[88:91], v[160:163], v[200:203], v[88:91]
	v_mfma_f32_16x16x32_bf16 v[76:79], v[152:155], v[208:211], v[76:79]
	v_mfma_f32_16x16x32_bf16 v[72:75], v[160:163], v[208:211], v[72:75]
	v_mfma_f32_16x16x32_bf16 v[124:127], v[156:159], v[188:191], v[124:127]
	v_mfma_f32_16x16x32_bf16 v[120:123], v[164:167], v[188:191], v[120:123]
	v_mfma_f32_16x16x32_bf16 v[108:111], v[156:159], v[196:199], v[108:111]
	v_mfma_f32_16x16x32_bf16 v[104:107], v[164:167], v[196:199], v[104:107]
	v_mfma_f32_16x16x32_bf16 v[92:95], v[156:159], v[204:207], v[92:95]
	v_mfma_f32_16x16x32_bf16 v[88:91], v[164:167], v[204:207], v[88:91]
	v_mfma_f32_16x16x32_bf16 v[76:79], v[156:159], v[212:215], v[76:79]
	v_mfma_f32_16x16x32_bf16 v[72:75], v[164:167], v[212:215], v[72:75]
	s_setprio 0
	s_setprio 1
	v_mfma_f32_16x16x32_bf16 v[116:119], v[168:171], v[184:187], v[116:119]
	v_mfma_f32_16x16x32_bf16 v[112:115], v[176:179], v[184:187], v[112:115]
	v_mfma_f32_16x16x32_bf16 v[100:103], v[168:171], v[192:195], v[100:103]
	v_mfma_f32_16x16x32_bf16 v[96:99], v[176:179], v[192:195], v[96:99]
	v_mfma_f32_16x16x32_bf16 v[84:87], v[168:171], v[200:203], v[84:87]
	v_mfma_f32_16x16x32_bf16 v[80:83], v[176:179], v[200:203], v[80:83]
	v_mfma_f32_16x16x32_bf16 v[68:71], v[168:171], v[208:211], v[68:71]
	v_mfma_f32_16x16x32_bf16 v[64:67], v[176:179], v[208:211], v[64:67]
	v_mfma_f32_16x16x32_bf16 v[116:119], v[172:175], v[188:191], v[116:119]
	v_mfma_f32_16x16x32_bf16 v[112:115], v[180:183], v[188:191], v[112:115]
	v_mfma_f32_16x16x32_bf16 v[100:103], v[172:175], v[196:199], v[100:103]
	v_mfma_f32_16x16x32_bf16 v[96:99], v[180:183], v[196:199], v[96:99]
	v_mfma_f32_16x16x32_bf16 v[84:87], v[172:175], v[204:207], v[84:87]
	v_mfma_f32_16x16x32_bf16 v[80:83], v[180:183], v[204:207], v[80:83]
	v_mfma_f32_16x16x32_bf16 v[68:71], v[172:175], v[212:215], v[68:71]
	v_mfma_f32_16x16x32_bf16 v[64:67], v[180:183], v[212:215], v[64:67]
	s_setprio 0
	s_barrier
	s_add_i32 s59, s43, s33
	v_lshl_add_u64 v[146:147], s[24:25], 0, v[132:133]
	s_mov_b32 m0, s59
	s_nop 0
	global_load_lds_dwordx4 v[146:147], off
	s_add_i32 m0, s59, 0x2000
	s_add_u32 s60, s24, 0x40000
	v_lshl_add_u64 v[216:217], s[24:25], 0, v[128:129]
	s_addc_u32 s61, s25, 0
	s_add_i32 s59, s44, s33
	global_load_lds_dwordx4 v[216:217], off
	v_lshl_add_u64 v[218:219], s[60:61], 0, v[132:133]
	s_mov_b32 m0, s59
	v_lshl_add_u64 v[220:221], s[26:27], 0, v[130:131]
	global_load_lds_dwordx4 v[218:219], off
	v_lshl_add_u64 v[218:219], s[60:61], 0, v[128:129]
	s_add_i32 m0, s59, 0x2000
	s_nop 0
	global_load_lds_dwordx4 v[218:219], off
	v_lshl_add_u64 v[218:219], s[26:27], 0, v[134:135]
	s_mov_b32 m0, s21
	s_nop 0
	global_load_lds_dwordx4 v[218:219], off
	s_mov_b32 m0, s36
	s_nop 0
	global_load_lds_dwordx4 v[220:221], off
	ds_read_b128 v[184:187], v151 offset:16384
	ds_read_b128 v[188:191], v151 offset:17408
	ds_read_b128 v[192:195], v151 offset:18432
	ds_read_b128 v[196:199], v151 offset:19456
	ds_read_b128 v[200:203], v151 offset:20480
	ds_read_b128 v[204:207], v151 offset:21504
	ds_read_b128 v[208:211], v151 offset:22528
	ds_read_b128 v[212:215], v151 offset:23552
	s_waitcnt vmcnt(8)
	s_waitcnt lgkmcnt(0)
	s_barrier
	s_setprio 1
	s_waitcnt lgkmcnt(0)
	v_mfma_f32_16x16x32_bf16 v[60:63], v[152:155], v[184:187], v[60:63]
	v_mfma_f32_16x16x32_bf16 v[56:59], v[160:163], v[184:187], v[56:59]
	v_mfma_f32_16x16x32_bf16 v[44:47], v[152:155], v[192:195], v[44:47]
	v_mfma_f32_16x16x32_bf16 v[40:43], v[160:163], v[192:195], v[40:43]
	v_mfma_f32_16x16x32_bf16 v[28:31], v[152:155], v[200:203], v[28:31]
	v_mfma_f32_16x16x32_bf16 v[24:27], v[160:163], v[200:203], v[24:27]
	v_mfma_f32_16x16x32_bf16 v[12:15], v[152:155], v[208:211], v[12:15]
	v_mfma_f32_16x16x32_bf16 v[8:11], v[160:163], v[208:211], v[8:11]
	v_mfma_f32_16x16x32_bf16 v[60:63], v[156:159], v[188:191], v[60:63]
	v_mfma_f32_16x16x32_bf16 v[56:59], v[164:167], v[188:191], v[56:59]
	v_mfma_f32_16x16x32_bf16 v[44:47], v[156:159], v[196:199], v[44:47]
	v_mfma_f32_16x16x32_bf16 v[40:43], v[164:167], v[196:199], v[40:43]
	v_mfma_f32_16x16x32_bf16 v[28:31], v[156:159], v[204:207], v[28:31]
	v_mfma_f32_16x16x32_bf16 v[24:27], v[164:167], v[204:207], v[24:27]
	v_mfma_f32_16x16x32_bf16 v[12:15], v[156:159], v[212:215], v[12:15]
	v_mfma_f32_16x16x32_bf16 v[8:11], v[164:167], v[212:215], v[8:11]
	s_setprio 0
	s_setprio 1
	v_mfma_f32_16x16x32_bf16 v[52:55], v[168:171], v[184:187], v[52:55]
	v_mfma_f32_16x16x32_bf16 v[48:51], v[176:179], v[184:187], v[48:51]
	v_mfma_f32_16x16x32_bf16 v[36:39], v[168:171], v[192:195], v[36:39]
	v_mfma_f32_16x16x32_bf16 v[32:35], v[176:179], v[192:195], v[32:35]
	v_mfma_f32_16x16x32_bf16 v[20:23], v[168:171], v[200:203], v[20:23]
	v_mfma_f32_16x16x32_bf16 v[16:19], v[176:179], v[200:203], v[16:19]
	v_mfma_f32_16x16x32_bf16 v[4:7], v[168:171], v[208:211], v[4:7]
	v_mfma_f32_16x16x32_bf16 v[0:3], v[176:179], v[208:211], v[0:3]
	v_mfma_f32_16x16x32_bf16 v[52:55], v[172:175], v[188:191], v[52:55]
	v_mfma_f32_16x16x32_bf16 v[48:51], v[180:183], v[188:191], v[48:51]
	v_mfma_f32_16x16x32_bf16 v[36:39], v[172:175], v[196:199], v[36:39]
	v_mfma_f32_16x16x32_bf16 v[32:35], v[180:183], v[196:199], v[32:35]
	v_mfma_f32_16x16x32_bf16 v[20:23], v[172:175], v[204:207], v[20:23]
	v_mfma_f32_16x16x32_bf16 v[16:19], v[180:183], v[204:207], v[16:19]
	v_mfma_f32_16x16x32_bf16 v[4:7], v[172:175], v[212:215], v[4:7]
	v_mfma_f32_16x16x32_bf16 v[0:3], v[180:183], v[212:215], v[0:3]
	s_setprio 0
	s_barrier
	s_add_i32 s59, 0, 0x18000
	s_add_i32 s60, 0, 0x1c000
	v_add_u32_e32 v164, s59, v148
	v_add_u32_e32 v180, s60, v148
	s_add_u32 s26, s26, 0x40000
	s_addc_u32 s27, s27, 0
	s_mov_b32 m0, s37
	v_lshl_add_u64 v[222:223], s[26:27], 0, v[134:135]
	global_load_lds_dwordx4 v[222:223], off
	v_lshl_add_u64 v[222:223], s[26:27], 0, v[130:131]
	s_mov_b32 m0, s38
	s_nop 0
	global_load_lds_dwordx4 v[222:223], off
	ds_read_b128 v[152:155], v164
	ds_read_b128 v[156:159], v164 offset:1024
	ds_read_b128 v[160:163], v164 offset:2048
	ds_read_b128 v[164:167], v164 offset:3072
	ds_read_b128 v[168:171], v180
	ds_read_b128 v[172:175], v180 offset:1024
	ds_read_b128 v[176:179], v180 offset:2048
	ds_read_b128 v[180:183], v180 offset:3072
	ds_read_b128 v[184:187], v151 offset:32768
	ds_read_b128 v[188:191], v151 offset:33792
	ds_read_b128 v[192:195], v151 offset:34816
	ds_read_b128 v[196:199], v151 offset:35840
	ds_read_b128 v[200:203], v151 offset:36864
	ds_read_b128 v[204:207], v151 offset:37888
	ds_read_b128 v[208:211], v151 offset:38912
	ds_read_b128 v[212:215], v151 offset:39936
	s_waitcnt vmcnt(8)
	s_waitcnt lgkmcnt(0)
	s_barrier
	s_setprio 1
	s_waitcnt lgkmcnt(0)
	v_mfma_f32_16x16x32_bf16 v[124:127], v[152:155], v[184:187], v[124:127]
	v_mfma_f32_16x16x32_bf16 v[120:123], v[160:163], v[184:187], v[120:123]
	v_mfma_f32_16x16x32_bf16 v[108:111], v[152:155], v[192:195], v[108:111]
	v_mfma_f32_16x16x32_bf16 v[104:107], v[160:163], v[192:195], v[104:107]
	v_mfma_f32_16x16x32_bf16 v[92:95], v[152:155], v[200:203], v[92:95]
	v_mfma_f32_16x16x32_bf16 v[88:91], v[160:163], v[200:203], v[88:91]
	v_mfma_f32_16x16x32_bf16 v[76:79], v[152:155], v[208:211], v[76:79]
	v_mfma_f32_16x16x32_bf16 v[72:75], v[160:163], v[208:211], v[72:75]
	v_mfma_f32_16x16x32_bf16 v[124:127], v[156:159], v[188:191], v[124:127]
	v_mfma_f32_16x16x32_bf16 v[120:123], v[164:167], v[188:191], v[120:123]
	v_mfma_f32_16x16x32_bf16 v[108:111], v[156:159], v[196:199], v[108:111]
	v_mfma_f32_16x16x32_bf16 v[104:107], v[164:167], v[196:199], v[104:107]
	v_mfma_f32_16x16x32_bf16 v[92:95], v[156:159], v[204:207], v[92:95]
	v_mfma_f32_16x16x32_bf16 v[88:91], v[164:167], v[204:207], v[88:91]
	v_mfma_f32_16x16x32_bf16 v[76:79], v[156:159], v[212:215], v[76:79]
	v_mfma_f32_16x16x32_bf16 v[72:75], v[164:167], v[212:215], v[72:75]
	s_setprio 0
	s_setprio 1
	v_mfma_f32_16x16x32_bf16 v[116:119], v[168:171], v[184:187], v[116:119]
	v_mfma_f32_16x16x32_bf16 v[112:115], v[176:179], v[184:187], v[112:115]
	v_mfma_f32_16x16x32_bf16 v[100:103], v[168:171], v[192:195], v[100:103]
	v_mfma_f32_16x16x32_bf16 v[96:99], v[176:179], v[192:195], v[96:99]
	v_mfma_f32_16x16x32_bf16 v[84:87], v[168:171], v[200:203], v[84:87]
	v_mfma_f32_16x16x32_bf16 v[80:83], v[176:179], v[200:203], v[80:83]
	v_mfma_f32_16x16x32_bf16 v[68:71], v[168:171], v[208:211], v[68:71]
	v_mfma_f32_16x16x32_bf16 v[64:67], v[176:179], v[208:211], v[64:67]
	v_mfma_f32_16x16x32_bf16 v[116:119], v[172:175], v[188:191], v[116:119]
	v_mfma_f32_16x16x32_bf16 v[112:115], v[180:183], v[188:191], v[112:115]
	v_mfma_f32_16x16x32_bf16 v[100:103], v[172:175], v[196:199], v[100:103]
	v_mfma_f32_16x16x32_bf16 v[96:99], v[180:183], v[196:199], v[96:99]
	v_mfma_f32_16x16x32_bf16 v[84:87], v[172:175], v[204:207], v[84:87]
	v_mfma_f32_16x16x32_bf16 v[80:83], v[180:183], v[204:207], v[80:83]
	v_mfma_f32_16x16x32_bf16 v[68:71], v[172:175], v[212:215], v[68:71]
	v_mfma_f32_16x16x32_bf16 v[64:67], v[180:183], v[212:215], v[64:67]
	s_setprio 0
	s_barrier
	s_add_i32 s26, s59, s33
	v_lshl_add_u64 v[146:147], v[146:147], 0, s[10:11]
	s_mov_b32 m0, s26
	s_nop 0
	global_load_lds_dwordx4 v[146:147], off
	s_add_i32 m0, s26, 0x2000
	s_add_u32 s24, s24, 0x40080
	v_lshl_add_u64 v[146:147], v[216:217], 0, s[10:11]
	s_addc_u32 s25, s25, 0
	s_add_i32 s26, s60, s33
	global_load_lds_dwordx4 v[146:147], off
	v_lshl_add_u64 v[146:147], s[24:25], 0, v[132:133]
	s_mov_b32 m0, s26
	s_nop 0
	global_load_lds_dwordx4 v[146:147], off
	v_lshl_add_u64 v[146:147], s[24:25], 0, v[128:129]
	s_add_i32 m0, s26, 0x2000
	s_nop 0
	global_load_lds_dwordx4 v[146:147], off
	v_lshl_add_u64 v[146:147], v[218:219], 0, s[10:11]
	s_mov_b32 m0, s40
	s_nop 0
	global_load_lds_dwordx4 v[146:147], off
	v_lshl_add_u64 v[146:147], v[220:221], 0, s[10:11]
	s_mov_b32 m0, s41
	s_nop 0
	global_load_lds_dwordx4 v[146:147], off
	ds_read_b128 v[184:187], v151 offset:49152
	ds_read_b128 v[188:191], v151 offset:50176
	ds_read_b128 v[192:195], v151 offset:51200
	ds_read_b128 v[196:199], v151 offset:52224
	ds_read_b128 v[200:203], v151 offset:53248
	ds_read_b128 v[204:207], v151 offset:54272
	ds_read_b128 v[208:211], v151 offset:55296
	ds_read_b128 v[212:215], v151 offset:56320
	s_waitcnt vmcnt(8)
	s_waitcnt lgkmcnt(0)
	s_barrier
	s_setprio 1
	s_waitcnt lgkmcnt(0)
	v_mfma_f32_16x16x32_bf16 v[60:63], v[152:155], v[184:187], v[60:63]
	v_mfma_f32_16x16x32_bf16 v[56:59], v[160:163], v[184:187], v[56:59]
	v_mfma_f32_16x16x32_bf16 v[44:47], v[152:155], v[192:195], v[44:47]
	v_mfma_f32_16x16x32_bf16 v[40:43], v[160:163], v[192:195], v[40:43]
	v_mfma_f32_16x16x32_bf16 v[28:31], v[152:155], v[200:203], v[28:31]
	v_mfma_f32_16x16x32_bf16 v[24:27], v[160:163], v[200:203], v[24:27]
	v_mfma_f32_16x16x32_bf16 v[12:15], v[152:155], v[208:211], v[12:15]
	v_mfma_f32_16x16x32_bf16 v[8:11], v[160:163], v[208:211], v[8:11]
	v_mfma_f32_16x16x32_bf16 v[60:63], v[156:159], v[188:191], v[60:63]
	v_mfma_f32_16x16x32_bf16 v[56:59], v[164:167], v[188:191], v[56:59]
	v_mfma_f32_16x16x32_bf16 v[44:47], v[156:159], v[196:199], v[44:47]
	v_mfma_f32_16x16x32_bf16 v[40:43], v[164:167], v[196:199], v[40:43]
	v_mfma_f32_16x16x32_bf16 v[28:31], v[156:159], v[204:207], v[28:31]
	v_mfma_f32_16x16x32_bf16 v[24:27], v[164:167], v[204:207], v[24:27]
	v_mfma_f32_16x16x32_bf16 v[12:15], v[156:159], v[212:215], v[12:15]
	v_mfma_f32_16x16x32_bf16 v[8:11], v[164:167], v[212:215], v[8:11]
	s_setprio 0
	s_setprio 1
	v_mfma_f32_16x16x32_bf16 v[52:55], v[168:171], v[184:187], v[52:55]
	v_mfma_f32_16x16x32_bf16 v[48:51], v[176:179], v[184:187], v[48:51]
	v_mfma_f32_16x16x32_bf16 v[36:39], v[168:171], v[192:195], v[36:39]
	v_mfma_f32_16x16x32_bf16 v[32:35], v[176:179], v[192:195], v[32:35]
	v_mfma_f32_16x16x32_bf16 v[20:23], v[168:171], v[200:203], v[20:23]
	v_mfma_f32_16x16x32_bf16 v[16:19], v[176:179], v[200:203], v[16:19]
	v_mfma_f32_16x16x32_bf16 v[4:7], v[168:171], v[208:211], v[4:7]
	v_mfma_f32_16x16x32_bf16 v[0:3], v[176:179], v[208:211], v[0:3]
	v_mfma_f32_16x16x32_bf16 v[52:55], v[172:175], v[188:191], v[52:55]
	v_mfma_f32_16x16x32_bf16 v[48:51], v[180:183], v[188:191], v[48:51]
	v_mfma_f32_16x16x32_bf16 v[36:39], v[172:175], v[196:199], v[36:39]
	v_mfma_f32_16x16x32_bf16 v[32:35], v[180:183], v[196:199], v[32:35]
	v_mfma_f32_16x16x32_bf16 v[20:23], v[172:175], v[204:207], v[20:23]
	v_mfma_f32_16x16x32_bf16 v[16:19], v[180:183], v[204:207], v[16:19]
	v_mfma_f32_16x16x32_bf16 v[4:7], v[172:175], v[212:215], v[4:7]
	v_mfma_f32_16x16x32_bf16 v[0:3], v[180:183], v[212:215], v[0:3]
	s_setprio 0
	s_barrier
	s_add_i32 s58, s58, 2
	s_add_u32 s22, s22, 0x100
	s_addc_u32 s23, s23, 0
	s_add_u32 s56, s56, 0x100
	s_addc_u32 s57, s57, 0
	s_cmp_gt_u32 s58, 13
	s_cbranch_scc0 .LBB5_9
	s_mov_b64 vcc, s[0:1]
	s_cbranch_vccz .LBB5_12
	s_barrier

.LBB6_19:
	s_ashr_i32 s17, s16, 31
	s_lshl_b64 s[18:19], s[16:17], 21
	s_add_u32 s18, s33, s18
	v_cmp_lt_i64_e64 s[4:5], s[4:5], v[142:143]
	s_addc_u32 s19, s34, s19
	s_and_b64 s[20:21], s[4:5], exec
	s_cselect_b32 s17, s19, s25
	s_cselect_b32 s53, s18, s24
	s_ashr_i32 s15, s14, 31
	s_lshl_b64 s[20:21], s[14:15], 21
	s_add_u32 s20, s6, s20
	s_addc_u32 s21, s7, s21
	s_and_b64 s[28:29], s[4:5], exec
	s_cselect_b32 s15, s21, s27
	s_cselect_b32 s54, s20, s26
	s_add_u32 s24, s24, 0x100080
	s_addc_u32 s25, s25, 0
	s_add_u32 s55, s26, 0x100
	s_addc_u32 s56, s27, 0
	s_mov_b32 s57, -2
	s_add_u32 s26, s24, 0xfff00080
	s_addc_u32 s27, s25, -1
	s_cmp_eq_u32 s57, 60
	s_cselect_b32 s29, s17, s27
	s_cselect_b32 s28, s53, s26
	s_cselect_b32 s27, s15, s56
	s_cselect_b32 s26, s54, s55
	v_lshl_add_u64 v[146:147], s[24:25], 0, v[138:139]
	s_add_i32 m0, s23, 0xc000
	s_nop 0
	global_load_lds_dwordx4 v[146:147], off
	v_lshl_add_u64 v[146:147], s[24:25], 0, v[140:141]
	s_add_i32 m0, s23, 0xe000
	s_nop 0
	global_load_lds_dwordx4 v[146:147], off
	ds_read_b128 v[152:155], v149
	ds_read_b128 v[156:159], v149 offset:1024
	ds_read_b128 v[160:163], v149 offset:2048
	ds_read_b128 v[164:167], v149 offset:3072
	ds_read_b128 v[168:171], v150
	ds_read_b128 v[172:175], v150 offset:1024
	ds_read_b128 v[176:179], v150 offset:2048
	ds_read_b128 v[180:183], v150 offset:3072
	ds_read_b128 v[184:187], v151
	ds_read_b128 v[188:191], v151 offset:1024
	ds_read_b128 v[192:195], v151 offset:2048
	ds_read_b128 v[196:199], v151 offset:3072
	ds_read_b128 v[200:203], v151 offset:4096
	ds_read_b128 v[204:207], v151 offset:5120
	ds_read_b128 v[208:211], v151 offset:6144
	ds_read_b128 v[212:215], v151 offset:7168
	s_waitcnt vmcnt(8)
	s_waitcnt lgkmcnt(0)
	s_barrier
	s_setprio 1
	s_waitcnt lgkmcnt(0)
	v_mfma_f32_16x16x32_bf16 v[124:127], v[152:155], v[184:187], 0
	v_mfma_f32_16x16x32_bf16 v[120:123], v[160:163], v[184:187], 0
	v_mfma_f32_16x16x32_bf16 v[116:119], v[152:155], v[192:195], 0
	v_mfma_f32_16x16x32_bf16 v[108:111], v[160:163], v[192:195], 0
	v_mfma_f32_16x16x32_bf16 v[100:103], v[152:155], v[200:203], 0
	v_mfma_f32_16x16x32_bf16 v[92:95], v[160:163], v[200:203], 0
	v_mfma_f32_16x16x32_bf16 v[84:87], v[152:155], v[208:211], 0
	v_mfma_f32_16x16x32_bf16 v[76:79], v[160:163], v[208:211], 0
	v_mfma_f32_16x16x32_bf16 v[124:127], v[156:159], v[188:191], v[124:127]
	v_mfma_f32_16x16x32_bf16 v[120:123], v[164:167], v[188:191], v[120:123]
	v_mfma_f32_16x16x32_bf16 v[116:119], v[156:159], v[196:199], v[116:119]
	v_mfma_f32_16x16x32_bf16 v[108:111], v[164:167], v[196:199], v[108:111]
	v_mfma_f32_16x16x32_bf16 v[100:103], v[156:159], v[204:207], v[100:103]
	v_mfma_f32_16x16x32_bf16 v[92:95], v[164:167], v[204:207], v[92:95]
	v_mfma_f32_16x16x32_bf16 v[84:87], v[156:159], v[212:215], v[84:87]
	v_mfma_f32_16x16x32_bf16 v[76:79], v[164:167], v[212:215], v[76:79]
	s_setprio 0
	s_setprio 1
	v_mfma_f32_16x16x32_bf16 v[112:115], v[168:171], v[184:187], 0
	v_mfma_f32_16x16x32_bf16 v[104:107], v[176:179], v[184:187], 0
	v_mfma_f32_16x16x32_bf16 v[96:99], v[168:171], v[192:195], 0
	v_mfma_f32_16x16x32_bf16 v[88:91], v[176:179], v[192:195], 0
	v_mfma_f32_16x16x32_bf16 v[80:83], v[168:171], v[200:203], 0
	v_mfma_f32_16x16x32_bf16 v[72:75], v[176:179], v[200:203], 0
	v_mfma_f32_16x16x32_bf16 v[68:71], v[168:171], v[208:211], 0
	v_mfma_f32_16x16x32_bf16 v[64:67], v[176:179], v[208:211], 0
	v_mfma_f32_16x16x32_bf16 v[112:115], v[172:175], v[188:191], v[112:115]
	v_mfma_f32_16x16x32_bf16 v[104:107], v[180:183], v[188:191], v[104:107]
	v_mfma_f32_16x16x32_bf16 v[96:99], v[172:175], v[196:199], v[96:99]
	v_mfma_f32_16x16x32_bf16 v[88:91], v[180:183], v[196:199], v[88:91]
	v_mfma_f32_16x16x32_bf16 v[80:83], v[172:175], v[204:207], v[80:83]
	v_mfma_f32_16x16x32_bf16 v[72:75], v[180:183], v[204:207], v[72:75]
	v_mfma_f32_16x16x32_bf16 v[68:71], v[172:175], v[212:215], v[68:71]
	v_mfma_f32_16x16x32_bf16 v[64:67], v[180:183], v[212:215], v[64:67]
	s_setprio 0
	s_barrier
	s_add_i32 s58, s45, s31
	v_lshl_add_u64 v[146:147], s[26:27], 0, v[130:131]
	s_mov_b32 m0, s58
	s_nop 0
	global_load_lds_dwordx4 v[146:147], off
	s_add_i32 m0, s58, 0x2000
	s_add_u32 s58, s26, 0x100000
	v_lshl_add_u64 v[216:217], s[26:27], 0, v[134:135]
	s_addc_u32 s59, s27, 0
	s_add_i32 s60, s46, s31
	global_load_lds_dwordx4 v[216:217], off
	v_lshl_add_u64 v[218:219], s[58:59], 0, v[130:131]
	s_mov_b32 m0, s60
	v_lshl_add_u64 v[220:221], s[28:29], 0, v[132:133]
	global_load_lds_dwordx4 v[218:219], off
	v_lshl_add_u64 v[218:219], s[58:59], 0, v[134:135]
	s_add_i32 m0, s60, 0x2000
	s_nop 0
	global_load_lds_dwordx4 v[218:219], off
	v_lshl_add_u64 v[218:219], s[28:29], 0, v[128:129]
	s_mov_b32 m0, s23
	s_nop 0
	global_load_lds_dwordx4 v[218:219], off
	s_mov_b32 m0, s35
	s_nop 0
	global_load_lds_dwordx4 v[220:221], off
	ds_read_b128 v[184:187], v151 offset:16384
	ds_read_b128 v[188:191], v151 offset:17408
	ds_read_b128 v[192:195], v151 offset:18432
	ds_read_b128 v[196:199], v151 offset:19456
	ds_read_b128 v[200:203], v151 offset:20480
	ds_read_b128 v[204:207], v151 offset:21504
	ds_read_b128 v[208:211], v151 offset:22528
	ds_read_b128 v[212:215], v151 offset:23552
	s_waitcnt vmcnt(8)
	s_waitcnt lgkmcnt(0)
	s_barrier
	s_setprio 1
	s_waitcnt lgkmcnt(0)
	v_mfma_f32_16x16x32_bf16 v[60:63], v[152:155], v[184:187], 0
	v_mfma_f32_16x16x32_bf16 v[56:59], v[160:163], v[184:187], 0
	v_mfma_f32_16x16x32_bf16 v[52:55], v[152:155], v[192:195], 0
	v_mfma_f32_16x16x32_bf16 v[44:47], v[160:163], v[192:195], 0
	v_mfma_f32_16x16x32_bf16 v[36:39], v[152:155], v[200:203], 0
	v_mfma_f32_16x16x32_bf16 v[28:31], v[160:163], v[200:203], 0
	v_mfma_f32_16x16x32_bf16 v[20:23], v[152:155], v[208:211], 0
	v_mfma_f32_16x16x32_bf16 v[12:15], v[160:163], v[208:211], 0
	v_mfma_f32_16x16x32_bf16 v[60:63], v[156:159], v[188:191], v[60:63]
	v_mfma_f32_16x16x32_bf16 v[56:59], v[164:167], v[188:191], v[56:59]
	v_mfma_f32_16x16x32_bf16 v[52:55], v[156:159], v[196:199], v[52:55]
	v_mfma_f32_16x16x32_bf16 v[44:47], v[164:167], v[196:199], v[44:47]
	v_mfma_f32_16x16x32_bf16 v[36:39], v[156:159], v[204:207], v[36:39]
	v_mfma_f32_16x16x32_bf16 v[28:31], v[164:167], v[204:207], v[28:31]
	v_mfma_f32_16x16x32_bf16 v[20:23], v[156:159], v[212:215], v[20:23]
	v_mfma_f32_16x16x32_bf16 v[12:15], v[164:167], v[212:215], v[12:15]
	s_setprio 0
	s_setprio 1
	v_mfma_f32_16x16x32_bf16 v[48:51], v[168:171], v[184:187], 0
	v_mfma_f32_16x16x32_bf16 v[40:43], v[176:179], v[184:187], 0
	v_mfma_f32_16x16x32_bf16 v[32:35], v[168:171], v[192:195], 0
	v_mfma_f32_16x16x32_bf16 v[24:27], v[176:179], v[192:195], 0
	v_mfma_f32_16x16x32_bf16 v[16:19], v[168:171], v[200:203], 0
	v_mfma_f32_16x16x32_bf16 v[8:11], v[176:179], v[200:203], 0
	v_mfma_f32_16x16x32_bf16 v[4:7], v[168:171], v[208:211], 0
	v_mfma_f32_16x16x32_bf16 v[0:3], v[176:179], v[208:211], 0
	v_mfma_f32_16x16x32_bf16 v[48:51], v[172:175], v[188:191], v[48:51]
	v_mfma_f32_16x16x32_bf16 v[40:43], v[180:183], v[188:191], v[40:43]
	v_mfma_f32_16x16x32_bf16 v[32:35], v[172:175], v[196:199], v[32:35]
	v_mfma_f32_16x16x32_bf16 v[24:27], v[180:183], v[196:199], v[24:27]
	v_mfma_f32_16x16x32_bf16 v[16:19], v[172:175], v[204:207], v[16:19]
	v_mfma_f32_16x16x32_bf16 v[8:11], v[180:183], v[204:207], v[8:11]
	v_mfma_f32_16x16x32_bf16 v[4:7], v[172:175], v[212:215], v[4:7]
	v_mfma_f32_16x16x32_bf16 v[0:3], v[180:183], v[212:215], v[0:3]
	s_setprio 0
	s_barrier
	s_add_i32 s58, 0, 0x18000
	s_add_i32 s59, 0, 0x1c000
	v_add_u32_e32 v164, s58, v148
	v_add_u32_e32 v180, s59, v148
	s_add_u32 s28, s28, 0x100000
	s_addc_u32 s29, s29, 0
	s_mov_b32 m0, s36
	v_lshl_add_u64 v[222:223], s[28:29], 0, v[128:129]
	global_load_lds_dwordx4 v[222:223], off
	v_lshl_add_u64 v[222:223], s[28:29], 0, v[132:133]
	s_mov_b32 m0, s37
	s_nop 0
	global_load_lds_dwordx4 v[222:223], off
	ds_read_b128 v[152:155], v164
	ds_read_b128 v[156:159], v164 offset:1024
	ds_read_b128 v[160:163], v164 offset:2048
	ds_read_b128 v[164:167], v164 offset:3072
	ds_read_b128 v[168:171], v180
	ds_read_b128 v[172:175], v180 offset:1024
	ds_read_b128 v[176:179], v180 offset:2048
	ds_read_b128 v[180:183], v180 offset:3072
	ds_read_b128 v[184:187], v151 offset:32768
	ds_read_b128 v[188:191], v151 offset:33792
	ds_read_b128 v[192:195], v151 offset:34816
	ds_read_b128 v[196:199], v151 offset:35840
	ds_read_b128 v[200:203], v151 offset:36864
	ds_read_b128 v[204:207], v151 offset:37888
	ds_read_b128 v[208:211], v151 offset:38912
	ds_read_b128 v[212:215], v151 offset:39936
	s_waitcnt vmcnt(8)
	s_waitcnt lgkmcnt(0)
	s_barrier
	s_setprio 1
	s_waitcnt lgkmcnt(0)
	v_mfma_f32_16x16x32_bf16 v[124:127], v[152:155], v[184:187], v[124:127]
	v_mfma_f32_16x16x32_bf16 v[120:123], v[160:163], v[184:187], v[120:123]
	v_mfma_f32_16x16x32_bf16 v[116:119], v[152:155], v[192:195], v[116:119]
	v_mfma_f32_16x16x32_bf16 v[108:111], v[160:163], v[192:195], v[108:111]
	v_mfma_f32_16x16x32_bf16 v[100:103], v[152:155], v[200:203], v[100:103]
	v_mfma_f32_16x16x32_bf16 v[92:95], v[160:163], v[200:203], v[92:95]
	v_mfma_f32_16x16x32_bf16 v[84:87], v[152:155], v[208:211], v[84:87]
	v_mfma_f32_16x16x32_bf16 v[76:79], v[160:163], v[208:211], v[76:79]
	v_mfma_f32_16x16x32_bf16 v[124:127], v[156:159], v[188:191], v[124:127]
	v_mfma_f32_16x16x32_bf16 v[120:123], v[164:167], v[188:191], v[120:123]
	v_mfma_f32_16x16x32_bf16 v[116:119], v[156:159], v[196:199], v[116:119]
	v_mfma_f32_16x16x32_bf16 v[108:111], v[164:167], v[196:199], v[108:111]
	v_mfma_f32_16x16x32_bf16 v[100:103], v[156:159], v[204:207], v[100:103]
	v_mfma_f32_16x16x32_bf16 v[92:95], v[164:167], v[204:207], v[92:95]
	v_mfma_f32_16x16x32_bf16 v[84:87], v[156:159], v[212:215], v[84:87]
	v_mfma_f32_16x16x32_bf16 v[76:79], v[164:167], v[212:215], v[76:79]
	s_setprio 0
	s_setprio 1
	v_mfma_f32_16x16x32_bf16 v[112:115], v[168:171], v[184:187], v[112:115]
	v_mfma_f32_16x16x32_bf16 v[104:107], v[176:179], v[184:187], v[104:107]
	v_mfma_f32_16x16x32_bf16 v[96:99], v[168:171], v[192:195], v[96:99]
	v_mfma_f32_16x16x32_bf16 v[88:91], v[176:179], v[192:195], v[88:91]
	v_mfma_f32_16x16x32_bf16 v[80:83], v[168:171], v[200:203], v[80:83]
	v_mfma_f32_16x16x32_bf16 v[72:75], v[176:179], v[200:203], v[72:75]
	v_mfma_f32_16x16x32_bf16 v[68:71], v[168:171], v[208:211], v[68:71]
	v_mfma_f32_16x16x32_bf16 v[64:67], v[176:179], v[208:211], v[64:67]
	v_mfma_f32_16x16x32_bf16 v[112:115], v[172:175], v[188:191], v[112:115]
	v_mfma_f32_16x16x32_bf16 v[104:107], v[180:183], v[188:191], v[104:107]
	v_mfma_f32_16x16x32_bf16 v[96:99], v[172:175], v[196:199], v[96:99]
	v_mfma_f32_16x16x32_bf16 v[88:91], v[180:183], v[196:199], v[88:91]
	v_mfma_f32_16x16x32_bf16 v[80:83], v[172:175], v[204:207], v[80:83]
	v_mfma_f32_16x16x32_bf16 v[72:75], v[180:183], v[204:207], v[72:75]
	v_mfma_f32_16x16x32_bf16 v[68:71], v[172:175], v[212:215], v[68:71]
	v_mfma_f32_16x16x32_bf16 v[64:67], v[180:183], v[212:215], v[64:67]
	s_setprio 0
	s_barrier
	s_add_i32 s28, s58, s31
	v_lshl_add_u64 v[146:147], v[146:147], 0, s[12:13]
	s_mov_b32 m0, s28
	s_nop 0
	global_load_lds_dwordx4 v[146:147], off
	s_add_i32 m0, s28, 0x2000
	s_add_u32 s26, s26, 0x100080
	v_lshl_add_u64 v[146:147], v[216:217], 0, s[12:13]
	s_addc_u32 s27, s27, 0
	s_add_i32 s28, s59, s31
	global_load_lds_dwordx4 v[146:147], off
	v_lshl_add_u64 v[146:147], s[26:27], 0, v[130:131]
	s_mov_b32 m0, s28
	s_nop 0
	global_load_lds_dwordx4 v[146:147], off
	v_lshl_add_u64 v[146:147], s[26:27], 0, v[134:135]
	s_add_i32 m0, s28, 0x2000
	s_nop 0
	global_load_lds_dwordx4 v[146:147], off
	v_lshl_add_u64 v[146:147], v[218:219], 0, s[12:13]
	s_mov_b32 m0, s40
	s_nop 0
	global_load_lds_dwordx4 v[146:147], off
	v_lshl_add_u64 v[146:147], v[220:221], 0, s[12:13]
	s_mov_b32 m0, s41
	s_nop 0
	global_load_lds_dwordx4 v[146:147], off
	ds_read_b128 v[184:187], v151 offset:49152
	ds_read_b128 v[188:191], v151 offset:50176
	ds_read_b128 v[192:195], v151 offset:51200
	ds_read_b128 v[196:199], v151 offset:52224
	ds_read_b128 v[200:203], v151 offset:53248
	ds_read_b128 v[204:207], v151 offset:54272
	ds_read_b128 v[208:211], v151 offset:55296
	ds_read_b128 v[212:215], v151 offset:56320
	s_waitcnt vmcnt(8)
	s_waitcnt lgkmcnt(0)
	s_barrier
	s_setprio 1
	s_waitcnt lgkmcnt(0)
	v_mfma_f32_16x16x32_bf16 v[60:63], v[152:155], v[184:187], v[60:63]
	v_mfma_f32_16x16x32_bf16 v[56:59], v[160:163], v[184:187], v[56:59]
	v_mfma_f32_16x16x32_bf16 v[52:55], v[152:155], v[192:195], v[52:55]
	v_mfma_f32_16x16x32_bf16 v[44:47], v[160:163], v[192:195], v[44:47]
	v_mfma_f32_16x16x32_bf16 v[36:39], v[152:155], v[200:203], v[36:39]
	v_mfma_f32_16x16x32_bf16 v[28:31], v[160:163], v[200:203], v[28:31]
	v_mfma_f32_16x16x32_bf16 v[20:23], v[152:155], v[208:211], v[20:23]
	v_mfma_f32_16x16x32_bf16 v[12:15], v[160:163], v[208:211], v[12:15]
	v_mfma_f32_16x16x32_bf16 v[60:63], v[156:159], v[188:191], v[60:63]
	v_mfma_f32_16x16x32_bf16 v[56:59], v[164:167], v[188:191], v[56:59]
	v_mfma_f32_16x16x32_bf16 v[52:55], v[156:159], v[196:199], v[52:55]
	v_mfma_f32_16x16x32_bf16 v[44:47], v[164:167], v[196:199], v[44:47]
	v_mfma_f32_16x16x32_bf16 v[36:39], v[156:159], v[204:207], v[36:39]
	v_mfma_f32_16x16x32_bf16 v[28:31], v[164:167], v[204:207], v[28:31]
	v_mfma_f32_16x16x32_bf16 v[20:23], v[156:159], v[212:215], v[20:23]
	v_mfma_f32_16x16x32_bf16 v[12:15], v[164:167], v[212:215], v[12:15]
	s_setprio 0
	s_setprio 1
	v_mfma_f32_16x16x32_bf16 v[48:51], v[168:171], v[184:187], v[48:51]
	v_mfma_f32_16x16x32_bf16 v[40:43], v[176:179], v[184:187], v[40:43]
	v_mfma_f32_16x16x32_bf16 v[32:35], v[168:171], v[192:195], v[32:35]
	v_mfma_f32_16x16x32_bf16 v[24:27], v[176:179], v[192:195], v[24:27]
	v_mfma_f32_16x16x32_bf16 v[16:19], v[168:171], v[200:203], v[16:19]
	v_mfma_f32_16x16x32_bf16 v[8:11], v[176:179], v[200:203], v[8:11]
	v_mfma_f32_16x16x32_bf16 v[4:7], v[168:171], v[208:211], v[4:7]
	v_mfma_f32_16x16x32_bf16 v[0:3], v[176:179], v[208:211], v[0:3]
	v_mfma_f32_16x16x32_bf16 v[48:51], v[172:175], v[188:191], v[48:51]
	v_mfma_f32_16x16x32_bf16 v[40:43], v[180:183], v[188:191], v[40:43]
	v_mfma_f32_16x16x32_bf16 v[32:35], v[172:175], v[196:199], v[32:35]
	v_mfma_f32_16x16x32_bf16 v[24:27], v[180:183], v[196:199], v[24:27]
	v_mfma_f32_16x16x32_bf16 v[16:19], v[172:175], v[204:207], v[16:19]
	v_mfma_f32_16x16x32_bf16 v[8:11], v[180:183], v[204:207], v[8:11]
	v_mfma_f32_16x16x32_bf16 v[4:7], v[172:175], v[212:215], v[4:7]
	v_mfma_f32_16x16x32_bf16 v[0:3], v[180:183], v[212:215], v[0:3]
	s_setprio 0
	s_barrier
	s_add_i32 s57, s57, 2
	s_add_u32 s24, s24, 0x100
	s_addc_u32 s25, s25, 0
	s_add_u32 s55, s55, 0x100
	s_addc_u32 s56, s56, 0
	s_cmp_gt_u32 s57, 61
.LBB6_20:
	s_add_u32 s26, s24, 0xfff00080
	s_addc_u32 s27, s25, -1
	s_cmp_eq_u32 s57, 60
	s_cselect_b32 s29, s17, s27
	s_cselect_b32 s28, s53, s26
	s_cselect_b32 s27, s15, s56
	s_cselect_b32 s26, s54, s55
	v_lshl_add_u64 v[146:147], s[24:25], 0, v[138:139]
	s_add_i32 m0, s23, 0xc000
	s_nop 0
	global_load_lds_dwordx4 v[146:147], off
	v_lshl_add_u64 v[146:147], s[24:25], 0, v[140:141]
	s_add_i32 m0, s23, 0xe000
	s_nop 0
	global_load_lds_dwordx4 v[146:147], off
	ds_read_b128 v[152:155], v149
	ds_read_b128 v[156:159], v149 offset:1024
	ds_read_b128 v[160:163], v149 offset:2048
	ds_read_b128 v[164:167], v149 offset:3072
	ds_read_b128 v[168:171], v150
	ds_read_b128 v[172:175], v150 offset:1024
	ds_read_b128 v[176:179], v150 offset:2048
	ds_read_b128 v[180:183], v150 offset:3072
	ds_read_b128 v[184:187], v151
	ds_read_b128 v[188:191], v151 offset:1024
	ds_read_b128 v[192:195], v151 offset:2048
	ds_read_b128 v[196:199], v151 offset:3072
	ds_read_b128 v[200:203], v151 offset:4096
	ds_read_b128 v[204:207], v151 offset:5120
	ds_read_b128 v[208:211], v151 offset:6144
	ds_read_b128 v[212:215], v151 offset:7168
	s_waitcnt vmcnt(8)
	s_waitcnt lgkmcnt(0)
	s_barrier
	s_setprio 1
	s_waitcnt lgkmcnt(0)
	v_mfma_f32_16x16x32_bf16 v[124:127], v[152:155], v[184:187], v[124:127]
	v_mfma_f32_16x16x32_bf16 v[120:123], v[160:163], v[184:187], v[120:123]
	v_mfma_f32_16x16x32_bf16 v[116:119], v[152:155], v[192:195], v[116:119]
	v_mfma_f32_16x16x32_bf16 v[108:111], v[160:163], v[192:195], v[108:111]
	v_mfma_f32_16x16x32_bf16 v[100:103], v[152:155], v[200:203], v[100:103]
	v_mfma_f32_16x16x32_bf16 v[92:95], v[160:163], v[200:203], v[92:95]
	v_mfma_f32_16x16x32_bf16 v[84:87], v[152:155], v[208:211], v[84:87]
	v_mfma_f32_16x16x32_bf16 v[76:79], v[160:163], v[208:211], v[76:79]
	v_mfma_f32_16x16x32_bf16 v[124:127], v[156:159], v[188:191], v[124:127]
	v_mfma_f32_16x16x32_bf16 v[120:123], v[164:167], v[188:191], v[120:123]
	v_mfma_f32_16x16x32_bf16 v[116:119], v[156:159], v[196:199], v[116:119]
	v_mfma_f32_16x16x32_bf16 v[108:111], v[164:167], v[196:199], v[108:111]
	v_mfma_f32_16x16x32_bf16 v[100:103], v[156:159], v[204:207], v[100:103]
	v_mfma_f32_16x16x32_bf16 v[92:95], v[164:167], v[204:207], v[92:95]
	v_mfma_f32_16x16x32_bf16 v[84:87], v[156:159], v[212:215], v[84:87]
	v_mfma_f32_16x16x32_bf16 v[76:79], v[164:167], v[212:215], v[76:79]
	s_setprio 0
	s_setprio 1
	v_mfma_f32_16x16x32_bf16 v[112:115], v[168:171], v[184:187], v[112:115]
	v_mfma_f32_16x16x32_bf16 v[104:107], v[176:179], v[184:187], v[104:107]
	v_mfma_f32_16x16x32_bf16 v[96:99], v[168:171], v[192:195], v[96:99]
	v_mfma_f32_16x16x32_bf16 v[88:91], v[176:179], v[192:195], v[88:91]
	v_mfma_f32_16x16x32_bf16 v[80:83], v[168:171], v[200:203], v[80:83]
	v_mfma_f32_16x16x32_bf16 v[72:75], v[176:179], v[200:203], v[72:75]
	v_mfma_f32_16x16x32_bf16 v[68:71], v[168:171], v[208:211], v[68:71]
	v_mfma_f32_16x16x32_bf16 v[64:67], v[176:179], v[208:211], v[64:67]
	v_mfma_f32_16x16x32_bf16 v[112:115], v[172:175], v[188:191], v[112:115]
	v_mfma_f32_16x16x32_bf16 v[104:107], v[180:183], v[188:191], v[104:107]
	v_mfma_f32_16x16x32_bf16 v[96:99], v[172:175], v[196:199], v[96:99]
	v_mfma_f32_16x16x32_bf16 v[88:91], v[180:183], v[196:199], v[88:91]
	v_mfma_f32_16x16x32_bf16 v[80:83], v[172:175], v[204:207], v[80:83]
	v_mfma_f32_16x16x32_bf16 v[72:75], v[180:183], v[204:207], v[72:75]
	v_mfma_f32_16x16x32_bf16 v[68:71], v[172:175], v[212:215], v[68:71]
	v_mfma_f32_16x16x32_bf16 v[64:67], v[180:183], v[212:215], v[64:67]
	s_setprio 0
	s_barrier
	s_add_i32 s58, s45, s31
	v_lshl_add_u64 v[146:147], s[26:27], 0, v[130:131]
	s_mov_b32 m0, s58
	s_nop 0
	global_load_lds_dwordx4 v[146:147], off
	s_add_i32 m0, s58, 0x2000
	s_add_u32 s58, s26, 0x100000
	v_lshl_add_u64 v[216:217], s[26:27], 0, v[134:135]
	s_addc_u32 s59, s27, 0
	s_add_i32 s60, s46, s31
	global_load_lds_dwordx4 v[216:217], off
	v_lshl_add_u64 v[218:219], s[58:59], 0, v[130:131]
	s_mov_b32 m0, s60
	v_lshl_add_u64 v[220:221], s[28:29], 0, v[132:133]
	global_load_lds_dwordx4 v[218:219], off
	v_lshl_add_u64 v[218:219], s[58:59], 0, v[134:135]
	s_add_i32 m0, s60, 0x2000
	s_nop 0
	global_load_lds_dwordx4 v[218:219], off
	v_lshl_add_u64 v[218:219], s[28:29], 0, v[128:129]
	s_mov_b32 m0, s23
	s_nop 0
	global_load_lds_dwordx4 v[218:219], off
	s_mov_b32 m0, s35
	s_nop 0
	global_load_lds_dwordx4 v[220:221], off
	ds_read_b128 v[184:187], v151 offset:16384
	ds_read_b128 v[188:191], v151 offset:17408
	ds_read_b128 v[192:195], v151 offset:18432
	ds_read_b128 v[196:199], v151 offset:19456
	ds_read_b128 v[200:203], v151 offset:20480
	ds_read_b128 v[204:207], v151 offset:21504
	ds_read_b128 v[208:211], v151 offset:22528
	ds_read_b128 v[212:215], v151 offset:23552
	s_waitcnt vmcnt(8)
	s_waitcnt lgkmcnt(0)
	s_barrier
	s_setprio 1
	s_waitcnt lgkmcnt(0)
	v_mfma_f32_16x16x32_bf16 v[60:63], v[152:155], v[184:187], v[60:63]
	v_mfma_f32_16x16x32_bf16 v[56:59], v[160:163], v[184:187], v[56:59]
	v_mfma_f32_16x16x32_bf16 v[52:55], v[152:155], v[192:195], v[52:55]
	v_mfma_f32_16x16x32_bf16 v[44:47], v[160:163], v[192:195], v[44:47]
	v_mfma_f32_16x16x32_bf16 v[36:39], v[152:155], v[200:203], v[36:39]
	v_mfma_f32_16x16x32_bf16 v[28:31], v[160:163], v[200:203], v[28:31]
	v_mfma_f32_16x16x32_bf16 v[20:23], v[152:155], v[208:211], v[20:23]
	v_mfma_f32_16x16x32_bf16 v[12:15], v[160:163], v[208:211], v[12:15]
	v_mfma_f32_16x16x32_bf16 v[60:63], v[156:159], v[188:191], v[60:63]
	v_mfma_f32_16x16x32_bf16 v[56:59], v[164:167], v[188:191], v[56:59]
	v_mfma_f32_16x16x32_bf16 v[52:55], v[156:159], v[196:199], v[52:55]
	v_mfma_f32_16x16x32_bf16 v[44:47], v[164:167], v[196:199], v[44:47]
	v_mfma_f32_16x16x32_bf16 v[36:39], v[156:159], v[204:207], v[36:39]
	v_mfma_f32_16x16x32_bf16 v[28:31], v[164:167], v[204:207], v[28:31]
	v_mfma_f32_16x16x32_bf16 v[20:23], v[156:159], v[212:215], v[20:23]
	v_mfma_f32_16x16x32_bf16 v[12:15], v[164:167], v[212:215], v[12:15]
	s_setprio 0
	s_setprio 1
	v_mfma_f32_16x16x32_bf16 v[48:51], v[168:171], v[184:187], v[48:51]
	v_mfma_f32_16x16x32_bf16 v[40:43], v[176:179], v[184:187], v[40:43]
	v_mfma_f32_16x16x32_bf16 v[32:35], v[168:171], v[192:195], v[32:35]
	v_mfma_f32_16x16x32_bf16 v[24:27], v[176:179], v[192:195], v[24:27]
	v_mfma_f32_16x16x32_bf16 v[16:19], v[168:171], v[200:203], v[16:19]
	v_mfma_f32_16x16x32_bf16 v[8:11], v[176:179], v[200:203], v[8:11]
	v_mfma_f32_16x16x32_bf16 v[4:7], v[168:171], v[208:211], v[4:7]
	v_mfma_f32_16x16x32_bf16 v[0:3], v[176:179], v[208:211], v[0:3]
	v_mfma_f32_16x16x32_bf16 v[48:51], v[172:175], v[188:191], v[48:51]
	v_mfma_f32_16x16x32_bf16 v[40:43], v[180:183], v[188:191], v[40:43]
	v_mfma_f32_16x16x32_bf16 v[32:35], v[172:175], v[196:199], v[32:35]
	v_mfma_f32_16x16x32_bf16 v[24:27], v[180:183], v[196:199], v[24:27]
	v_mfma_f32_16x16x32_bf16 v[16:19], v[172:175], v[204:207], v[16:19]
	v_mfma_f32_16x16x32_bf16 v[8:11], v[180:183], v[204:207], v[8:11]
	v_mfma_f32_16x16x32_bf16 v[4:7], v[172:175], v[212:215], v[4:7]
	v_mfma_f32_16x16x32_bf16 v[0:3], v[180:183], v[212:215], v[0:3]
	s_setprio 0
	s_barrier
	s_add_i32 s58, 0, 0x18000
	s_add_i32 s59, 0, 0x1c000
	v_add_u32_e32 v164, s58, v148
	v_add_u32_e32 v180, s59, v148
	s_add_u32 s28, s28, 0x100000
	s_addc_u32 s29, s29, 0
	s_mov_b32 m0, s36
	v_lshl_add_u64 v[222:223], s[28:29], 0, v[128:129]
	global_load_lds_dwordx4 v[222:223], off
	v_lshl_add_u64 v[222:223], s[28:29], 0, v[132:133]
	s_mov_b32 m0, s37
	s_nop 0
	global_load_lds_dwordx4 v[222:223], off
	ds_read_b128 v[152:155], v164
	ds_read_b128 v[156:159], v164 offset:1024
	ds_read_b128 v[160:163], v164 offset:2048
	ds_read_b128 v[164:167], v164 offset:3072
	ds_read_b128 v[168:171], v180
	ds_read_b128 v[172:175], v180 offset:1024
	ds_read_b128 v[176:179], v180 offset:2048
	ds_read_b128 v[180:183], v180 offset:3072
	ds_read_b128 v[184:187], v151 offset:32768
	ds_read_b128 v[188:191], v151 offset:33792
	ds_read_b128 v[192:195], v151 offset:34816
	ds_read_b128 v[196:199], v151 offset:35840
	ds_read_b128 v[200:203], v151 offset:36864
	ds_read_b128 v[204:207], v151 offset:37888
	ds_read_b128 v[208:211], v151 offset:38912
	ds_read_b128 v[212:215], v151 offset:39936
	s_waitcnt vmcnt(8)
	s_waitcnt lgkmcnt(0)
	s_barrier
	s_setprio 1
	s_waitcnt lgkmcnt(0)
	v_mfma_f32_16x16x32_bf16 v[124:127], v[152:155], v[184:187], v[124:127]
	v_mfma_f32_16x16x32_bf16 v[120:123], v[160:163], v[184:187], v[120:123]
	v_mfma_f32_16x16x32_bf16 v[116:119], v[152:155], v[192:195], v[116:119]
	v_mfma_f32_16x16x32_bf16 v[108:111], v[160:163], v[192:195], v[108:111]
	v_mfma_f32_16x16x32_bf16 v[100:103], v[152:155], v[200:203], v[100:103]
	v_mfma_f32_16x16x32_bf16 v[92:95], v[160:163], v[200:203], v[92:95]
	v_mfma_f32_16x16x32_bf16 v[84:87], v[152:155], v[208:211], v[84:87]
	v_mfma_f32_16x16x32_bf16 v[76:79], v[160:163], v[208:211], v[76:79]
	v_mfma_f32_16x16x32_bf16 v[124:127], v[156:159], v[188:191], v[124:127]
	v_mfma_f32_16x16x32_bf16 v[120:123], v[164:167], v[188:191], v[120:123]
	v_mfma_f32_16x16x32_bf16 v[116:119], v[156:159], v[196:199], v[116:119]
	v_mfma_f32_16x16x32_bf16 v[108:111], v[164:167], v[196:199], v[108:111]
	v_mfma_f32_16x16x32_bf16 v[100:103], v[156:159], v[204:207], v[100:103]
	v_mfma_f32_16x16x32_bf16 v[92:95], v[164:167], v[204:207], v[92:95]
	v_mfma_f32_16x16x32_bf16 v[84:87], v[156:159], v[212:215], v[84:87]
	v_mfma_f32_16x16x32_bf16 v[76:79], v[164:167], v[212:215], v[76:79]
	s_setprio 0
	s_setprio 1
	v_mfma_f32_16x16x32_bf16 v[112:115], v[168:171], v[184:187], v[112:115]
	v_mfma_f32_16x16x32_bf16 v[104:107], v[176:179], v[184:187], v[104:107]
	v_mfma_f32_16x16x32_bf16 v[96:99], v[168:171], v[192:195], v[96:99]
	v_mfma_f32_16x16x32_bf16 v[88:91], v[176:179], v[192:195], v[88:91]
	v_mfma_f32_16x16x32_bf16 v[80:83], v[168:171], v[200:203], v[80:83]
	v_mfma_f32_16x16x32_bf16 v[72:75], v[176:179], v[200:203], v[72:75]
	v_mfma_f32_16x16x32_bf16 v[68:71], v[168:171], v[208:211], v[68:71]
	v_mfma_f32_16x16x32_bf16 v[64:67], v[176:179], v[208:211], v[64:67]
	v_mfma_f32_16x16x32_bf16 v[112:115], v[172:175], v[188:191], v[112:115]
	v_mfma_f32_16x16x32_bf16 v[104:107], v[180:183], v[188:191], v[104:107]
	v_mfma_f32_16x16x32_bf16 v[96:99], v[172:175], v[196:199], v[96:99]
	v_mfma_f32_16x16x32_bf16 v[88:91], v[180:183], v[196:199], v[88:91]
	v_mfma_f32_16x16x32_bf16 v[80:83], v[172:175], v[204:207], v[80:83]
	v_mfma_f32_16x16x32_bf16 v[72:75], v[180:183], v[204:207], v[72:75]
	v_mfma_f32_16x16x32_bf16 v[68:71], v[172:175], v[212:215], v[68:71]
	v_mfma_f32_16x16x32_bf16 v[64:67], v[180:183], v[212:215], v[64:67]
	s_setprio 0
	s_barrier
	s_add_i32 s28, s58, s31
	v_lshl_add_u64 v[146:147], v[146:147], 0, s[12:13]
	s_mov_b32 m0, s28
	s_nop 0
	global_load_lds_dwordx4 v[146:147], off
	s_add_i32 m0, s28, 0x2000
	s_add_u32 s26, s26, 0x100080
	v_lshl_add_u64 v[146:147], v[216:217], 0, s[12:13]
	s_addc_u32 s27, s27, 0
	s_add_i32 s28, s59, s31
	global_load_lds_dwordx4 v[146:147], off
	v_lshl_add_u64 v[146:147], s[26:27], 0, v[130:131]
	s_mov_b32 m0, s28
	s_nop 0
	global_load_lds_dwordx4 v[146:147], off
	v_lshl_add_u64 v[146:147], s[26:27], 0, v[134:135]
	s_add_i32 m0, s28, 0x2000
	s_nop 0
	global_load_lds_dwordx4 v[146:147], off
	v_lshl_add_u64 v[146:147], v[218:219], 0, s[12:13]
	s_mov_b32 m0, s40
	s_nop 0
	global_load_lds_dwordx4 v[146:147], off
	v_lshl_add_u64 v[146:147], v[220:221], 0, s[12:13]
	s_mov_b32 m0, s41
	s_nop 0
	global_load_lds_dwordx4 v[146:147], off
	ds_read_b128 v[184:187], v151 offset:49152
	ds_read_b128 v[188:191], v151 offset:50176
	ds_read_b128 v[192:195], v151 offset:51200
	ds_read_b128 v[196:199], v151 offset:52224
	ds_read_b128 v[200:203], v151 offset:53248
	ds_read_b128 v[204:207], v151 offset:54272
	ds_read_b128 v[208:211], v151 offset:55296
	ds_read_b128 v[212:215], v151 offset:56320
	s_waitcnt vmcnt(8)
	s_waitcnt lgkmcnt(0)
	s_barrier
	s_setprio 1
	s_waitcnt lgkmcnt(0)
	v_mfma_f32_16x16x32_bf16 v[60:63], v[152:155], v[184:187], v[60:63]
	v_mfma_f32_16x16x32_bf16 v[56:59], v[160:163], v[184:187], v[56:59]
	v_mfma_f32_16x16x32_bf16 v[52:55], v[152:155], v[192:195], v[52:55]
	v_mfma_f32_16x16x32_bf16 v[44:47], v[160:163], v[192:195], v[44:47]
	v_mfma_f32_16x16x32_bf16 v[36:39], v[152:155], v[200:203], v[36:39]
	v_mfma_f32_16x16x32_bf16 v[28:31], v[160:163], v[200:203], v[28:31]
	v_mfma_f32_16x16x32_bf16 v[20:23], v[152:155], v[208:211], v[20:23]
	v_mfma_f32_16x16x32_bf16 v[12:15], v[160:163], v[208:211], v[12:15]
	v_mfma_f32_16x16x32_bf16 v[60:63], v[156:159], v[188:191], v[60:63]
	v_mfma_f32_16x16x32_bf16 v[56:59], v[164:167], v[188:191], v[56:59]
	v_mfma_f32_16x16x32_bf16 v[52:55], v[156:159], v[196:199], v[52:55]
	v_mfma_f32_16x16x32_bf16 v[44:47], v[164:167], v[196:199], v[44:47]
	v_mfma_f32_16x16x32_bf16 v[36:39], v[156:159], v[204:207], v[36:39]
	v_mfma_f32_16x16x32_bf16 v[28:31], v[164:167], v[204:207], v[28:31]
	v_mfma_f32_16x16x32_bf16 v[20:23], v[156:159], v[212:215], v[20:23]
	v_mfma_f32_16x16x32_bf16 v[12:15], v[164:167], v[212:215], v[12:15]
	s_setprio 0
	s_setprio 1
	v_mfma_f32_16x16x32_bf16 v[48:51], v[168:171], v[184:187], v[48:51]
	v_mfma_f32_16x16x32_bf16 v[40:43], v[176:179], v[184:187], v[40:43]
	v_mfma_f32_16x16x32_bf16 v[32:35], v[168:171], v[192:195], v[32:35]
	v_mfma_f32_16x16x32_bf16 v[24:27], v[176:179], v[192:195], v[24:27]
	v_mfma_f32_16x16x32_bf16 v[16:19], v[168:171], v[200:203], v[16:19]
	v_mfma_f32_16x16x32_bf16 v[8:11], v[176:179], v[200:203], v[8:11]
	v_mfma_f32_16x16x32_bf16 v[4:7], v[168:171], v[208:211], v[4:7]
	v_mfma_f32_16x16x32_bf16 v[0:3], v[176:179], v[208:211], v[0:3]
	v_mfma_f32_16x16x32_bf16 v[48:51], v[172:175], v[188:191], v[48:51]
	v_mfma_f32_16x16x32_bf16 v[40:43], v[180:183], v[188:191], v[40:43]
	v_mfma_f32_16x16x32_bf16 v[32:35], v[172:175], v[196:199], v[32:35]
	v_mfma_f32_16x16x32_bf16 v[24:27], v[180:183], v[196:199], v[24:27]
	v_mfma_f32_16x16x32_bf16 v[16:19], v[172:175], v[204:207], v[16:19]
	v_mfma_f32_16x16x32_bf16 v[8:11], v[180:183], v[204:207], v[8:11]
	v_mfma_f32_16x16x32_bf16 v[4:7], v[172:175], v[212:215], v[4:7]
	v_mfma_f32_16x16x32_bf16 v[0:3], v[180:183], v[212:215], v[0:3]
	s_setprio 0
	s_barrier
	s_add_i32 s57, s57, 2
	s_add_u32 s24, s24, 0x100
	s_addc_u32 s25, s25, 0
	s_add_u32 s55, s55, 0x100
	s_addc_u32 s56, s56, 0
	s_cmp_gt_u32 s57, 61
	s_cbranch_scc0 .LBB6_20
	s_mov_b64 vcc, s[0:1]
	s_cbranch_vccz .LBB6_23
	s_barrier

.LBB8_11:
	s_ashr_i32 s19, s18, 31
	v_cmp_lt_i64_e32 vcc, s[0:1], v[144:145]
	s_lshl_b64 s[0:1], s[18:19], 19
	s_add_u32 s20, s33, s0
	s_addc_u32 s21, s36, s1
	s_and_b64 s[0:1], vcc, exec
	s_cselect_b32 s5, s21, s29
	s_cselect_b32 s19, s20, s28
	s_ashr_i32 s11, s10, 31
	s_lshl_b64 s[0:1], s[10:11], 19
	s_add_u32 s22, s37, s0
	s_addc_u32 s23, s38, s1
	s_and_b64 s[0:1], vcc, exec
	s_cselect_b32 s11, s23, s27
	s_cselect_b32 s25, s22, s26
	s_add_u32 s34, s26, 0x100
	s_addc_u32 s35, s27, 0
	s_add_u32 s26, s28, 0x40080
	s_addc_u32 s27, s29, 0
	s_mov_b32 s65, -2
	s_add_u32 s28, s26, 0xfffc0080
	s_addc_u32 s29, s27, -1
	s_cmp_eq_u32 s65, 12
	s_cselect_b32 s31, s5, s29
	s_cselect_b32 s30, s19, s28
	s_cselect_b32 s29, s11, s35
	s_cselect_b32 s28, s25, s34
	v_lshl_add_u64 v[216:217], s[26:27], 0, v[142:143]
	s_add_i32 m0, s40, 0xc000
	s_nop 0
	global_load_lds_dwordx4 v[216:217], off
	v_lshl_add_u64 v[216:217], s[26:27], 0, v[140:141]
	s_add_i32 m0, s40, 0xe000
	s_nop 0
	global_load_lds_dwordx4 v[216:217], off
	ds_read_b128 v[148:151], v153
	ds_read_b128 v[156:159], v153 offset:1024
	ds_read_b128 v[160:163], v153 offset:2048
	ds_read_b128 v[164:167], v153 offset:3072
	ds_read_b128 v[168:171], v154
	ds_read_b128 v[172:175], v154 offset:1024
	ds_read_b128 v[176:179], v154 offset:2048
	ds_read_b128 v[180:183], v154 offset:3072
	ds_read_b128 v[184:187], v155
	ds_read_b128 v[188:191], v155 offset:1024
	ds_read_b128 v[192:195], v155 offset:2048
	ds_read_b128 v[196:199], v155 offset:3072
	ds_read_b128 v[200:203], v155 offset:4096
	ds_read_b128 v[204:207], v155 offset:5120
	ds_read_b128 v[208:211], v155 offset:6144
	ds_read_b128 v[212:215], v155 offset:7168
	s_waitcnt vmcnt(8)
	s_waitcnt lgkmcnt(0)
	s_barrier
	s_setprio 1
	s_waitcnt lgkmcnt(0)
	v_mfma_f32_16x16x32_bf16 v[124:127], v[148:151], v[184:187], 0
	v_mfma_f32_16x16x32_bf16 v[120:123], v[160:163], v[184:187], 0
	v_mfma_f32_16x16x32_bf16 v[108:111], v[148:151], v[192:195], 0
	v_mfma_f32_16x16x32_bf16 v[104:107], v[160:163], v[192:195], 0
	v_mfma_f32_16x16x32_bf16 v[92:95], v[148:151], v[200:203], 0
	v_mfma_f32_16x16x32_bf16 v[88:91], v[160:163], v[200:203], 0
	v_mfma_f32_16x16x32_bf16 v[76:79], v[148:151], v[208:211], 0
	v_mfma_f32_16x16x32_bf16 v[72:75], v[160:163], v[208:211], 0
	v_mfma_f32_16x16x32_bf16 v[124:127], v[156:159], v[188:191], v[124:127]
	v_mfma_f32_16x16x32_bf16 v[120:123], v[164:167], v[188:191], v[120:123]
	v_mfma_f32_16x16x32_bf16 v[108:111], v[156:159], v[196:199], v[108:111]
	v_mfma_f32_16x16x32_bf16 v[104:107], v[164:167], v[196:199], v[104:107]
	v_mfma_f32_16x16x32_bf16 v[92:95], v[156:159], v[204:207], v[92:95]
	v_mfma_f32_16x16x32_bf16 v[88:91], v[164:167], v[204:207], v[88:91]
	v_mfma_f32_16x16x32_bf16 v[76:79], v[156:159], v[212:215], v[76:79]
	v_mfma_f32_16x16x32_bf16 v[72:75], v[164:167], v[212:215], v[72:75]
	s_setprio 0
	s_setprio 1
	v_mfma_f32_16x16x32_bf16 v[116:119], v[168:171], v[184:187], 0
	v_mfma_f32_16x16x32_bf16 v[112:115], v[176:179], v[184:187], 0
	v_mfma_f32_16x16x32_bf16 v[100:103], v[168:171], v[192:195], 0
	v_mfma_f32_16x16x32_bf16 v[96:99], v[176:179], v[192:195], 0
	v_mfma_f32_16x16x32_bf16 v[84:87], v[168:171], v[200:203], 0
	v_mfma_f32_16x16x32_bf16 v[80:83], v[176:179], v[200:203], 0
	v_mfma_f32_16x16x32_bf16 v[68:71], v[168:171], v[208:211], 0
	v_mfma_f32_16x16x32_bf16 v[64:67], v[176:179], v[208:211], 0
	v_mfma_f32_16x16x32_bf16 v[116:119], v[172:175], v[188:191], v[116:119]
	v_mfma_f32_16x16x32_bf16 v[112:115], v[180:183], v[188:191], v[112:115]
	v_mfma_f32_16x16x32_bf16 v[100:103], v[172:175], v[196:199], v[100:103]
	v_mfma_f32_16x16x32_bf16 v[96:99], v[180:183], v[196:199], v[96:99]
	v_mfma_f32_16x16x32_bf16 v[84:87], v[172:175], v[204:207], v[84:87]
	v_mfma_f32_16x16x32_bf16 v[80:83], v[180:183], v[204:207], v[80:83]
	v_mfma_f32_16x16x32_bf16 v[68:71], v[172:175], v[212:215], v[68:71]
	v_mfma_f32_16x16x32_bf16 v[64:67], v[180:183], v[212:215], v[64:67]
	s_setprio 0
	s_barrier
	s_add_i32 s66, s52, s39
	v_lshl_add_u64 v[216:217], s[28:29], 0, v[130:131]
	s_mov_b32 m0, s66
	s_nop 0
	global_load_lds_dwordx4 v[216:217], off
	s_add_i32 m0, s66, 0x2000
	s_add_u32 s66, s28, 0x40000
	v_lshl_add_u64 v[218:219], s[28:29], 0, v[134:135]
	s_addc_u32 s67, s29, 0
	s_add_i32 s68, s53, s39
	global_load_lds_dwordx4 v[218:219], off
	v_lshl_add_u64 v[220:221], s[66:67], 0, v[130:131]
	s_mov_b32 m0, s68
	v_lshl_add_u64 v[222:223], s[30:31], 0, v[132:133]
	global_load_lds_dwordx4 v[220:221], off
	v_lshl_add_u64 v[220:221], s[66:67], 0, v[134:135]
	s_add_i32 m0, s68, 0x2000
	s_nop 0
	global_load_lds_dwordx4 v[220:221], off
	v_lshl_add_u64 v[220:221], s[30:31], 0, v[128:129]
	s_mov_b32 m0, s40
	s_nop 0
	global_load_lds_dwordx4 v[220:221], off
	s_mov_b32 m0, s41
	s_nop 0
	global_load_lds_dwordx4 v[222:223], off
	ds_read_b128 v[184:187], v155 offset:16384
	ds_read_b128 v[188:191], v155 offset:17408
	ds_read_b128 v[192:195], v155 offset:18432
	ds_read_b128 v[196:199], v155 offset:19456
	ds_read_b128 v[200:203], v155 offset:20480
	ds_read_b128 v[204:207], v155 offset:21504
	ds_read_b128 v[208:211], v155 offset:22528
	ds_read_b128 v[212:215], v155 offset:23552
	s_waitcnt vmcnt(8)
	s_waitcnt lgkmcnt(0)
	s_barrier
	s_setprio 1
	s_waitcnt lgkmcnt(0)
	v_mfma_f32_16x16x32_bf16 v[60:63], v[148:151], v[184:187], 0
	v_mfma_f32_16x16x32_bf16 v[56:59], v[160:163], v[184:187], 0
	v_mfma_f32_16x16x32_bf16 v[44:47], v[148:151], v[192:195], 0
	v_mfma_f32_16x16x32_bf16 v[40:43], v[160:163], v[192:195], 0
	v_mfma_f32_16x16x32_bf16 v[28:31], v[148:151], v[200:203], 0
	v_mfma_f32_16x16x32_bf16 v[24:27], v[160:163], v[200:203], 0
	v_mfma_f32_16x16x32_bf16 v[12:15], v[148:151], v[208:211], 0
	v_mfma_f32_16x16x32_bf16 v[8:11], v[160:163], v[208:211], 0
	v_mfma_f32_16x16x32_bf16 v[60:63], v[156:159], v[188:191], v[60:63]
	v_mfma_f32_16x16x32_bf16 v[56:59], v[164:167], v[188:191], v[56:59]
	v_mfma_f32_16x16x32_bf16 v[44:47], v[156:159], v[196:199], v[44:47]
	v_mfma_f32_16x16x32_bf16 v[40:43], v[164:167], v[196:199], v[40:43]
	v_mfma_f32_16x16x32_bf16 v[28:31], v[156:159], v[204:207], v[28:31]
	v_mfma_f32_16x16x32_bf16 v[24:27], v[164:167], v[204:207], v[24:27]
	v_mfma_f32_16x16x32_bf16 v[12:15], v[156:159], v[212:215], v[12:15]
	v_mfma_f32_16x16x32_bf16 v[8:11], v[164:167], v[212:215], v[8:11]
	s_setprio 0
	s_setprio 1
	v_mfma_f32_16x16x32_bf16 v[52:55], v[168:171], v[184:187], 0
	v_mfma_f32_16x16x32_bf16 v[48:51], v[176:179], v[184:187], 0
	v_mfma_f32_16x16x32_bf16 v[36:39], v[168:171], v[192:195], 0
	v_mfma_f32_16x16x32_bf16 v[32:35], v[176:179], v[192:195], 0
	v_mfma_f32_16x16x32_bf16 v[20:23], v[168:171], v[200:203], 0
	v_mfma_f32_16x16x32_bf16 v[16:19], v[176:179], v[200:203], 0
	v_mfma_f32_16x16x32_bf16 v[4:7], v[168:171], v[208:211], 0
	v_mfma_f32_16x16x32_bf16 v[0:3], v[176:179], v[208:211], 0
	v_mfma_f32_16x16x32_bf16 v[52:55], v[172:175], v[188:191], v[52:55]
	v_mfma_f32_16x16x32_bf16 v[48:51], v[180:183], v[188:191], v[48:51]
	v_mfma_f32_16x16x32_bf16 v[36:39], v[172:175], v[196:199], v[36:39]
	v_mfma_f32_16x16x32_bf16 v[32:35], v[180:183], v[196:199], v[32:35]
	v_mfma_f32_16x16x32_bf16 v[20:23], v[172:175], v[204:207], v[20:23]
	v_mfma_f32_16x16x32_bf16 v[16:19], v[180:183], v[204:207], v[16:19]
	v_mfma_f32_16x16x32_bf16 v[4:7], v[172:175], v[212:215], v[4:7]
	v_mfma_f32_16x16x32_bf16 v[0:3], v[180:183], v[212:215], v[0:3]
	s_setprio 0
	s_barrier
	s_add_i32 s66, 0, 0x18000
	s_add_i32 s67, 0, 0x1c000
	v_add_u32_e32 v164, s66, v152
	v_add_u32_e32 v180, s67, v152
	s_add_u32 s30, s30, 0x40000
	s_addc_u32 s31, s31, 0
	s_mov_b32 m0, s42
	v_lshl_add_u64 v[224:225], s[30:31], 0, v[128:129]
	global_load_lds_dwordx4 v[224:225], off
	v_lshl_add_u64 v[224:225], s[30:31], 0, v[132:133]
	s_mov_b32 m0, s43
	s_nop 0
	global_load_lds_dwordx4 v[224:225], off
	ds_read_b128 v[148:151], v164
	ds_read_b128 v[156:159], v164 offset:1024
	ds_read_b128 v[160:163], v164 offset:2048
	ds_read_b128 v[164:167], v164 offset:3072
	ds_read_b128 v[168:171], v180
	ds_read_b128 v[172:175], v180 offset:1024
	ds_read_b128 v[176:179], v180 offset:2048
	ds_read_b128 v[180:183], v180 offset:3072
	ds_read_b128 v[184:187], v155 offset:32768
	ds_read_b128 v[188:191], v155 offset:33792
	ds_read_b128 v[192:195], v155 offset:34816
	ds_read_b128 v[196:199], v155 offset:35840
	ds_read_b128 v[200:203], v155 offset:36864
	ds_read_b128 v[204:207], v155 offset:37888
	ds_read_b128 v[208:211], v155 offset:38912
	ds_read_b128 v[212:215], v155 offset:39936
	s_waitcnt vmcnt(8)
	s_waitcnt lgkmcnt(0)
	s_barrier
	s_setprio 1
	s_waitcnt lgkmcnt(0)
	v_mfma_f32_16x16x32_bf16 v[124:127], v[148:151], v[184:187], v[124:127]
	v_mfma_f32_16x16x32_bf16 v[120:123], v[160:163], v[184:187], v[120:123]
	v_mfma_f32_16x16x32_bf16 v[108:111], v[148:151], v[192:195], v[108:111]
	v_mfma_f32_16x16x32_bf16 v[104:107], v[160:163], v[192:195], v[104:107]
	v_mfma_f32_16x16x32_bf16 v[92:95], v[148:151], v[200:203], v[92:95]
	v_mfma_f32_16x16x32_bf16 v[88:91], v[160:163], v[200:203], v[88:91]
	v_mfma_f32_16x16x32_bf16 v[76:79], v[148:151], v[208:211], v[76:79]
	v_mfma_f32_16x16x32_bf16 v[72:75], v[160:163], v[208:211], v[72:75]
	v_mfma_f32_16x16x32_bf16 v[124:127], v[156:159], v[188:191], v[124:127]
	v_mfma_f32_16x16x32_bf16 v[120:123], v[164:167], v[188:191], v[120:123]
	v_mfma_f32_16x16x32_bf16 v[108:111], v[156:159], v[196:199], v[108:111]
	v_mfma_f32_16x16x32_bf16 v[104:107], v[164:167], v[196:199], v[104:107]
	v_mfma_f32_16x16x32_bf16 v[92:95], v[156:159], v[204:207], v[92:95]
	v_mfma_f32_16x16x32_bf16 v[88:91], v[164:167], v[204:207], v[88:91]
	v_mfma_f32_16x16x32_bf16 v[76:79], v[156:159], v[212:215], v[76:79]
	v_mfma_f32_16x16x32_bf16 v[72:75], v[164:167], v[212:215], v[72:75]
	s_setprio 0
	s_setprio 1
	v_mfma_f32_16x16x32_bf16 v[116:119], v[168:171], v[184:187], v[116:119]
	v_mfma_f32_16x16x32_bf16 v[112:115], v[176:179], v[184:187], v[112:115]
	v_mfma_f32_16x16x32_bf16 v[100:103], v[168:171], v[192:195], v[100:103]
	v_mfma_f32_16x16x32_bf16 v[96:99], v[176:179], v[192:195], v[96:99]
	v_mfma_f32_16x16x32_bf16 v[84:87], v[168:171], v[200:203], v[84:87]
	v_mfma_f32_16x16x32_bf16 v[80:83], v[176:179], v[200:203], v[80:83]
	v_mfma_f32_16x16x32_bf16 v[68:71], v[168:171], v[208:211], v[68:71]
	v_mfma_f32_16x16x32_bf16 v[64:67], v[176:179], v[208:211], v[64:67]
	v_mfma_f32_16x16x32_bf16 v[116:119], v[172:175], v[188:191], v[116:119]
	v_mfma_f32_16x16x32_bf16 v[112:115], v[180:183], v[188:191], v[112:115]
	v_mfma_f32_16x16x32_bf16 v[100:103], v[172:175], v[196:199], v[100:103]
	v_mfma_f32_16x16x32_bf16 v[96:99], v[180:183], v[196:199], v[96:99]
	v_mfma_f32_16x16x32_bf16 v[84:87], v[172:175], v[204:207], v[84:87]
	v_mfma_f32_16x16x32_bf16 v[80:83], v[180:183], v[204:207], v[80:83]
	v_mfma_f32_16x16x32_bf16 v[68:71], v[172:175], v[212:215], v[68:71]
	v_mfma_f32_16x16x32_bf16 v[64:67], v[180:183], v[212:215], v[64:67]
	s_setprio 0
	s_barrier
	s_add_i32 s30, s66, s39
	v_lshl_add_u64 v[216:217], v[216:217], 0, s[14:15]
	s_mov_b32 m0, s30
	s_nop 0
	global_load_lds_dwordx4 v[216:217], off
	s_add_i32 m0, s30, 0x2000
	s_add_u32 s28, s28, 0x40080
	v_lshl_add_u64 v[216:217], v[218:219], 0, s[14:15]
	s_addc_u32 s29, s29, 0
	s_add_i32 s30, s67, s39
	global_load_lds_dwordx4 v[216:217], off
	v_lshl_add_u64 v[216:217], s[28:29], 0, v[130:131]
	s_mov_b32 m0, s30
	s_nop 0
	global_load_lds_dwordx4 v[216:217], off
	v_lshl_add_u64 v[216:217], s[28:29], 0, v[134:135]
	s_add_i32 m0, s30, 0x2000
	s_nop 0
	global_load_lds_dwordx4 v[216:217], off
	v_lshl_add_u64 v[216:217], v[220:221], 0, s[14:15]
	s_mov_b32 m0, s45
	s_nop 0
	global_load_lds_dwordx4 v[216:217], off
	v_lshl_add_u64 v[216:217], v[222:223], 0, s[14:15]
	s_mov_b32 m0, s46
	s_nop 0
	global_load_lds_dwordx4 v[216:217], off
	ds_read_b128 v[184:187], v155 offset:49152
	ds_read_b128 v[188:191], v155 offset:50176
	ds_read_b128 v[192:195], v155 offset:51200
	ds_read_b128 v[196:199], v155 offset:52224
	ds_read_b128 v[200:203], v155 offset:53248
	ds_read_b128 v[204:207], v155 offset:54272
	ds_read_b128 v[208:211], v155 offset:55296
	ds_read_b128 v[212:215], v155 offset:56320
	s_waitcnt vmcnt(8)
	s_waitcnt lgkmcnt(0)
	s_barrier
	s_setprio 1
	s_waitcnt lgkmcnt(0)
	v_mfma_f32_16x16x32_bf16 v[60:63], v[148:151], v[184:187], v[60:63]
	v_mfma_f32_16x16x32_bf16 v[56:59], v[160:163], v[184:187], v[56:59]
	v_mfma_f32_16x16x32_bf16 v[44:47], v[148:151], v[192:195], v[44:47]
	v_mfma_f32_16x16x32_bf16 v[40:43], v[160:163], v[192:195], v[40:43]
	v_mfma_f32_16x16x32_bf16 v[28:31], v[148:151], v[200:203], v[28:31]
	v_mfma_f32_16x16x32_bf16 v[24:27], v[160:163], v[200:203], v[24:27]
	v_mfma_f32_16x16x32_bf16 v[12:15], v[148:151], v[208:211], v[12:15]
	v_mfma_f32_16x16x32_bf16 v[8:11], v[160:163], v[208:211], v[8:11]
	v_mfma_f32_16x16x32_bf16 v[60:63], v[156:159], v[188:191], v[60:63]
	v_mfma_f32_16x16x32_bf16 v[56:59], v[164:167], v[188:191], v[56:59]
	v_mfma_f32_16x16x32_bf16 v[44:47], v[156:159], v[196:199], v[44:47]
	v_mfma_f32_16x16x32_bf16 v[40:43], v[164:167], v[196:199], v[40:43]
	v_mfma_f32_16x16x32_bf16 v[28:31], v[156:159], v[204:207], v[28:31]
	v_mfma_f32_16x16x32_bf16 v[24:27], v[164:167], v[204:207], v[24:27]
	v_mfma_f32_16x16x32_bf16 v[12:15], v[156:159], v[212:215], v[12:15]
	v_mfma_f32_16x16x32_bf16 v[8:11], v[164:167], v[212:215], v[8:11]
	s_setprio 0
	s_setprio 1
	v_mfma_f32_16x16x32_bf16 v[52:55], v[168:171], v[184:187], v[52:55]
	v_mfma_f32_16x16x32_bf16 v[48:51], v[176:179], v[184:187], v[48:51]
	v_mfma_f32_16x16x32_bf16 v[36:39], v[168:171], v[192:195], v[36:39]
	v_mfma_f32_16x16x32_bf16 v[32:35], v[176:179], v[192:195], v[32:35]
	v_mfma_f32_16x16x32_bf16 v[20:23], v[168:171], v[200:203], v[20:23]
	v_mfma_f32_16x16x32_bf16 v[16:19], v[176:179], v[200:203], v[16:19]
	v_mfma_f32_16x16x32_bf16 v[4:7], v[168:171], v[208:211], v[4:7]
	v_mfma_f32_16x16x32_bf16 v[0:3], v[176:179], v[208:211], v[0:3]
	v_mfma_f32_16x16x32_bf16 v[52:55], v[172:175], v[188:191], v[52:55]
	v_mfma_f32_16x16x32_bf16 v[48:51], v[180:183], v[188:191], v[48:51]
	v_mfma_f32_16x16x32_bf16 v[36:39], v[172:175], v[196:199], v[36:39]
	v_mfma_f32_16x16x32_bf16 v[32:35], v[180:183], v[196:199], v[32:35]
	v_mfma_f32_16x16x32_bf16 v[20:23], v[172:175], v[204:207], v[20:23]
	v_mfma_f32_16x16x32_bf16 v[16:19], v[180:183], v[204:207], v[16:19]
	v_mfma_f32_16x16x32_bf16 v[4:7], v[172:175], v[212:215], v[4:7]
	v_mfma_f32_16x16x32_bf16 v[0:3], v[180:183], v[212:215], v[0:3]
	s_setprio 0
	s_barrier
	s_add_i32 s65, s65, 2
	s_add_u32 s34, s34, 0x100
	s_addc_u32 s35, s35, 0
	s_add_u32 s26, s26, 0x100
	s_addc_u32 s27, s27, 0
	s_cmp_lt_u32 s65, 14
.LBB8_12:
	s_add_u32 s28, s26, 0xfffc0080
	s_addc_u32 s29, s27, -1
	s_cmp_eq_u32 s65, 12
	s_cselect_b32 s31, s5, s29
	s_cselect_b32 s30, s19, s28
	s_cselect_b32 s29, s11, s35
	s_cselect_b32 s28, s25, s34
	v_lshl_add_u64 v[216:217], s[26:27], 0, v[142:143]
	s_add_i32 m0, s40, 0xc000
	s_nop 0
	global_load_lds_dwordx4 v[216:217], off
	v_lshl_add_u64 v[216:217], s[26:27], 0, v[140:141]
	s_add_i32 m0, s40, 0xe000
	s_nop 0
	global_load_lds_dwordx4 v[216:217], off
	ds_read_b128 v[148:151], v153
	ds_read_b128 v[156:159], v153 offset:1024
	ds_read_b128 v[160:163], v153 offset:2048
	ds_read_b128 v[164:167], v153 offset:3072
	ds_read_b128 v[168:171], v154
	ds_read_b128 v[172:175], v154 offset:1024
	ds_read_b128 v[176:179], v154 offset:2048
	ds_read_b128 v[180:183], v154 offset:3072
	ds_read_b128 v[184:187], v155
	ds_read_b128 v[188:191], v155 offset:1024
	ds_read_b128 v[192:195], v155 offset:2048
	ds_read_b128 v[196:199], v155 offset:3072
	ds_read_b128 v[200:203], v155 offset:4096
	ds_read_b128 v[204:207], v155 offset:5120
	ds_read_b128 v[208:211], v155 offset:6144
	ds_read_b128 v[212:215], v155 offset:7168
	s_waitcnt vmcnt(8)
	s_waitcnt lgkmcnt(0)
	s_barrier
	s_setprio 1
	s_waitcnt lgkmcnt(0)
	v_mfma_f32_16x16x32_bf16 v[124:127], v[148:151], v[184:187], v[124:127]
	v_mfma_f32_16x16x32_bf16 v[120:123], v[160:163], v[184:187], v[120:123]
	v_mfma_f32_16x16x32_bf16 v[108:111], v[148:151], v[192:195], v[108:111]
	v_mfma_f32_16x16x32_bf16 v[104:107], v[160:163], v[192:195], v[104:107]
	v_mfma_f32_16x16x32_bf16 v[92:95], v[148:151], v[200:203], v[92:95]
	v_mfma_f32_16x16x32_bf16 v[88:91], v[160:163], v[200:203], v[88:91]
	v_mfma_f32_16x16x32_bf16 v[76:79], v[148:151], v[208:211], v[76:79]
	v_mfma_f32_16x16x32_bf16 v[72:75], v[160:163], v[208:211], v[72:75]
	v_mfma_f32_16x16x32_bf16 v[124:127], v[156:159], v[188:191], v[124:127]
	v_mfma_f32_16x16x32_bf16 v[120:123], v[164:167], v[188:191], v[120:123]
	v_mfma_f32_16x16x32_bf16 v[108:111], v[156:159], v[196:199], v[108:111]
	v_mfma_f32_16x16x32_bf16 v[104:107], v[164:167], v[196:199], v[104:107]
	v_mfma_f32_16x16x32_bf16 v[92:95], v[156:159], v[204:207], v[92:95]
	v_mfma_f32_16x16x32_bf16 v[88:91], v[164:167], v[204:207], v[88:91]
	v_mfma_f32_16x16x32_bf16 v[76:79], v[156:159], v[212:215], v[76:79]
	v_mfma_f32_16x16x32_bf16 v[72:75], v[164:167], v[212:215], v[72:75]
	s_setprio 0
	s_setprio 1
	v_mfma_f32_16x16x32_bf16 v[116:119], v[168:171], v[184:187], v[116:119]
	v_mfma_f32_16x16x32_bf16 v[112:115], v[176:179], v[184:187], v[112:115]
	v_mfma_f32_16x16x32_bf16 v[100:103], v[168:171], v[192:195], v[100:103]
	v_mfma_f32_16x16x32_bf16 v[96:99], v[176:179], v[192:195], v[96:99]
	v_mfma_f32_16x16x32_bf16 v[84:87], v[168:171], v[200:203], v[84:87]
	v_mfma_f32_16x16x32_bf16 v[80:83], v[176:179], v[200:203], v[80:83]
	v_mfma_f32_16x16x32_bf16 v[68:71], v[168:171], v[208:211], v[68:71]
	v_mfma_f32_16x16x32_bf16 v[64:67], v[176:179], v[208:211], v[64:67]
	v_mfma_f32_16x16x32_bf16 v[116:119], v[172:175], v[188:191], v[116:119]
	v_mfma_f32_16x16x32_bf16 v[112:115], v[180:183], v[188:191], v[112:115]
	v_mfma_f32_16x16x32_bf16 v[100:103], v[172:175], v[196:199], v[100:103]
	v_mfma_f32_16x16x32_bf16 v[96:99], v[180:183], v[196:199], v[96:99]
	v_mfma_f32_16x16x32_bf16 v[84:87], v[172:175], v[204:207], v[84:87]
	v_mfma_f32_16x16x32_bf16 v[80:83], v[180:183], v[204:207], v[80:83]
	v_mfma_f32_16x16x32_bf16 v[68:71], v[172:175], v[212:215], v[68:71]
	v_mfma_f32_16x16x32_bf16 v[64:67], v[180:183], v[212:215], v[64:67]
	s_setprio 0
	s_barrier
	s_add_i32 s66, s52, s39
	v_lshl_add_u64 v[216:217], s[28:29], 0, v[130:131]
	s_mov_b32 m0, s66
	s_nop 0
	global_load_lds_dwordx4 v[216:217], off
	s_add_i32 m0, s66, 0x2000
	s_add_u32 s66, s28, 0x40000
	v_lshl_add_u64 v[218:219], s[28:29], 0, v[134:135]
	s_addc_u32 s67, s29, 0
	s_add_i32 s68, s53, s39
	global_load_lds_dwordx4 v[218:219], off
	v_lshl_add_u64 v[220:221], s[66:67], 0, v[130:131]
	s_mov_b32 m0, s68
	v_lshl_add_u64 v[222:223], s[30:31], 0, v[132:133]
	global_load_lds_dwordx4 v[220:221], off
	v_lshl_add_u64 v[220:221], s[66:67], 0, v[134:135]
	s_add_i32 m0, s68, 0x2000
	s_nop 0
	global_load_lds_dwordx4 v[220:221], off
	v_lshl_add_u64 v[220:221], s[30:31], 0, v[128:129]
	s_mov_b32 m0, s40
	s_nop 0
	global_load_lds_dwordx4 v[220:221], off
	s_mov_b32 m0, s41
	s_nop 0
	global_load_lds_dwordx4 v[222:223], off
	ds_read_b128 v[184:187], v155 offset:16384
	ds_read_b128 v[188:191], v155 offset:17408
	ds_read_b128 v[192:195], v155 offset:18432
	ds_read_b128 v[196:199], v155 offset:19456
	ds_read_b128 v[200:203], v155 offset:20480
	ds_read_b128 v[204:207], v155 offset:21504
	ds_read_b128 v[208:211], v155 offset:22528
	ds_read_b128 v[212:215], v155 offset:23552
	s_waitcnt vmcnt(8)
	s_waitcnt lgkmcnt(0)
	s_barrier
	s_setprio 1
	s_waitcnt lgkmcnt(0)
	v_mfma_f32_16x16x32_bf16 v[60:63], v[148:151], v[184:187], v[60:63]
	v_mfma_f32_16x16x32_bf16 v[56:59], v[160:163], v[184:187], v[56:59]
	v_mfma_f32_16x16x32_bf16 v[44:47], v[148:151], v[192:195], v[44:47]
	v_mfma_f32_16x16x32_bf16 v[40:43], v[160:163], v[192:195], v[40:43]
	v_mfma_f32_16x16x32_bf16 v[28:31], v[148:151], v[200:203], v[28:31]
	v_mfma_f32_16x16x32_bf16 v[24:27], v[160:163], v[200:203], v[24:27]
	v_mfma_f32_16x16x32_bf16 v[12:15], v[148:151], v[208:211], v[12:15]
	v_mfma_f32_16x16x32_bf16 v[8:11], v[160:163], v[208:211], v[8:11]
	v_mfma_f32_16x16x32_bf16 v[60:63], v[156:159], v[188:191], v[60:63]
	v_mfma_f32_16x16x32_bf16 v[56:59], v[164:167], v[188:191], v[56:59]
	v_mfma_f32_16x16x32_bf16 v[44:47], v[156:159], v[196:199], v[44:47]
	v_mfma_f32_16x16x32_bf16 v[40:43], v[164:167], v[196:199], v[40:43]
	v_mfma_f32_16x16x32_bf16 v[28:31], v[156:159], v[204:207], v[28:31]
	v_mfma_f32_16x16x32_bf16 v[24:27], v[164:167], v[204:207], v[24:27]
	v_mfma_f32_16x16x32_bf16 v[12:15], v[156:159], v[212:215], v[12:15]
	v_mfma_f32_16x16x32_bf16 v[8:11], v[164:167], v[212:215], v[8:11]
	s_setprio 0
	s_setprio 1
	v_mfma_f32_16x16x32_bf16 v[52:55], v[168:171], v[184:187], v[52:55]
	v_mfma_f32_16x16x32_bf16 v[48:51], v[176:179], v[184:187], v[48:51]
	v_mfma_f32_16x16x32_bf16 v[36:39], v[168:171], v[192:195], v[36:39]
	v_mfma_f32_16x16x32_bf16 v[32:35], v[176:179], v[192:195], v[32:35]
	v_mfma_f32_16x16x32_bf16 v[20:23], v[168:171], v[200:203], v[20:23]
	v_mfma_f32_16x16x32_bf16 v[16:19], v[176:179], v[200:203], v[16:19]
	v_mfma_f32_16x16x32_bf16 v[4:7], v[168:171], v[208:211], v[4:7]
	v_mfma_f32_16x16x32_bf16 v[0:3], v[176:179], v[208:211], v[0:3]
	v_mfma_f32_16x16x32_bf16 v[52:55], v[172:175], v[188:191], v[52:55]
	v_mfma_f32_16x16x32_bf16 v[48:51], v[180:183], v[188:191], v[48:51]
	v_mfma_f32_16x16x32_bf16 v[36:39], v[172:175], v[196:199], v[36:39]
	v_mfma_f32_16x16x32_bf16 v[32:35], v[180:183], v[196:199], v[32:35]
	v_mfma_f32_16x16x32_bf16 v[20:23], v[172:175], v[204:207], v[20:23]
	v_mfma_f32_16x16x32_bf16 v[16:19], v[180:183], v[204:207], v[16:19]
	v_mfma_f32_16x16x32_bf16 v[4:7], v[172:175], v[212:215], v[4:7]
	v_mfma_f32_16x16x32_bf16 v[0:3], v[180:183], v[212:215], v[0:3]
	s_setprio 0
	s_barrier
	s_add_i32 s66, 0, 0x18000
	s_add_i32 s67, 0, 0x1c000
	v_add_u32_e32 v164, s66, v152
	v_add_u32_e32 v180, s67, v152
	s_add_u32 s30, s30, 0x40000
	s_addc_u32 s31, s31, 0
	s_mov_b32 m0, s42
	v_lshl_add_u64 v[224:225], s[30:31], 0, v[128:129]
	global_load_lds_dwordx4 v[224:225], off
	v_lshl_add_u64 v[224:225], s[30:31], 0, v[132:133]
	s_mov_b32 m0, s43
	s_nop 0
	global_load_lds_dwordx4 v[224:225], off
	ds_read_b128 v[148:151], v164
	ds_read_b128 v[156:159], v164 offset:1024
	ds_read_b128 v[160:163], v164 offset:2048
	ds_read_b128 v[164:167], v164 offset:3072
	ds_read_b128 v[168:171], v180
	ds_read_b128 v[172:175], v180 offset:1024
	ds_read_b128 v[176:179], v180 offset:2048
	ds_read_b128 v[180:183], v180 offset:3072
	ds_read_b128 v[184:187], v155 offset:32768
	ds_read_b128 v[188:191], v155 offset:33792
	ds_read_b128 v[192:195], v155 offset:34816
	ds_read_b128 v[196:199], v155 offset:35840
	ds_read_b128 v[200:203], v155 offset:36864
	ds_read_b128 v[204:207], v155 offset:37888
	ds_read_b128 v[208:211], v155 offset:38912
	ds_read_b128 v[212:215], v155 offset:39936
	s_waitcnt vmcnt(8)
	s_waitcnt lgkmcnt(0)
	s_barrier
	s_setprio 1
	s_waitcnt lgkmcnt(0)
	v_mfma_f32_16x16x32_bf16 v[124:127], v[148:151], v[184:187], v[124:127]
	v_mfma_f32_16x16x32_bf16 v[120:123], v[160:163], v[184:187], v[120:123]
	v_mfma_f32_16x16x32_bf16 v[108:111], v[148:151], v[192:195], v[108:111]
	v_mfma_f32_16x16x32_bf16 v[104:107], v[160:163], v[192:195], v[104:107]
	v_mfma_f32_16x16x32_bf16 v[92:95], v[148:151], v[200:203], v[92:95]
	v_mfma_f32_16x16x32_bf16 v[88:91], v[160:163], v[200:203], v[88:91]
	v_mfma_f32_16x16x32_bf16 v[76:79], v[148:151], v[208:211], v[76:79]
	v_mfma_f32_16x16x32_bf16 v[72:75], v[160:163], v[208:211], v[72:75]
	v_mfma_f32_16x16x32_bf16 v[124:127], v[156:159], v[188:191], v[124:127]
	v_mfma_f32_16x16x32_bf16 v[120:123], v[164:167], v[188:191], v[120:123]
	v_mfma_f32_16x16x32_bf16 v[108:111], v[156:159], v[196:199], v[108:111]
	v_mfma_f32_16x16x32_bf16 v[104:107], v[164:167], v[196:199], v[104:107]
	v_mfma_f32_16x16x32_bf16 v[92:95], v[156:159], v[204:207], v[92:95]
	v_mfma_f32_16x16x32_bf16 v[88:91], v[164:167], v[204:207], v[88:91]
	v_mfma_f32_16x16x32_bf16 v[76:79], v[156:159], v[212:215], v[76:79]
	v_mfma_f32_16x16x32_bf16 v[72:75], v[164:167], v[212:215], v[72:75]
	s_setprio 0
	s_setprio 1
	v_mfma_f32_16x16x32_bf16 v[116:119], v[168:171], v[184:187], v[116:119]
	v_mfma_f32_16x16x32_bf16 v[112:115], v[176:179], v[184:187], v[112:115]
	v_mfma_f32_16x16x32_bf16 v[100:103], v[168:171], v[192:195], v[100:103]
	v_mfma_f32_16x16x32_bf16 v[96:99], v[176:179], v[192:195], v[96:99]
	v_mfma_f32_16x16x32_bf16 v[84:87], v[168:171], v[200:203], v[84:87]
	v_mfma_f32_16x16x32_bf16 v[80:83], v[176:179], v[200:203], v[80:83]
	v_mfma_f32_16x16x32_bf16 v[68:71], v[168:171], v[208:211], v[68:71]
	v_mfma_f32_16x16x32_bf16 v[64:67], v[176:179], v[208:211], v[64:67]
	v_mfma_f32_16x16x32_bf16 v[116:119], v[172:175], v[188:191], v[116:119]
	v_mfma_f32_16x16x32_bf16 v[112:115], v[180:183], v[188:191], v[112:115]
	v_mfma_f32_16x16x32_bf16 v[100:103], v[172:175], v[196:199], v[100:103]
	v_mfma_f32_16x16x32_bf16 v[96:99], v[180:183], v[196:199], v[96:99]
	v_mfma_f32_16x16x32_bf16 v[84:87], v[172:175], v[204:207], v[84:87]
	v_mfma_f32_16x16x32_bf16 v[80:83], v[180:183], v[204:207], v[80:83]
	v_mfma_f32_16x16x32_bf16 v[68:71], v[172:175], v[212:215], v[68:71]
	v_mfma_f32_16x16x32_bf16 v[64:67], v[180:183], v[212:215], v[64:67]
	s_setprio 0
	s_barrier
	s_add_i32 s30, s66, s39
	v_lshl_add_u64 v[216:217], v[216:217], 0, s[14:15]
	s_mov_b32 m0, s30
	s_nop 0
	global_load_lds_dwordx4 v[216:217], off
	s_add_i32 m0, s30, 0x2000
	s_add_u32 s28, s28, 0x40080
	v_lshl_add_u64 v[216:217], v[218:219], 0, s[14:15]
	s_addc_u32 s29, s29, 0
	s_add_i32 s30, s67, s39
	global_load_lds_dwordx4 v[216:217], off
	v_lshl_add_u64 v[216:217], s[28:29], 0, v[130:131]
	s_mov_b32 m0, s30
	s_nop 0
	global_load_lds_dwordx4 v[216:217], off
	v_lshl_add_u64 v[216:217], s[28:29], 0, v[134:135]
	s_add_i32 m0, s30, 0x2000
	s_nop 0
	global_load_lds_dwordx4 v[216:217], off
	v_lshl_add_u64 v[216:217], v[220:221], 0, s[14:15]
	s_mov_b32 m0, s45
	s_nop 0
	global_load_lds_dwordx4 v[216:217], off
	v_lshl_add_u64 v[216:217], v[222:223], 0, s[14:15]
	s_mov_b32 m0, s46
	s_nop 0
	global_load_lds_dwordx4 v[216:217], off
	ds_read_b128 v[184:187], v155 offset:49152
	ds_read_b128 v[188:191], v155 offset:50176
	ds_read_b128 v[192:195], v155 offset:51200
	ds_read_b128 v[196:199], v155 offset:52224
	ds_read_b128 v[200:203], v155 offset:53248
	ds_read_b128 v[204:207], v155 offset:54272
	ds_read_b128 v[208:211], v155 offset:55296
	ds_read_b128 v[212:215], v155 offset:56320
	s_waitcnt vmcnt(8)
	s_waitcnt lgkmcnt(0)
	s_barrier
	s_setprio 1
	s_waitcnt lgkmcnt(0)
	v_mfma_f32_16x16x32_bf16 v[60:63], v[148:151], v[184:187], v[60:63]
	v_mfma_f32_16x16x32_bf16 v[56:59], v[160:163], v[184:187], v[56:59]
	v_mfma_f32_16x16x32_bf16 v[44:47], v[148:151], v[192:195], v[44:47]
	v_mfma_f32_16x16x32_bf16 v[40:43], v[160:163], v[192:195], v[40:43]
	v_mfma_f32_16x16x32_bf16 v[28:31], v[148:151], v[200:203], v[28:31]
	v_mfma_f32_16x16x32_bf16 v[24:27], v[160:163], v[200:203], v[24:27]
	v_mfma_f32_16x16x32_bf16 v[12:15], v[148:151], v[208:211], v[12:15]
	v_mfma_f32_16x16x32_bf16 v[8:11], v[160:163], v[208:211], v[8:11]
	v_mfma_f32_16x16x32_bf16 v[60:63], v[156:159], v[188:191], v[60:63]
	v_mfma_f32_16x16x32_bf16 v[56:59], v[164:167], v[188:191], v[56:59]
	v_mfma_f32_16x16x32_bf16 v[44:47], v[156:159], v[196:199], v[44:47]
	v_mfma_f32_16x16x32_bf16 v[40:43], v[164:167], v[196:199], v[40:43]
	v_mfma_f32_16x16x32_bf16 v[28:31], v[156:159], v[204:207], v[28:31]
	v_mfma_f32_16x16x32_bf16 v[24:27], v[164:167], v[204:207], v[24:27]
	v_mfma_f32_16x16x32_bf16 v[12:15], v[156:159], v[212:215], v[12:15]
	v_mfma_f32_16x16x32_bf16 v[8:11], v[164:167], v[212:215], v[8:11]
	s_setprio 0
	s_setprio 1
	v_mfma_f32_16x16x32_bf16 v[52:55], v[168:171], v[184:187], v[52:55]
	v_mfma_f32_16x16x32_bf16 v[48:51], v[176:179], v[184:187], v[48:51]
	v_mfma_f32_16x16x32_bf16 v[36:39], v[168:171], v[192:195], v[36:39]
	v_mfma_f32_16x16x32_bf16 v[32:35], v[176:179], v[192:195], v[32:35]
	v_mfma_f32_16x16x32_bf16 v[20:23], v[168:171], v[200:203], v[20:23]
	v_mfma_f32_16x16x32_bf16 v[16:19], v[176:179], v[200:203], v[16:19]
	v_mfma_f32_16x16x32_bf16 v[4:7], v[168:171], v[208:211], v[4:7]
	v_mfma_f32_16x16x32_bf16 v[0:3], v[176:179], v[208:211], v[0:3]
	v_mfma_f32_16x16x32_bf16 v[52:55], v[172:175], v[188:191], v[52:55]
	v_mfma_f32_16x16x32_bf16 v[48:51], v[180:183], v[188:191], v[48:51]
	v_mfma_f32_16x16x32_bf16 v[36:39], v[172:175], v[196:199], v[36:39]
	v_mfma_f32_16x16x32_bf16 v[32:35], v[180:183], v[196:199], v[32:35]
	v_mfma_f32_16x16x32_bf16 v[20:23], v[172:175], v[204:207], v[20:23]
	v_mfma_f32_16x16x32_bf16 v[16:19], v[180:183], v[204:207], v[16:19]
	v_mfma_f32_16x16x32_bf16 v[4:7], v[172:175], v[212:215], v[4:7]
	v_mfma_f32_16x16x32_bf16 v[0:3], v[180:183], v[212:215], v[0:3]
	s_setprio 0
	s_barrier
	s_add_i32 s65, s65, 2
	s_add_u32 s34, s34, 0x100
	s_addc_u32 s35, s35, 0
	s_add_u32 s26, s26, 0x100
	s_addc_u32 s27, s27, 0
	s_cmp_lt_u32 s65, 14
	s_cbranch_scc1 .LBB8_12
	s_andn2_b64 vcc, exec, s[16:17]
	s_cbranch_vccnz .LBB8_15
	s_barrier

.LBB10_19:
	s_ashr_i32 s17, s16, 31
	v_cmp_lt_i64_e32 vcc, s[0:1], v[142:143]
	s_lshl_b64 s[0:1], s[16:17], 19
	s_add_u32 s18, s33, s0
	s_addc_u32 s19, s34, s1
	s_and_b64 s[0:1], vcc, exec
	s_cselect_b32 s17, s19, s27
	s_cselect_b32 s53, s18, s26
	s_ashr_i32 s15, s14, 31
	s_lshl_b64 s[0:1], s[14:15], 19
	s_add_u32 s20, s4, s0
	s_addc_u32 s21, s5, s1
	s_and_b64 s[0:1], vcc, exec
	s_cselect_b32 s15, s21, s25
	s_cselect_b32 s54, s20, s24
	s_add_u32 s55, s24, 0x100
	s_addc_u32 s56, s25, 0
	s_add_u32 s24, s26, 0x40080
	s_addc_u32 s25, s27, 0
	s_mov_b32 s57, -2
	s_add_u32 s26, s24, 0xfffc0080
	s_addc_u32 s27, s25, -1
	s_cmp_eq_u32 s57, 12
	s_cselect_b32 s29, s17, s27
	s_cselect_b32 s28, s53, s26
	s_cselect_b32 s27, s15, s56
	s_cselect_b32 s26, s54, s55
	v_lshl_add_u64 v[146:147], s[24:25], 0, v[140:141]
	s_add_i32 m0, s35, 0xc000
	s_nop 0
	global_load_lds_dwordx4 v[146:147], off
	v_lshl_add_u64 v[146:147], s[24:25], 0, v[138:139]
	s_add_i32 m0, s35, 0xe000
	s_nop 0
	global_load_lds_dwordx4 v[146:147], off
	ds_read_b128 v[152:155], v149
	ds_read_b128 v[156:159], v149 offset:1024
	ds_read_b128 v[160:163], v149 offset:2048
	ds_read_b128 v[164:167], v149 offset:3072
	ds_read_b128 v[168:171], v150
	ds_read_b128 v[172:175], v150 offset:1024
	ds_read_b128 v[176:179], v150 offset:2048
	ds_read_b128 v[180:183], v150 offset:3072
	ds_read_b128 v[184:187], v151
	ds_read_b128 v[188:191], v151 offset:1024
	ds_read_b128 v[192:195], v151 offset:2048
	ds_read_b128 v[196:199], v151 offset:3072
	ds_read_b128 v[200:203], v151 offset:4096
	ds_read_b128 v[204:207], v151 offset:5120
	ds_read_b128 v[208:211], v151 offset:6144
	ds_read_b128 v[212:215], v151 offset:7168
	s_waitcnt vmcnt(8)
	s_waitcnt lgkmcnt(0)
	s_barrier
	s_setprio 1
	s_waitcnt lgkmcnt(0)
	v_mfma_f32_16x16x32_bf16 v[124:127], v[152:155], v[184:187], 0
	v_mfma_f32_16x16x32_bf16 v[120:123], v[160:163], v[184:187], 0
	v_mfma_f32_16x16x32_bf16 v[116:119], v[152:155], v[192:195], 0
	v_mfma_f32_16x16x32_bf16 v[108:111], v[160:163], v[192:195], 0
	v_mfma_f32_16x16x32_bf16 v[100:103], v[152:155], v[200:203], 0
	v_mfma_f32_16x16x32_bf16 v[92:95], v[160:163], v[200:203], 0
	v_mfma_f32_16x16x32_bf16 v[84:87], v[152:155], v[208:211], 0
	v_mfma_f32_16x16x32_bf16 v[76:79], v[160:163], v[208:211], 0
	v_mfma_f32_16x16x32_bf16 v[124:127], v[156:159], v[188:191], v[124:127]
	v_mfma_f32_16x16x32_bf16 v[120:123], v[164:167], v[188:191], v[120:123]
	v_mfma_f32_16x16x32_bf16 v[116:119], v[156:159], v[196:199], v[116:119]
	v_mfma_f32_16x16x32_bf16 v[108:111], v[164:167], v[196:199], v[108:111]
	v_mfma_f32_16x16x32_bf16 v[100:103], v[156:159], v[204:207], v[100:103]
	v_mfma_f32_16x16x32_bf16 v[92:95], v[164:167], v[204:207], v[92:95]
	v_mfma_f32_16x16x32_bf16 v[84:87], v[156:159], v[212:215], v[84:87]
	v_mfma_f32_16x16x32_bf16 v[76:79], v[164:167], v[212:215], v[76:79]
	s_setprio 0
	s_setprio 1
	v_mfma_f32_16x16x32_bf16 v[112:115], v[168:171], v[184:187], 0
	v_mfma_f32_16x16x32_bf16 v[104:107], v[176:179], v[184:187], 0
	v_mfma_f32_16x16x32_bf16 v[96:99], v[168:171], v[192:195], 0
	v_mfma_f32_16x16x32_bf16 v[88:91], v[176:179], v[192:195], 0
	v_mfma_f32_16x16x32_bf16 v[80:83], v[168:171], v[200:203], 0
	v_mfma_f32_16x16x32_bf16 v[72:75], v[176:179], v[200:203], 0
	v_mfma_f32_16x16x32_bf16 v[68:71], v[168:171], v[208:211], 0
	v_mfma_f32_16x16x32_bf16 v[64:67], v[176:179], v[208:211], 0
	v_mfma_f32_16x16x32_bf16 v[112:115], v[172:175], v[188:191], v[112:115]
	v_mfma_f32_16x16x32_bf16 v[104:107], v[180:183], v[188:191], v[104:107]
	v_mfma_f32_16x16x32_bf16 v[96:99], v[172:175], v[196:199], v[96:99]
	v_mfma_f32_16x16x32_bf16 v[88:91], v[180:183], v[196:199], v[88:91]
	v_mfma_f32_16x16x32_bf16 v[80:83], v[172:175], v[204:207], v[80:83]
	v_mfma_f32_16x16x32_bf16 v[72:75], v[180:183], v[204:207], v[72:75]
	v_mfma_f32_16x16x32_bf16 v[68:71], v[172:175], v[212:215], v[68:71]
	v_mfma_f32_16x16x32_bf16 v[64:67], v[180:183], v[212:215], v[64:67]
	s_setprio 0
	s_barrier
	s_add_i32 s58, s46, s31
	v_lshl_add_u64 v[146:147], s[26:27], 0, v[130:131]
	s_mov_b32 m0, s58
	s_nop 0
	global_load_lds_dwordx4 v[146:147], off
	s_add_i32 m0, s58, 0x2000
	s_add_u32 s58, s26, 0x40000
	v_lshl_add_u64 v[216:217], s[26:27], 0, v[134:135]
	s_addc_u32 s59, s27, 0
	s_add_i32 s60, s47, s31
	global_load_lds_dwordx4 v[216:217], off
	v_lshl_add_u64 v[218:219], s[58:59], 0, v[130:131]
	s_mov_b32 m0, s60
	v_lshl_add_u64 v[220:221], s[28:29], 0, v[132:133]
	global_load_lds_dwordx4 v[218:219], off
	v_lshl_add_u64 v[218:219], s[58:59], 0, v[134:135]
	s_add_i32 m0, s60, 0x2000
	s_nop 0
	global_load_lds_dwordx4 v[218:219], off
	v_lshl_add_u64 v[218:219], s[28:29], 0, v[128:129]
	s_mov_b32 m0, s35
	s_nop 0
	global_load_lds_dwordx4 v[218:219], off
	s_mov_b32 m0, s36
	s_nop 0
	global_load_lds_dwordx4 v[220:221], off
	ds_read_b128 v[184:187], v151 offset:16384
	ds_read_b128 v[188:191], v151 offset:17408
	ds_read_b128 v[192:195], v151 offset:18432
	ds_read_b128 v[196:199], v151 offset:19456
	ds_read_b128 v[200:203], v151 offset:20480
	ds_read_b128 v[204:207], v151 offset:21504
	ds_read_b128 v[208:211], v151 offset:22528
	ds_read_b128 v[212:215], v151 offset:23552
	s_waitcnt vmcnt(8)
	s_waitcnt lgkmcnt(0)
	s_barrier
	s_setprio 1
	s_waitcnt lgkmcnt(0)
	v_mfma_f32_16x16x32_bf16 v[60:63], v[152:155], v[184:187], 0
	v_mfma_f32_16x16x32_bf16 v[56:59], v[160:163], v[184:187], 0
	v_mfma_f32_16x16x32_bf16 v[52:55], v[152:155], v[192:195], 0
	v_mfma_f32_16x16x32_bf16 v[44:47], v[160:163], v[192:195], 0
	v_mfma_f32_16x16x32_bf16 v[36:39], v[152:155], v[200:203], 0
	v_mfma_f32_16x16x32_bf16 v[28:31], v[160:163], v[200:203], 0
	v_mfma_f32_16x16x32_bf16 v[20:23], v[152:155], v[208:211], 0
	v_mfma_f32_16x16x32_bf16 v[12:15], v[160:163], v[208:211], 0
	v_mfma_f32_16x16x32_bf16 v[60:63], v[156:159], v[188:191], v[60:63]
	v_mfma_f32_16x16x32_bf16 v[56:59], v[164:167], v[188:191], v[56:59]
	v_mfma_f32_16x16x32_bf16 v[52:55], v[156:159], v[196:199], v[52:55]
	v_mfma_f32_16x16x32_bf16 v[44:47], v[164:167], v[196:199], v[44:47]
	v_mfma_f32_16x16x32_bf16 v[36:39], v[156:159], v[204:207], v[36:39]
	v_mfma_f32_16x16x32_bf16 v[28:31], v[164:167], v[204:207], v[28:31]
	v_mfma_f32_16x16x32_bf16 v[20:23], v[156:159], v[212:215], v[20:23]
	v_mfma_f32_16x16x32_bf16 v[12:15], v[164:167], v[212:215], v[12:15]
	s_setprio 0
	s_setprio 1
	v_mfma_f32_16x16x32_bf16 v[48:51], v[168:171], v[184:187], 0
	v_mfma_f32_16x16x32_bf16 v[40:43], v[176:179], v[184:187], 0
	v_mfma_f32_16x16x32_bf16 v[32:35], v[168:171], v[192:195], 0
	v_mfma_f32_16x16x32_bf16 v[24:27], v[176:179], v[192:195], 0
	v_mfma_f32_16x16x32_bf16 v[16:19], v[168:171], v[200:203], 0
	v_mfma_f32_16x16x32_bf16 v[8:11], v[176:179], v[200:203], 0
	v_mfma_f32_16x16x32_bf16 v[4:7], v[168:171], v[208:211], 0
	v_mfma_f32_16x16x32_bf16 v[0:3], v[176:179], v[208:211], 0
	v_mfma_f32_16x16x32_bf16 v[48:51], v[172:175], v[188:191], v[48:51]
	v_mfma_f32_16x16x32_bf16 v[40:43], v[180:183], v[188:191], v[40:43]
	v_mfma_f32_16x16x32_bf16 v[32:35], v[172:175], v[196:199], v[32:35]
	v_mfma_f32_16x16x32_bf16 v[24:27], v[180:183], v[196:199], v[24:27]
	v_mfma_f32_16x16x32_bf16 v[16:19], v[172:175], v[204:207], v[16:19]
	v_mfma_f32_16x16x32_bf16 v[8:11], v[180:183], v[204:207], v[8:11]
	v_mfma_f32_16x16x32_bf16 v[4:7], v[172:175], v[212:215], v[4:7]
	v_mfma_f32_16x16x32_bf16 v[0:3], v[180:183], v[212:215], v[0:3]
	s_setprio 0
	s_barrier
	s_add_i32 s58, 0, 0x18000
	s_add_i32 s59, 0, 0x1c000
	v_add_u32_e32 v164, s58, v148
	v_add_u32_e32 v180, s59, v148
	s_add_u32 s28, s28, 0x40000
	s_addc_u32 s29, s29, 0
	s_mov_b32 m0, s37
	v_lshl_add_u64 v[222:223], s[28:29], 0, v[128:129]
	global_load_lds_dwordx4 v[222:223], off
	v_lshl_add_u64 v[222:223], s[28:29], 0, v[132:133]
	s_mov_b32 m0, s38
	s_nop 0
	global_load_lds_dwordx4 v[222:223], off
	ds_read_b128 v[152:155], v164
	ds_read_b128 v[156:159], v164 offset:1024
	ds_read_b128 v[160:163], v164 offset:2048
	ds_read_b128 v[164:167], v164 offset:3072
	ds_read_b128 v[168:171], v180
	ds_read_b128 v[172:175], v180 offset:1024
	ds_read_b128 v[176:179], v180 offset:2048
	ds_read_b128 v[180:183], v180 offset:3072
	ds_read_b128 v[184:187], v151 offset:32768
	ds_read_b128 v[188:191], v151 offset:33792
	ds_read_b128 v[192:195], v151 offset:34816
	ds_read_b128 v[196:199], v151 offset:35840
	ds_read_b128 v[200:203], v151 offset:36864
	ds_read_b128 v[204:207], v151 offset:37888
	ds_read_b128 v[208:211], v151 offset:38912
	ds_read_b128 v[212:215], v151 offset:39936
	s_waitcnt vmcnt(8)
	s_waitcnt lgkmcnt(0)
	s_barrier
	s_setprio 1
	s_waitcnt lgkmcnt(0)
	v_mfma_f32_16x16x32_bf16 v[124:127], v[152:155], v[184:187], v[124:127]
	v_mfma_f32_16x16x32_bf16 v[120:123], v[160:163], v[184:187], v[120:123]
	v_mfma_f32_16x16x32_bf16 v[116:119], v[152:155], v[192:195], v[116:119]
	v_mfma_f32_16x16x32_bf16 v[108:111], v[160:163], v[192:195], v[108:111]
	v_mfma_f32_16x16x32_bf16 v[100:103], v[152:155], v[200:203], v[100:103]
	v_mfma_f32_16x16x32_bf16 v[92:95], v[160:163], v[200:203], v[92:95]
	v_mfma_f32_16x16x32_bf16 v[84:87], v[152:155], v[208:211], v[84:87]
	v_mfma_f32_16x16x32_bf16 v[76:79], v[160:163], v[208:211], v[76:79]
	v_mfma_f32_16x16x32_bf16 v[124:127], v[156:159], v[188:191], v[124:127]
	v_mfma_f32_16x16x32_bf16 v[120:123], v[164:167], v[188:191], v[120:123]
	v_mfma_f32_16x16x32_bf16 v[116:119], v[156:159], v[196:199], v[116:119]
	v_mfma_f32_16x16x32_bf16 v[108:111], v[164:167], v[196:199], v[108:111]
	v_mfma_f32_16x16x32_bf16 v[100:103], v[156:159], v[204:207], v[100:103]
	v_mfma_f32_16x16x32_bf16 v[92:95], v[164:167], v[204:207], v[92:95]
	v_mfma_f32_16x16x32_bf16 v[84:87], v[156:159], v[212:215], v[84:87]
	v_mfma_f32_16x16x32_bf16 v[76:79], v[164:167], v[212:215], v[76:79]
	s_setprio 0
	s_setprio 1
	v_mfma_f32_16x16x32_bf16 v[112:115], v[168:171], v[184:187], v[112:115]
	v_mfma_f32_16x16x32_bf16 v[104:107], v[176:179], v[184:187], v[104:107]
	v_mfma_f32_16x16x32_bf16 v[96:99], v[168:171], v[192:195], v[96:99]
	v_mfma_f32_16x16x32_bf16 v[88:91], v[176:179], v[192:195], v[88:91]
	v_mfma_f32_16x16x32_bf16 v[80:83], v[168:171], v[200:203], v[80:83]
	v_mfma_f32_16x16x32_bf16 v[72:75], v[176:179], v[200:203], v[72:75]
	v_mfma_f32_16x16x32_bf16 v[68:71], v[168:171], v[208:211], v[68:71]
	v_mfma_f32_16x16x32_bf16 v[64:67], v[176:179], v[208:211], v[64:67]
	v_mfma_f32_16x16x32_bf16 v[112:115], v[172:175], v[188:191], v[112:115]
	v_mfma_f32_16x16x32_bf16 v[104:107], v[180:183], v[188:191], v[104:107]
	v_mfma_f32_16x16x32_bf16 v[96:99], v[172:175], v[196:199], v[96:99]
	v_mfma_f32_16x16x32_bf16 v[88:91], v[180:183], v[196:199], v[88:91]
	v_mfma_f32_16x16x32_bf16 v[80:83], v[172:175], v[204:207], v[80:83]
	v_mfma_f32_16x16x32_bf16 v[72:75], v[180:183], v[204:207], v[72:75]
	v_mfma_f32_16x16x32_bf16 v[68:71], v[172:175], v[212:215], v[68:71]
	v_mfma_f32_16x16x32_bf16 v[64:67], v[180:183], v[212:215], v[64:67]
	s_setprio 0
	s_barrier
	s_add_i32 s28, s58, s31
	v_lshl_add_u64 v[146:147], v[146:147], 0, s[10:11]
	s_mov_b32 m0, s28
	s_nop 0
	global_load_lds_dwordx4 v[146:147], off
	s_add_i32 m0, s28, 0x2000
	s_add_u32 s26, s26, 0x40080
	v_lshl_add_u64 v[146:147], v[216:217], 0, s[10:11]
	s_addc_u32 s27, s27, 0
	s_add_i32 s28, s59, s31
	global_load_lds_dwordx4 v[146:147], off
	v_lshl_add_u64 v[146:147], s[26:27], 0, v[130:131]
	s_mov_b32 m0, s28
	s_nop 0
	global_load_lds_dwordx4 v[146:147], off
	v_lshl_add_u64 v[146:147], s[26:27], 0, v[134:135]
	s_add_i32 m0, s28, 0x2000
	s_nop 0
	global_load_lds_dwordx4 v[146:147], off
	v_lshl_add_u64 v[146:147], v[218:219], 0, s[10:11]
	s_mov_b32 m0, s41
	s_nop 0
	global_load_lds_dwordx4 v[146:147], off
	v_lshl_add_u64 v[146:147], v[220:221], 0, s[10:11]
	s_mov_b32 m0, s42
	s_nop 0
	global_load_lds_dwordx4 v[146:147], off
	ds_read_b128 v[184:187], v151 offset:49152
	ds_read_b128 v[188:191], v151 offset:50176
	ds_read_b128 v[192:195], v151 offset:51200
	ds_read_b128 v[196:199], v151 offset:52224
	ds_read_b128 v[200:203], v151 offset:53248
	ds_read_b128 v[204:207], v151 offset:54272
	ds_read_b128 v[208:211], v151 offset:55296
	ds_read_b128 v[212:215], v151 offset:56320
	s_waitcnt vmcnt(8)
	s_waitcnt lgkmcnt(0)
	s_barrier
	s_setprio 1
	s_waitcnt lgkmcnt(0)
	v_mfma_f32_16x16x32_bf16 v[60:63], v[152:155], v[184:187], v[60:63]
	v_mfma_f32_16x16x32_bf16 v[56:59], v[160:163], v[184:187], v[56:59]
	v_mfma_f32_16x16x32_bf16 v[52:55], v[152:155], v[192:195], v[52:55]
	v_mfma_f32_16x16x32_bf16 v[44:47], v[160:163], v[192:195], v[44:47]
	v_mfma_f32_16x16x32_bf16 v[36:39], v[152:155], v[200:203], v[36:39]
	v_mfma_f32_16x16x32_bf16 v[28:31], v[160:163], v[200:203], v[28:31]
	v_mfma_f32_16x16x32_bf16 v[20:23], v[152:155], v[208:211], v[20:23]
	v_mfma_f32_16x16x32_bf16 v[12:15], v[160:163], v[208:211], v[12:15]
	v_mfma_f32_16x16x32_bf16 v[60:63], v[156:159], v[188:191], v[60:63]
	v_mfma_f32_16x16x32_bf16 v[56:59], v[164:167], v[188:191], v[56:59]
	v_mfma_f32_16x16x32_bf16 v[52:55], v[156:159], v[196:199], v[52:55]
	v_mfma_f32_16x16x32_bf16 v[44:47], v[164:167], v[196:199], v[44:47]
	v_mfma_f32_16x16x32_bf16 v[36:39], v[156:159], v[204:207], v[36:39]
	v_mfma_f32_16x16x32_bf16 v[28:31], v[164:167], v[204:207], v[28:31]
	v_mfma_f32_16x16x32_bf16 v[20:23], v[156:159], v[212:215], v[20:23]
	v_mfma_f32_16x16x32_bf16 v[12:15], v[164:167], v[212:215], v[12:15]
	s_setprio 0
	s_setprio 1
	v_mfma_f32_16x16x32_bf16 v[48:51], v[168:171], v[184:187], v[48:51]
	v_mfma_f32_16x16x32_bf16 v[40:43], v[176:179], v[184:187], v[40:43]
	v_mfma_f32_16x16x32_bf16 v[32:35], v[168:171], v[192:195], v[32:35]
	v_mfma_f32_16x16x32_bf16 v[24:27], v[176:179], v[192:195], v[24:27]
	v_mfma_f32_16x16x32_bf16 v[16:19], v[168:171], v[200:203], v[16:19]
	v_mfma_f32_16x16x32_bf16 v[8:11], v[176:179], v[200:203], v[8:11]
	v_mfma_f32_16x16x32_bf16 v[4:7], v[168:171], v[208:211], v[4:7]
	v_mfma_f32_16x16x32_bf16 v[0:3], v[176:179], v[208:211], v[0:3]
	v_mfma_f32_16x16x32_bf16 v[48:51], v[172:175], v[188:191], v[48:51]
	v_mfma_f32_16x16x32_bf16 v[40:43], v[180:183], v[188:191], v[40:43]
	v_mfma_f32_16x16x32_bf16 v[32:35], v[172:175], v[196:199], v[32:35]
	v_mfma_f32_16x16x32_bf16 v[24:27], v[180:183], v[196:199], v[24:27]
	v_mfma_f32_16x16x32_bf16 v[16:19], v[172:175], v[204:207], v[16:19]
	v_mfma_f32_16x16x32_bf16 v[8:11], v[180:183], v[204:207], v[8:11]
	v_mfma_f32_16x16x32_bf16 v[4:7], v[172:175], v[212:215], v[4:7]
	v_mfma_f32_16x16x32_bf16 v[0:3], v[180:183], v[212:215], v[0:3]
	s_setprio 0
	s_barrier
	s_add_i32 s57, s57, 2
	s_add_u32 s55, s55, 0x100
	s_addc_u32 s56, s56, 0
	s_add_u32 s24, s24, 0x100
	s_addc_u32 s25, s25, 0
	s_cmp_lt_u32 s57, 14
.LBB10_20:
	s_add_u32 s26, s24, 0xfffc0080
	s_addc_u32 s27, s25, -1
	s_cmp_eq_u32 s57, 12
	s_cselect_b32 s29, s17, s27
	s_cselect_b32 s28, s53, s26
	s_cselect_b32 s27, s15, s56
	s_cselect_b32 s26, s54, s55
	v_lshl_add_u64 v[146:147], s[24:25], 0, v[140:141]
	s_add_i32 m0, s35, 0xc000
	s_nop 0
	global_load_lds_dwordx4 v[146:147], off
	v_lshl_add_u64 v[146:147], s[24:25], 0, v[138:139]
	s_add_i32 m0, s35, 0xe000
	s_nop 0
	global_load_lds_dwordx4 v[146:147], off
	ds_read_b128 v[152:155], v149
	ds_read_b128 v[156:159], v149 offset:1024
	ds_read_b128 v[160:163], v149 offset:2048
	ds_read_b128 v[164:167], v149 offset:3072
	ds_read_b128 v[168:171], v150
	ds_read_b128 v[172:175], v150 offset:1024
	ds_read_b128 v[176:179], v150 offset:2048
	ds_read_b128 v[180:183], v150 offset:3072
	ds_read_b128 v[184:187], v151
	ds_read_b128 v[188:191], v151 offset:1024
	ds_read_b128 v[192:195], v151 offset:2048
	ds_read_b128 v[196:199], v151 offset:3072
	ds_read_b128 v[200:203], v151 offset:4096
	ds_read_b128 v[204:207], v151 offset:5120
	ds_read_b128 v[208:211], v151 offset:6144
	ds_read_b128 v[212:215], v151 offset:7168
	s_waitcnt vmcnt(8)
	s_waitcnt lgkmcnt(0)
	s_barrier
	s_setprio 1
	s_waitcnt lgkmcnt(0)
	v_mfma_f32_16x16x32_bf16 v[124:127], v[152:155], v[184:187], v[124:127]
	v_mfma_f32_16x16x32_bf16 v[120:123], v[160:163], v[184:187], v[120:123]
	v_mfma_f32_16x16x32_bf16 v[116:119], v[152:155], v[192:195], v[116:119]
	v_mfma_f32_16x16x32_bf16 v[108:111], v[160:163], v[192:195], v[108:111]
	v_mfma_f32_16x16x32_bf16 v[100:103], v[152:155], v[200:203], v[100:103]
	v_mfma_f32_16x16x32_bf16 v[92:95], v[160:163], v[200:203], v[92:95]
	v_mfma_f32_16x16x32_bf16 v[84:87], v[152:155], v[208:211], v[84:87]
	v_mfma_f32_16x16x32_bf16 v[76:79], v[160:163], v[208:211], v[76:79]
	v_mfma_f32_16x16x32_bf16 v[124:127], v[156:159], v[188:191], v[124:127]
	v_mfma_f32_16x16x32_bf16 v[120:123], v[164:167], v[188:191], v[120:123]
	v_mfma_f32_16x16x32_bf16 v[116:119], v[156:159], v[196:199], v[116:119]
	v_mfma_f32_16x16x32_bf16 v[108:111], v[164:167], v[196:199], v[108:111]
	v_mfma_f32_16x16x32_bf16 v[100:103], v[156:159], v[204:207], v[100:103]
	v_mfma_f32_16x16x32_bf16 v[92:95], v[164:167], v[204:207], v[92:95]
	v_mfma_f32_16x16x32_bf16 v[84:87], v[156:159], v[212:215], v[84:87]
	v_mfma_f32_16x16x32_bf16 v[76:79], v[164:167], v[212:215], v[76:79]
	s_setprio 0
	s_setprio 1
	v_mfma_f32_16x16x32_bf16 v[112:115], v[168:171], v[184:187], v[112:115]
	v_mfma_f32_16x16x32_bf16 v[104:107], v[176:179], v[184:187], v[104:107]
	v_mfma_f32_16x16x32_bf16 v[96:99], v[168:171], v[192:195], v[96:99]
	v_mfma_f32_16x16x32_bf16 v[88:91], v[176:179], v[192:195], v[88:91]
	v_mfma_f32_16x16x32_bf16 v[80:83], v[168:171], v[200:203], v[80:83]
	v_mfma_f32_16x16x32_bf16 v[72:75], v[176:179], v[200:203], v[72:75]
	v_mfma_f32_16x16x32_bf16 v[68:71], v[168:171], v[208:211], v[68:71]
	v_mfma_f32_16x16x32_bf16 v[64:67], v[176:179], v[208:211], v[64:67]
	v_mfma_f32_16x16x32_bf16 v[112:115], v[172:175], v[188:191], v[112:115]
	v_mfma_f32_16x16x32_bf16 v[104:107], v[180:183], v[188:191], v[104:107]
	v_mfma_f32_16x16x32_bf16 v[96:99], v[172:175], v[196:199], v[96:99]
	v_mfma_f32_16x16x32_bf16 v[88:91], v[180:183], v[196:199], v[88:91]
	v_mfma_f32_16x16x32_bf16 v[80:83], v[172:175], v[204:207], v[80:83]
	v_mfma_f32_16x16x32_bf16 v[72:75], v[180:183], v[204:207], v[72:75]
	v_mfma_f32_16x16x32_bf16 v[68:71], v[172:175], v[212:215], v[68:71]
	v_mfma_f32_16x16x32_bf16 v[64:67], v[180:183], v[212:215], v[64:67]
	s_setprio 0
	s_barrier
	s_add_i32 s58, s46, s31
	v_lshl_add_u64 v[146:147], s[26:27], 0, v[130:131]
	s_mov_b32 m0, s58
	s_nop 0
	global_load_lds_dwordx4 v[146:147], off
	s_add_i32 m0, s58, 0x2000
	s_add_u32 s58, s26, 0x40000
	v_lshl_add_u64 v[216:217], s[26:27], 0, v[134:135]
	s_addc_u32 s59, s27, 0
	s_add_i32 s60, s47, s31
	global_load_lds_dwordx4 v[216:217], off
	v_lshl_add_u64 v[218:219], s[58:59], 0, v[130:131]
	s_mov_b32 m0, s60
	v_lshl_add_u64 v[220:221], s[28:29], 0, v[132:133]
	global_load_lds_dwordx4 v[218:219], off
	v_lshl_add_u64 v[218:219], s[58:59], 0, v[134:135]
	s_add_i32 m0, s60, 0x2000
	s_nop 0
	global_load_lds_dwordx4 v[218:219], off
	v_lshl_add_u64 v[218:219], s[28:29], 0, v[128:129]
	s_mov_b32 m0, s35
	s_nop 0
	global_load_lds_dwordx4 v[218:219], off
	s_mov_b32 m0, s36
	s_nop 0
	global_load_lds_dwordx4 v[220:221], off
	ds_read_b128 v[184:187], v151 offset:16384
	ds_read_b128 v[188:191], v151 offset:17408
	ds_read_b128 v[192:195], v151 offset:18432
	ds_read_b128 v[196:199], v151 offset:19456
	ds_read_b128 v[200:203], v151 offset:20480
	ds_read_b128 v[204:207], v151 offset:21504
	ds_read_b128 v[208:211], v151 offset:22528
	ds_read_b128 v[212:215], v151 offset:23552
	s_waitcnt vmcnt(8)
	s_waitcnt lgkmcnt(0)
	s_barrier
	s_setprio 1
	s_waitcnt lgkmcnt(0)
	v_mfma_f32_16x16x32_bf16 v[60:63], v[152:155], v[184:187], v[60:63]
	v_mfma_f32_16x16x32_bf16 v[56:59], v[160:163], v[184:187], v[56:59]
	v_mfma_f32_16x16x32_bf16 v[52:55], v[152:155], v[192:195], v[52:55]
	v_mfma_f32_16x16x32_bf16 v[44:47], v[160:163], v[192:195], v[44:47]
	v_mfma_f32_16x16x32_bf16 v[36:39], v[152:155], v[200:203], v[36:39]
	v_mfma_f32_16x16x32_bf16 v[28:31], v[160:163], v[200:203], v[28:31]
	v_mfma_f32_16x16x32_bf16 v[20:23], v[152:155], v[208:211], v[20:23]
	v_mfma_f32_16x16x32_bf16 v[12:15], v[160:163], v[208:211], v[12:15]
	v_mfma_f32_16x16x32_bf16 v[60:63], v[156:159], v[188:191], v[60:63]
	v_mfma_f32_16x16x32_bf16 v[56:59], v[164:167], v[188:191], v[56:59]
	v_mfma_f32_16x16x32_bf16 v[52:55], v[156:159], v[196:199], v[52:55]
	v_mfma_f32_16x16x32_bf16 v[44:47], v[164:167], v[196:199], v[44:47]
	v_mfma_f32_16x16x32_bf16 v[36:39], v[156:159], v[204:207], v[36:39]
	v_mfma_f32_16x16x32_bf16 v[28:31], v[164:167], v[204:207], v[28:31]
	v_mfma_f32_16x16x32_bf16 v[20:23], v[156:159], v[212:215], v[20:23]
	v_mfma_f32_16x16x32_bf16 v[12:15], v[164:167], v[212:215], v[12:15]
	s_setprio 0
	s_setprio 1
	v_mfma_f32_16x16x32_bf16 v[48:51], v[168:171], v[184:187], v[48:51]
	v_mfma_f32_16x16x32_bf16 v[40:43], v[176:179], v[184:187], v[40:43]
	v_mfma_f32_16x16x32_bf16 v[32:35], v[168:171], v[192:195], v[32:35]
	v_mfma_f32_16x16x32_bf16 v[24:27], v[176:179], v[192:195], v[24:27]
	v_mfma_f32_16x16x32_bf16 v[16:19], v[168:171], v[200:203], v[16:19]
	v_mfma_f32_16x16x32_bf16 v[8:11], v[176:179], v[200:203], v[8:11]
	v_mfma_f32_16x16x32_bf16 v[4:7], v[168:171], v[208:211], v[4:7]
	v_mfma_f32_16x16x32_bf16 v[0:3], v[176:179], v[208:211], v[0:3]
	v_mfma_f32_16x16x32_bf16 v[48:51], v[172:175], v[188:191], v[48:51]
	v_mfma_f32_16x16x32_bf16 v[40:43], v[180:183], v[188:191], v[40:43]
	v_mfma_f32_16x16x32_bf16 v[32:35], v[172:175], v[196:199], v[32:35]
	v_mfma_f32_16x16x32_bf16 v[24:27], v[180:183], v[196:199], v[24:27]
	v_mfma_f32_16x16x32_bf16 v[16:19], v[172:175], v[204:207], v[16:19]
	v_mfma_f32_16x16x32_bf16 v[8:11], v[180:183], v[204:207], v[8:11]
	v_mfma_f32_16x16x32_bf16 v[4:7], v[172:175], v[212:215], v[4:7]
	v_mfma_f32_16x16x32_bf16 v[0:3], v[180:183], v[212:215], v[0:3]
	s_setprio 0
	s_barrier
	s_add_i32 s58, 0, 0x18000
	s_add_i32 s59, 0, 0x1c000
	v_add_u32_e32 v164, s58, v148
	v_add_u32_e32 v180, s59, v148
	s_add_u32 s28, s28, 0x40000
	s_addc_u32 s29, s29, 0
	s_mov_b32 m0, s37
	v_lshl_add_u64 v[222:223], s[28:29], 0, v[128:129]
	global_load_lds_dwordx4 v[222:223], off
	v_lshl_add_u64 v[222:223], s[28:29], 0, v[132:133]
	s_mov_b32 m0, s38
	s_nop 0
	global_load_lds_dwordx4 v[222:223], off
	ds_read_b128 v[152:155], v164
	ds_read_b128 v[156:159], v164 offset:1024
	ds_read_b128 v[160:163], v164 offset:2048
	ds_read_b128 v[164:167], v164 offset:3072
	ds_read_b128 v[168:171], v180
	ds_read_b128 v[172:175], v180 offset:1024
	ds_read_b128 v[176:179], v180 offset:2048
	ds_read_b128 v[180:183], v180 offset:3072
	ds_read_b128 v[184:187], v151 offset:32768
	ds_read_b128 v[188:191], v151 offset:33792
	ds_read_b128 v[192:195], v151 offset:34816
	ds_read_b128 v[196:199], v151 offset:35840
	ds_read_b128 v[200:203], v151 offset:36864
	ds_read_b128 v[204:207], v151 offset:37888
	ds_read_b128 v[208:211], v151 offset:38912
	ds_read_b128 v[212:215], v151 offset:39936
	s_waitcnt vmcnt(8)
	s_waitcnt lgkmcnt(0)
	s_barrier
	s_setprio 1
	s_waitcnt lgkmcnt(0)
	v_mfma_f32_16x16x32_bf16 v[124:127], v[152:155], v[184:187], v[124:127]
	v_mfma_f32_16x16x32_bf16 v[120:123], v[160:163], v[184:187], v[120:123]
	v_mfma_f32_16x16x32_bf16 v[116:119], v[152:155], v[192:195], v[116:119]
	v_mfma_f32_16x16x32_bf16 v[108:111], v[160:163], v[192:195], v[108:111]
	v_mfma_f32_16x16x32_bf16 v[100:103], v[152:155], v[200:203], v[100:103]
	v_mfma_f32_16x16x32_bf16 v[92:95], v[160:163], v[200:203], v[92:95]
	v_mfma_f32_16x16x32_bf16 v[84:87], v[152:155], v[208:211], v[84:87]
	v_mfma_f32_16x16x32_bf16 v[76:79], v[160:163], v[208:211], v[76:79]
	v_mfma_f32_16x16x32_bf16 v[124:127], v[156:159], v[188:191], v[124:127]
	v_mfma_f32_16x16x32_bf16 v[120:123], v[164:167], v[188:191], v[120:123]
	v_mfma_f32_16x16x32_bf16 v[116:119], v[156:159], v[196:199], v[116:119]
	v_mfma_f32_16x16x32_bf16 v[108:111], v[164:167], v[196:199], v[108:111]
	v_mfma_f32_16x16x32_bf16 v[100:103], v[156:159], v[204:207], v[100:103]
	v_mfma_f32_16x16x32_bf16 v[92:95], v[164:167], v[204:207], v[92:95]
	v_mfma_f32_16x16x32_bf16 v[84:87], v[156:159], v[212:215], v[84:87]
	v_mfma_f32_16x16x32_bf16 v[76:79], v[164:167], v[212:215], v[76:79]
	s_setprio 0
	s_setprio 1
	v_mfma_f32_16x16x32_bf16 v[112:115], v[168:171], v[184:187], v[112:115]
	v_mfma_f32_16x16x32_bf16 v[104:107], v[176:179], v[184:187], v[104:107]
	v_mfma_f32_16x16x32_bf16 v[96:99], v[168:171], v[192:195], v[96:99]
	v_mfma_f32_16x16x32_bf16 v[88:91], v[176:179], v[192:195], v[88:91]
	v_mfma_f32_16x16x32_bf16 v[80:83], v[168:171], v[200:203], v[80:83]
	v_mfma_f32_16x16x32_bf16 v[72:75], v[176:179], v[200:203], v[72:75]
	v_mfma_f32_16x16x32_bf16 v[68:71], v[168:171], v[208:211], v[68:71]
	v_mfma_f32_16x16x32_bf16 v[64:67], v[176:179], v[208:211], v[64:67]
	v_mfma_f32_16x16x32_bf16 v[112:115], v[172:175], v[188:191], v[112:115]
	v_mfma_f32_16x16x32_bf16 v[104:107], v[180:183], v[188:191], v[104:107]
	v_mfma_f32_16x16x32_bf16 v[96:99], v[172:175], v[196:199], v[96:99]
	v_mfma_f32_16x16x32_bf16 v[88:91], v[180:183], v[196:199], v[88:91]
	v_mfma_f32_16x16x32_bf16 v[80:83], v[172:175], v[204:207], v[80:83]
	v_mfma_f32_16x16x32_bf16 v[72:75], v[180:183], v[204:207], v[72:75]
	v_mfma_f32_16x16x32_bf16 v[68:71], v[172:175], v[212:215], v[68:71]
	v_mfma_f32_16x16x32_bf16 v[64:67], v[180:183], v[212:215], v[64:67]
	s_setprio 0
	s_barrier
	s_add_i32 s28, s58, s31
	v_lshl_add_u64 v[146:147], v[146:147], 0, s[10:11]
	s_mov_b32 m0, s28
	s_nop 0
	global_load_lds_dwordx4 v[146:147], off
	s_add_i32 m0, s28, 0x2000
	s_add_u32 s26, s26, 0x40080
	v_lshl_add_u64 v[146:147], v[216:217], 0, s[10:11]
	s_addc_u32 s27, s27, 0
	s_add_i32 s28, s59, s31
	global_load_lds_dwordx4 v[146:147], off
	v_lshl_add_u64 v[146:147], s[26:27], 0, v[130:131]
	s_mov_b32 m0, s28
	s_nop 0
	global_load_lds_dwordx4 v[146:147], off
	v_lshl_add_u64 v[146:147], s[26:27], 0, v[134:135]
	s_add_i32 m0, s28, 0x2000
	s_nop 0
	global_load_lds_dwordx4 v[146:147], off
	v_lshl_add_u64 v[146:147], v[218:219], 0, s[10:11]
	s_mov_b32 m0, s41
	s_nop 0
	global_load_lds_dwordx4 v[146:147], off
	v_lshl_add_u64 v[146:147], v[220:221], 0, s[10:11]
	s_mov_b32 m0, s42
	s_nop 0
	global_load_lds_dwordx4 v[146:147], off
	ds_read_b128 v[184:187], v151 offset:49152
	ds_read_b128 v[188:191], v151 offset:50176
	ds_read_b128 v[192:195], v151 offset:51200
	ds_read_b128 v[196:199], v151 offset:52224
	ds_read_b128 v[200:203], v151 offset:53248
	ds_read_b128 v[204:207], v151 offset:54272
	ds_read_b128 v[208:211], v151 offset:55296
	ds_read_b128 v[212:215], v151 offset:56320
	s_waitcnt vmcnt(8)
	s_waitcnt lgkmcnt(0)
	s_barrier
	s_setprio 1
	s_waitcnt lgkmcnt(0)
	v_mfma_f32_16x16x32_bf16 v[60:63], v[152:155], v[184:187], v[60:63]
	v_mfma_f32_16x16x32_bf16 v[56:59], v[160:163], v[184:187], v[56:59]
	v_mfma_f32_16x16x32_bf16 v[52:55], v[152:155], v[192:195], v[52:55]
	v_mfma_f32_16x16x32_bf16 v[44:47], v[160:163], v[192:195], v[44:47]
	v_mfma_f32_16x16x32_bf16 v[36:39], v[152:155], v[200:203], v[36:39]
	v_mfma_f32_16x16x32_bf16 v[28:31], v[160:163], v[200:203], v[28:31]
	v_mfma_f32_16x16x32_bf16 v[20:23], v[152:155], v[208:211], v[20:23]
	v_mfma_f32_16x16x32_bf16 v[12:15], v[160:163], v[208:211], v[12:15]
	v_mfma_f32_16x16x32_bf16 v[60:63], v[156:159], v[188:191], v[60:63]
	v_mfma_f32_16x16x32_bf16 v[56:59], v[164:167], v[188:191], v[56:59]
	v_mfma_f32_16x16x32_bf16 v[52:55], v[156:159], v[196:199], v[52:55]
	v_mfma_f32_16x16x32_bf16 v[44:47], v[164:167], v[196:199], v[44:47]
	v_mfma_f32_16x16x32_bf16 v[36:39], v[156:159], v[204:207], v[36:39]
	v_mfma_f32_16x16x32_bf16 v[28:31], v[164:167], v[204:207], v[28:31]
	v_mfma_f32_16x16x32_bf16 v[20:23], v[156:159], v[212:215], v[20:23]
	v_mfma_f32_16x16x32_bf16 v[12:15], v[164:167], v[212:215], v[12:15]
	s_setprio 0
	s_setprio 1
	v_mfma_f32_16x16x32_bf16 v[48:51], v[168:171], v[184:187], v[48:51]
	v_mfma_f32_16x16x32_bf16 v[40:43], v[176:179], v[184:187], v[40:43]
	v_mfma_f32_16x16x32_bf16 v[32:35], v[168:171], v[192:195], v[32:35]
	v_mfma_f32_16x16x32_bf16 v[24:27], v[176:179], v[192:195], v[24:27]
	v_mfma_f32_16x16x32_bf16 v[16:19], v[168:171], v[200:203], v[16:19]
	v_mfma_f32_16x16x32_bf16 v[8:11], v[176:179], v[200:203], v[8:11]
	v_mfma_f32_16x16x32_bf16 v[4:7], v[168:171], v[208:211], v[4:7]
	v_mfma_f32_16x16x32_bf16 v[0:3], v[176:179], v[208:211], v[0:3]
	v_mfma_f32_16x16x32_bf16 v[48:51], v[172:175], v[188:191], v[48:51]
	v_mfma_f32_16x16x32_bf16 v[40:43], v[180:183], v[188:191], v[40:43]
	v_mfma_f32_16x16x32_bf16 v[32:35], v[172:175], v[196:199], v[32:35]
	v_mfma_f32_16x16x32_bf16 v[24:27], v[180:183], v[196:199], v[24:27]
	v_mfma_f32_16x16x32_bf16 v[16:19], v[172:175], v[204:207], v[16:19]
	v_mfma_f32_16x16x32_bf16 v[8:11], v[180:183], v[204:207], v[8:11]
	v_mfma_f32_16x16x32_bf16 v[4:7], v[172:175], v[212:215], v[4:7]
	v_mfma_f32_16x16x32_bf16 v[0:3], v[180:183], v[212:215], v[0:3]
	s_setprio 0
	s_barrier
	s_add_i32 s57, s57, 2
	s_add_u32 s55, s55, 0x100
	s_addc_u32 s56, s56, 0
	s_add_u32 s24, s24, 0x100
	s_addc_u32 s25, s25, 0
	s_cmp_lt_u32 s57, 14
	s_cbranch_scc1 .LBB10_20
	s_andn2_b64 vcc, exec, s[12:13]
	s_cbranch_vccnz .LBB10_23
	s_barrier

.LBB12_8:
	s_ashr_i32 s15, s14, 31
	v_cmp_lt_i64_e32 vcc, s[0:1], v[142:143]
	s_lshl_b64 s[0:1], s[14:15], 19
	s_add_u32 s16, s28, s0
	s_addc_u32 s17, s29, s1
	s_and_b64 s[0:1], vcc, exec
	s_cselect_b32 s15, s17, s25
	s_cselect_b32 s54, s16, s24
	s_ashr_i32 s13, s12, 31
	s_lshl_b64 s[0:1], s[12:13], 19
	s_add_u32 s18, s30, s0
	s_addc_u32 s19, s31, s1
	s_and_b64 s[0:1], vcc, exec
	s_cselect_b32 s13, s19, s23
	s_cselect_b32 s55, s18, s22
	s_add_u32 s56, s22, 0x100
	s_addc_u32 s57, s23, 0
	s_add_u32 s22, s24, 0x40080
	s_addc_u32 s23, s25, 0
	s_mov_b32 s58, -2
	s_add_u32 s24, s22, 0xfffc0080
	s_addc_u32 s25, s23, -1
	s_cmp_eq_u32 s58, 12
	s_cselect_b32 s27, s15, s25
	s_cselect_b32 s26, s54, s24
	s_cselect_b32 s25, s13, s57
	s_cselect_b32 s24, s55, s56
	v_lshl_add_u64 v[146:147], s[22:23], 0, v[140:141]
	s_add_i32 m0, s36, 0xc000
	s_nop 0
	global_load_lds_dwordx4 v[146:147], off
	v_lshl_add_u64 v[146:147], s[22:23], 0, v[138:139]
	s_add_i32 m0, s36, 0xe000
	s_nop 0
	global_load_lds_dwordx4 v[146:147], off
	ds_read_b128 v[152:155], v149
	ds_read_b128 v[156:159], v149 offset:1024
	ds_read_b128 v[160:163], v149 offset:2048
	ds_read_b128 v[164:167], v149 offset:3072
	ds_read_b128 v[168:171], v150
	ds_read_b128 v[172:175], v150 offset:1024
	ds_read_b128 v[176:179], v150 offset:2048
	ds_read_b128 v[180:183], v150 offset:3072
	ds_read_b128 v[184:187], v151
	ds_read_b128 v[188:191], v151 offset:1024
	ds_read_b128 v[192:195], v151 offset:2048
	ds_read_b128 v[196:199], v151 offset:3072
	ds_read_b128 v[200:203], v151 offset:4096
	ds_read_b128 v[204:207], v151 offset:5120
	ds_read_b128 v[208:211], v151 offset:6144
	ds_read_b128 v[212:215], v151 offset:7168
	s_waitcnt vmcnt(8)
	s_waitcnt lgkmcnt(0)
	s_barrier
	s_setprio 1
	s_waitcnt lgkmcnt(0)
	v_mfma_f32_16x16x32_bf16 v[124:127], v[152:155], v[184:187], 0
	v_mfma_f32_16x16x32_bf16 v[120:123], v[160:163], v[184:187], 0
	v_mfma_f32_16x16x32_bf16 v[108:111], v[152:155], v[192:195], 0
	v_mfma_f32_16x16x32_bf16 v[104:107], v[160:163], v[192:195], 0
	v_mfma_f32_16x16x32_bf16 v[92:95], v[152:155], v[200:203], 0
	v_mfma_f32_16x16x32_bf16 v[88:91], v[160:163], v[200:203], 0
	v_mfma_f32_16x16x32_bf16 v[76:79], v[152:155], v[208:211], 0
	v_mfma_f32_16x16x32_bf16 v[72:75], v[160:163], v[208:211], 0
	v_mfma_f32_16x16x32_bf16 v[124:127], v[156:159], v[188:191], v[124:127]
	v_mfma_f32_16x16x32_bf16 v[120:123], v[164:167], v[188:191], v[120:123]
	v_mfma_f32_16x16x32_bf16 v[108:111], v[156:159], v[196:199], v[108:111]
	v_mfma_f32_16x16x32_bf16 v[104:107], v[164:167], v[196:199], v[104:107]
	v_mfma_f32_16x16x32_bf16 v[92:95], v[156:159], v[204:207], v[92:95]
	v_mfma_f32_16x16x32_bf16 v[88:91], v[164:167], v[204:207], v[88:91]
	v_mfma_f32_16x16x32_bf16 v[76:79], v[156:159], v[212:215], v[76:79]
	v_mfma_f32_16x16x32_bf16 v[72:75], v[164:167], v[212:215], v[72:75]
	s_setprio 0
	s_setprio 1
	v_mfma_f32_16x16x32_bf16 v[116:119], v[168:171], v[184:187], 0
	v_mfma_f32_16x16x32_bf16 v[112:115], v[176:179], v[184:187], 0
	v_mfma_f32_16x16x32_bf16 v[100:103], v[168:171], v[192:195], 0
	v_mfma_f32_16x16x32_bf16 v[96:99], v[176:179], v[192:195], 0
	v_mfma_f32_16x16x32_bf16 v[84:87], v[168:171], v[200:203], 0
	v_mfma_f32_16x16x32_bf16 v[80:83], v[176:179], v[200:203], 0
	v_mfma_f32_16x16x32_bf16 v[68:71], v[168:171], v[208:211], 0
	v_mfma_f32_16x16x32_bf16 v[64:67], v[176:179], v[208:211], 0
	v_mfma_f32_16x16x32_bf16 v[116:119], v[172:175], v[188:191], v[116:119]
	v_mfma_f32_16x16x32_bf16 v[112:115], v[180:183], v[188:191], v[112:115]
	v_mfma_f32_16x16x32_bf16 v[100:103], v[172:175], v[196:199], v[100:103]
	v_mfma_f32_16x16x32_bf16 v[96:99], v[180:183], v[196:199], v[96:99]
	v_mfma_f32_16x16x32_bf16 v[84:87], v[172:175], v[204:207], v[84:87]
	v_mfma_f32_16x16x32_bf16 v[80:83], v[180:183], v[204:207], v[80:83]
	v_mfma_f32_16x16x32_bf16 v[68:71], v[172:175], v[212:215], v[68:71]
	v_mfma_f32_16x16x32_bf16 v[64:67], v[180:183], v[212:215], v[64:67]
	s_setprio 0
	s_barrier
	s_add_i32 s59, s44, s33
	v_lshl_add_u64 v[146:147], s[24:25], 0, v[132:133]
	s_mov_b32 m0, s59
	s_nop 0
	global_load_lds_dwordx4 v[146:147], off
	s_add_i32 m0, s59, 0x2000
	s_add_u32 s60, s24, 0x40000
	v_lshl_add_u64 v[216:217], s[24:25], 0, v[128:129]
	s_addc_u32 s61, s25, 0
	s_add_i32 s59, s45, s33
	global_load_lds_dwordx4 v[216:217], off
	v_lshl_add_u64 v[218:219], s[60:61], 0, v[132:133]
	s_mov_b32 m0, s59
	v_lshl_add_u64 v[220:221], s[26:27], 0, v[130:131]
	global_load_lds_dwordx4 v[218:219], off
	v_lshl_add_u64 v[218:219], s[60:61], 0, v[128:129]
	s_add_i32 m0, s59, 0x2000
	s_nop 0
	global_load_lds_dwordx4 v[218:219], off
	v_lshl_add_u64 v[218:219], s[26:27], 0, v[134:135]
	s_mov_b32 m0, s36
	s_nop 0
	global_load_lds_dwordx4 v[218:219], off
	s_mov_b32 m0, s37
	s_nop 0
	global_load_lds_dwordx4 v[220:221], off
	ds_read_b128 v[184:187], v151 offset:16384
	ds_read_b128 v[188:191], v151 offset:17408
	ds_read_b128 v[192:195], v151 offset:18432
	ds_read_b128 v[196:199], v151 offset:19456
	ds_read_b128 v[200:203], v151 offset:20480
	ds_read_b128 v[204:207], v151 offset:21504
	ds_read_b128 v[208:211], v151 offset:22528
	ds_read_b128 v[212:215], v151 offset:23552
	s_waitcnt vmcnt(8)
	s_waitcnt lgkmcnt(0)
	s_barrier
	s_setprio 1
	s_waitcnt lgkmcnt(0)
	v_mfma_f32_16x16x32_bf16 v[60:63], v[152:155], v[184:187], 0
	v_mfma_f32_16x16x32_bf16 v[56:59], v[160:163], v[184:187], 0
	v_mfma_f32_16x16x32_bf16 v[44:47], v[152:155], v[192:195], 0
	v_mfma_f32_16x16x32_bf16 v[40:43], v[160:163], v[192:195], 0
	v_mfma_f32_16x16x32_bf16 v[28:31], v[152:155], v[200:203], 0
	v_mfma_f32_16x16x32_bf16 v[24:27], v[160:163], v[200:203], 0
	v_mfma_f32_16x16x32_bf16 v[12:15], v[152:155], v[208:211], 0
	v_mfma_f32_16x16x32_bf16 v[8:11], v[160:163], v[208:211], 0
	v_mfma_f32_16x16x32_bf16 v[60:63], v[156:159], v[188:191], v[60:63]
	v_mfma_f32_16x16x32_bf16 v[56:59], v[164:167], v[188:191], v[56:59]
	v_mfma_f32_16x16x32_bf16 v[44:47], v[156:159], v[196:199], v[44:47]
	v_mfma_f32_16x16x32_bf16 v[40:43], v[164:167], v[196:199], v[40:43]
	v_mfma_f32_16x16x32_bf16 v[28:31], v[156:159], v[204:207], v[28:31]
	v_mfma_f32_16x16x32_bf16 v[24:27], v[164:167], v[204:207], v[24:27]
	v_mfma_f32_16x16x32_bf16 v[12:15], v[156:159], v[212:215], v[12:15]
	v_mfma_f32_16x16x32_bf16 v[8:11], v[164:167], v[212:215], v[8:11]
	s_setprio 0
	s_setprio 1
	v_mfma_f32_16x16x32_bf16 v[52:55], v[168:171], v[184:187], 0
	v_mfma_f32_16x16x32_bf16 v[48:51], v[176:179], v[184:187], 0
	v_mfma_f32_16x16x32_bf16 v[36:39], v[168:171], v[192:195], 0
	v_mfma_f32_16x16x32_bf16 v[32:35], v[176:179], v[192:195], 0
	v_mfma_f32_16x16x32_bf16 v[20:23], v[168:171], v[200:203], 0
	v_mfma_f32_16x16x32_bf16 v[16:19], v[176:179], v[200:203], 0
	v_mfma_f32_16x16x32_bf16 v[4:7], v[168:171], v[208:211], 0
	v_mfma_f32_16x16x32_bf16 v[0:3], v[176:179], v[208:211], 0
	v_mfma_f32_16x16x32_bf16 v[52:55], v[172:175], v[188:191], v[52:55]
	v_mfma_f32_16x16x32_bf16 v[48:51], v[180:183], v[188:191], v[48:51]
	v_mfma_f32_16x16x32_bf16 v[36:39], v[172:175], v[196:199], v[36:39]
	v_mfma_f32_16x16x32_bf16 v[32:35], v[180:183], v[196:199], v[32:35]
	v_mfma_f32_16x16x32_bf16 v[20:23], v[172:175], v[204:207], v[20:23]
	v_mfma_f32_16x16x32_bf16 v[16:19], v[180:183], v[204:207], v[16:19]
	v_mfma_f32_16x16x32_bf16 v[4:7], v[172:175], v[212:215], v[4:7]
	v_mfma_f32_16x16x32_bf16 v[0:3], v[180:183], v[212:215], v[0:3]
	s_setprio 0
	s_barrier
	s_add_i32 s59, 0, 0x18000
	s_add_i32 s60, 0, 0x1c000
	v_add_u32_e32 v164, s59, v148
	v_add_u32_e32 v180, s60, v148
	s_add_u32 s26, s26, 0x40000
	s_addc_u32 s27, s27, 0
	s_mov_b32 m0, s38
	v_lshl_add_u64 v[222:223], s[26:27], 0, v[134:135]
	global_load_lds_dwordx4 v[222:223], off
	v_lshl_add_u64 v[222:223], s[26:27], 0, v[130:131]
	s_mov_b32 m0, s39
	s_nop 0
	global_load_lds_dwordx4 v[222:223], off
	ds_read_b128 v[152:155], v164
	ds_read_b128 v[156:159], v164 offset:1024
	ds_read_b128 v[160:163], v164 offset:2048
	ds_read_b128 v[164:167], v164 offset:3072
	ds_read_b128 v[168:171], v180
	ds_read_b128 v[172:175], v180 offset:1024
	ds_read_b128 v[176:179], v180 offset:2048
	ds_read_b128 v[180:183], v180 offset:3072
	ds_read_b128 v[184:187], v151 offset:32768
	ds_read_b128 v[188:191], v151 offset:33792
	ds_read_b128 v[192:195], v151 offset:34816
	ds_read_b128 v[196:199], v151 offset:35840
	ds_read_b128 v[200:203], v151 offset:36864
	ds_read_b128 v[204:207], v151 offset:37888
	ds_read_b128 v[208:211], v151 offset:38912
	ds_read_b128 v[212:215], v151 offset:39936
	s_waitcnt vmcnt(8)
	s_waitcnt lgkmcnt(0)
	s_barrier
	s_setprio 1
	s_waitcnt lgkmcnt(0)
	v_mfma_f32_16x16x32_bf16 v[124:127], v[152:155], v[184:187], v[124:127]
	v_mfma_f32_16x16x32_bf16 v[120:123], v[160:163], v[184:187], v[120:123]
	v_mfma_f32_16x16x32_bf16 v[108:111], v[152:155], v[192:195], v[108:111]
	v_mfma_f32_16x16x32_bf16 v[104:107], v[160:163], v[192:195], v[104:107]
	v_mfma_f32_16x16x32_bf16 v[92:95], v[152:155], v[200:203], v[92:95]
	v_mfma_f32_16x16x32_bf16 v[88:91], v[160:163], v[200:203], v[88:91]
	v_mfma_f32_16x16x32_bf16 v[76:79], v[152:155], v[208:211], v[76:79]
	v_mfma_f32_16x16x32_bf16 v[72:75], v[160:163], v[208:211], v[72:75]
	v_mfma_f32_16x16x32_bf16 v[124:127], v[156:159], v[188:191], v[124:127]
	v_mfma_f32_16x16x32_bf16 v[120:123], v[164:167], v[188:191], v[120:123]
	v_mfma_f32_16x16x32_bf16 v[108:111], v[156:159], v[196:199], v[108:111]
	v_mfma_f32_16x16x32_bf16 v[104:107], v[164:167], v[196:199], v[104:107]
	v_mfma_f32_16x16x32_bf16 v[92:95], v[156:159], v[204:207], v[92:95]
	v_mfma_f32_16x16x32_bf16 v[88:91], v[164:167], v[204:207], v[88:91]
	v_mfma_f32_16x16x32_bf16 v[76:79], v[156:159], v[212:215], v[76:79]
	v_mfma_f32_16x16x32_bf16 v[72:75], v[164:167], v[212:215], v[72:75]
	s_setprio 0
	s_setprio 1
	v_mfma_f32_16x16x32_bf16 v[116:119], v[168:171], v[184:187], v[116:119]
	v_mfma_f32_16x16x32_bf16 v[112:115], v[176:179], v[184:187], v[112:115]
	v_mfma_f32_16x16x32_bf16 v[100:103], v[168:171], v[192:195], v[100:103]
	v_mfma_f32_16x16x32_bf16 v[96:99], v[176:179], v[192:195], v[96:99]
	v_mfma_f32_16x16x32_bf16 v[84:87], v[168:171], v[200:203], v[84:87]
	v_mfma_f32_16x16x32_bf16 v[80:83], v[176:179], v[200:203], v[80:83]
	v_mfma_f32_16x16x32_bf16 v[68:71], v[168:171], v[208:211], v[68:71]
	v_mfma_f32_16x16x32_bf16 v[64:67], v[176:179], v[208:211], v[64:67]
	v_mfma_f32_16x16x32_bf16 v[116:119], v[172:175], v[188:191], v[116:119]
	v_mfma_f32_16x16x32_bf16 v[112:115], v[180:183], v[188:191], v[112:115]
	v_mfma_f32_16x16x32_bf16 v[100:103], v[172:175], v[196:199], v[100:103]
	v_mfma_f32_16x16x32_bf16 v[96:99], v[180:183], v[196:199], v[96:99]
	v_mfma_f32_16x16x32_bf16 v[84:87], v[172:175], v[204:207], v[84:87]
	v_mfma_f32_16x16x32_bf16 v[80:83], v[180:183], v[204:207], v[80:83]
	v_mfma_f32_16x16x32_bf16 v[68:71], v[172:175], v[212:215], v[68:71]
	v_mfma_f32_16x16x32_bf16 v[64:67], v[180:183], v[212:215], v[64:67]
	s_setprio 0
	s_barrier
	s_add_i32 s26, s59, s33
	v_lshl_add_u64 v[146:147], v[146:147], 0, s[8:9]
	s_mov_b32 m0, s26
	s_nop 0
	global_load_lds_dwordx4 v[146:147], off
	s_add_i32 m0, s26, 0x2000
	s_add_u32 s24, s24, 0x40080
	v_lshl_add_u64 v[146:147], v[216:217], 0, s[8:9]
	s_addc_u32 s25, s25, 0
	s_add_i32 s26, s60, s33
	global_load_lds_dwordx4 v[146:147], off
	v_lshl_add_u64 v[146:147], s[24:25], 0, v[132:133]
	s_mov_b32 m0, s26
	s_nop 0
	global_load_lds_dwordx4 v[146:147], off
	v_lshl_add_u64 v[146:147], s[24:25], 0, v[128:129]
	s_add_i32 m0, s26, 0x2000
	s_nop 0
	global_load_lds_dwordx4 v[146:147], off
	v_lshl_add_u64 v[146:147], v[218:219], 0, s[8:9]
	s_mov_b32 m0, s41
	s_nop 0
	global_load_lds_dwordx4 v[146:147], off
	v_lshl_add_u64 v[146:147], v[220:221], 0, s[8:9]
	s_mov_b32 m0, s42
	s_nop 0
	global_load_lds_dwordx4 v[146:147], off
	ds_read_b128 v[184:187], v151 offset:49152
	ds_read_b128 v[188:191], v151 offset:50176
	ds_read_b128 v[192:195], v151 offset:51200
	ds_read_b128 v[196:199], v151 offset:52224
	ds_read_b128 v[200:203], v151 offset:53248
	ds_read_b128 v[204:207], v151 offset:54272
	ds_read_b128 v[208:211], v151 offset:55296
	ds_read_b128 v[212:215], v151 offset:56320
	s_waitcnt vmcnt(8)
	s_waitcnt lgkmcnt(0)
	s_barrier
	s_setprio 1
	s_waitcnt lgkmcnt(0)
	v_mfma_f32_16x16x32_bf16 v[60:63], v[152:155], v[184:187], v[60:63]
	v_mfma_f32_16x16x32_bf16 v[56:59], v[160:163], v[184:187], v[56:59]
	v_mfma_f32_16x16x32_bf16 v[44:47], v[152:155], v[192:195], v[44:47]
	v_mfma_f32_16x16x32_bf16 v[40:43], v[160:163], v[192:195], v[40:43]
	v_mfma_f32_16x16x32_bf16 v[28:31], v[152:155], v[200:203], v[28:31]
	v_mfma_f32_16x16x32_bf16 v[24:27], v[160:163], v[200:203], v[24:27]
	v_mfma_f32_16x16x32_bf16 v[12:15], v[152:155], v[208:211], v[12:15]
	v_mfma_f32_16x16x32_bf16 v[8:11], v[160:163], v[208:211], v[8:11]
	v_mfma_f32_16x16x32_bf16 v[60:63], v[156:159], v[188:191], v[60:63]
	v_mfma_f32_16x16x32_bf16 v[56:59], v[164:167], v[188:191], v[56:59]
	v_mfma_f32_16x16x32_bf16 v[44:47], v[156:159], v[196:199], v[44:47]
	v_mfma_f32_16x16x32_bf16 v[40:43], v[164:167], v[196:199], v[40:43]
	v_mfma_f32_16x16x32_bf16 v[28:31], v[156:159], v[204:207], v[28:31]
	v_mfma_f32_16x16x32_bf16 v[24:27], v[164:167], v[204:207], v[24:27]
	v_mfma_f32_16x16x32_bf16 v[12:15], v[156:159], v[212:215], v[12:15]
	v_mfma_f32_16x16x32_bf16 v[8:11], v[164:167], v[212:215], v[8:11]
	s_setprio 0
	s_setprio 1
	v_mfma_f32_16x16x32_bf16 v[52:55], v[168:171], v[184:187], v[52:55]
	v_mfma_f32_16x16x32_bf16 v[48:51], v[176:179], v[184:187], v[48:51]
	v_mfma_f32_16x16x32_bf16 v[36:39], v[168:171], v[192:195], v[36:39]
	v_mfma_f32_16x16x32_bf16 v[32:35], v[176:179], v[192:195], v[32:35]
	v_mfma_f32_16x16x32_bf16 v[20:23], v[168:171], v[200:203], v[20:23]
	v_mfma_f32_16x16x32_bf16 v[16:19], v[176:179], v[200:203], v[16:19]
	v_mfma_f32_16x16x32_bf16 v[4:7], v[168:171], v[208:211], v[4:7]
	v_mfma_f32_16x16x32_bf16 v[0:3], v[176:179], v[208:211], v[0:3]
	v_mfma_f32_16x16x32_bf16 v[52:55], v[172:175], v[188:191], v[52:55]
	v_mfma_f32_16x16x32_bf16 v[48:51], v[180:183], v[188:191], v[48:51]
	v_mfma_f32_16x16x32_bf16 v[36:39], v[172:175], v[196:199], v[36:39]
	v_mfma_f32_16x16x32_bf16 v[32:35], v[180:183], v[196:199], v[32:35]
	v_mfma_f32_16x16x32_bf16 v[20:23], v[172:175], v[204:207], v[20:23]
	v_mfma_f32_16x16x32_bf16 v[16:19], v[180:183], v[204:207], v[16:19]
	v_mfma_f32_16x16x32_bf16 v[4:7], v[172:175], v[212:215], v[4:7]
	v_mfma_f32_16x16x32_bf16 v[0:3], v[180:183], v[212:215], v[0:3]
	s_setprio 0
	s_barrier
	s_add_i32 s58, s58, 2
	s_add_u32 s56, s56, 0x100
	s_addc_u32 s57, s57, 0
	s_add_u32 s22, s22, 0x100
	s_addc_u32 s23, s23, 0
	s_cmp_lt_u32 s58, 14
.LBB12_9:
	s_add_u32 s24, s22, 0xfffc0080
	s_addc_u32 s25, s23, -1
	s_cmp_eq_u32 s58, 12
	s_cselect_b32 s27, s15, s25
	s_cselect_b32 s26, s54, s24
	s_cselect_b32 s25, s13, s57
	s_cselect_b32 s24, s55, s56
	v_lshl_add_u64 v[146:147], s[22:23], 0, v[140:141]
	s_add_i32 m0, s36, 0xc000
	s_nop 0
	global_load_lds_dwordx4 v[146:147], off
	v_lshl_add_u64 v[146:147], s[22:23], 0, v[138:139]
	s_add_i32 m0, s36, 0xe000
	s_nop 0
	global_load_lds_dwordx4 v[146:147], off
	ds_read_b128 v[152:155], v149
	ds_read_b128 v[156:159], v149 offset:1024
	ds_read_b128 v[160:163], v149 offset:2048
	ds_read_b128 v[164:167], v149 offset:3072
	ds_read_b128 v[168:171], v150
	ds_read_b128 v[172:175], v150 offset:1024
	ds_read_b128 v[176:179], v150 offset:2048
	ds_read_b128 v[180:183], v150 offset:3072
	ds_read_b128 v[184:187], v151
	ds_read_b128 v[188:191], v151 offset:1024
	ds_read_b128 v[192:195], v151 offset:2048
	ds_read_b128 v[196:199], v151 offset:3072
	ds_read_b128 v[200:203], v151 offset:4096
	ds_read_b128 v[204:207], v151 offset:5120
	ds_read_b128 v[208:211], v151 offset:6144
	ds_read_b128 v[212:215], v151 offset:7168
	s_waitcnt vmcnt(8)
	s_waitcnt lgkmcnt(0)
	s_barrier
	s_setprio 1
	s_waitcnt lgkmcnt(0)
	v_mfma_f32_16x16x32_bf16 v[124:127], v[152:155], v[184:187], v[124:127]
	v_mfma_f32_16x16x32_bf16 v[120:123], v[160:163], v[184:187], v[120:123]
	v_mfma_f32_16x16x32_bf16 v[108:111], v[152:155], v[192:195], v[108:111]
	v_mfma_f32_16x16x32_bf16 v[104:107], v[160:163], v[192:195], v[104:107]
	v_mfma_f32_16x16x32_bf16 v[92:95], v[152:155], v[200:203], v[92:95]
	v_mfma_f32_16x16x32_bf16 v[88:91], v[160:163], v[200:203], v[88:91]
	v_mfma_f32_16x16x32_bf16 v[76:79], v[152:155], v[208:211], v[76:79]
	v_mfma_f32_16x16x32_bf16 v[72:75], v[160:163], v[208:211], v[72:75]
	v_mfma_f32_16x16x32_bf16 v[124:127], v[156:159], v[188:191], v[124:127]
	v_mfma_f32_16x16x32_bf16 v[120:123], v[164:167], v[188:191], v[120:123]
	v_mfma_f32_16x16x32_bf16 v[108:111], v[156:159], v[196:199], v[108:111]
	v_mfma_f32_16x16x32_bf16 v[104:107], v[164:167], v[196:199], v[104:107]
	v_mfma_f32_16x16x32_bf16 v[92:95], v[156:159], v[204:207], v[92:95]
	v_mfma_f32_16x16x32_bf16 v[88:91], v[164:167], v[204:207], v[88:91]
	v_mfma_f32_16x16x32_bf16 v[76:79], v[156:159], v[212:215], v[76:79]
	v_mfma_f32_16x16x32_bf16 v[72:75], v[164:167], v[212:215], v[72:75]
	s_setprio 0
	s_setprio 1
	v_mfma_f32_16x16x32_bf16 v[116:119], v[168:171], v[184:187], v[116:119]
	v_mfma_f32_16x16x32_bf16 v[112:115], v[176:179], v[184:187], v[112:115]
	v_mfma_f32_16x16x32_bf16 v[100:103], v[168:171], v[192:195], v[100:103]
	v_mfma_f32_16x16x32_bf16 v[96:99], v[176:179], v[192:195], v[96:99]
	v_mfma_f32_16x16x32_bf16 v[84:87], v[168:171], v[200:203], v[84:87]
	v_mfma_f32_16x16x32_bf16 v[80:83], v[176:179], v[200:203], v[80:83]
	v_mfma_f32_16x16x32_bf16 v[68:71], v[168:171], v[208:211], v[68:71]
	v_mfma_f32_16x16x32_bf16 v[64:67], v[176:179], v[208:211], v[64:67]
	v_mfma_f32_16x16x32_bf16 v[116:119], v[172:175], v[188:191], v[116:119]
	v_mfma_f32_16x16x32_bf16 v[112:115], v[180:183], v[188:191], v[112:115]
	v_mfma_f32_16x16x32_bf16 v[100:103], v[172:175], v[196:199], v[100:103]
	v_mfma_f32_16x16x32_bf16 v[96:99], v[180:183], v[196:199], v[96:99]
	v_mfma_f32_16x16x32_bf16 v[84:87], v[172:175], v[204:207], v[84:87]
	v_mfma_f32_16x16x32_bf16 v[80:83], v[180:183], v[204:207], v[80:83]
	v_mfma_f32_16x16x32_bf16 v[68:71], v[172:175], v[212:215], v[68:71]
	v_mfma_f32_16x16x32_bf16 v[64:67], v[180:183], v[212:215], v[64:67]
	s_setprio 0
	s_barrier
	s_add_i32 s59, s44, s33
	v_lshl_add_u64 v[146:147], s[24:25], 0, v[132:133]
	s_mov_b32 m0, s59
	s_nop 0
	global_load_lds_dwordx4 v[146:147], off
	s_add_i32 m0, s59, 0x2000
	s_add_u32 s60, s24, 0x40000
	v_lshl_add_u64 v[216:217], s[24:25], 0, v[128:129]
	s_addc_u32 s61, s25, 0
	s_add_i32 s59, s45, s33
	global_load_lds_dwordx4 v[216:217], off
	v_lshl_add_u64 v[218:219], s[60:61], 0, v[132:133]
	s_mov_b32 m0, s59
	v_lshl_add_u64 v[220:221], s[26:27], 0, v[130:131]
	global_load_lds_dwordx4 v[218:219], off
	v_lshl_add_u64 v[218:219], s[60:61], 0, v[128:129]
	s_add_i32 m0, s59, 0x2000
	s_nop 0
	global_load_lds_dwordx4 v[218:219], off
	v_lshl_add_u64 v[218:219], s[26:27], 0, v[134:135]
	s_mov_b32 m0, s36
	s_nop 0
	global_load_lds_dwordx4 v[218:219], off
	s_mov_b32 m0, s37
	s_nop 0
	global_load_lds_dwordx4 v[220:221], off
	ds_read_b128 v[184:187], v151 offset:16384
	ds_read_b128 v[188:191], v151 offset:17408
	ds_read_b128 v[192:195], v151 offset:18432
	ds_read_b128 v[196:199], v151 offset:19456
	ds_read_b128 v[200:203], v151 offset:20480
	ds_read_b128 v[204:207], v151 offset:21504
	ds_read_b128 v[208:211], v151 offset:22528
	ds_read_b128 v[212:215], v151 offset:23552
	s_waitcnt vmcnt(8)
	s_waitcnt lgkmcnt(0)
	s_barrier
	s_setprio 1
	s_waitcnt lgkmcnt(0)
	v_mfma_f32_16x16x32_bf16 v[60:63], v[152:155], v[184:187], v[60:63]
	v_mfma_f32_16x16x32_bf16 v[56:59], v[160:163], v[184:187], v[56:59]
	v_mfma_f32_16x16x32_bf16 v[44:47], v[152:155], v[192:195], v[44:47]
	v_mfma_f32_16x16x32_bf16 v[40:43], v[160:163], v[192:195], v[40:43]
	v_mfma_f32_16x16x32_bf16 v[28:31], v[152:155], v[200:203], v[28:31]
	v_mfma_f32_16x16x32_bf16 v[24:27], v[160:163], v[200:203], v[24:27]
	v_mfma_f32_16x16x32_bf16 v[12:15], v[152:155], v[208:211], v[12:15]
	v_mfma_f32_16x16x32_bf16 v[8:11], v[160:163], v[208:211], v[8:11]
	v_mfma_f32_16x16x32_bf16 v[60:63], v[156:159], v[188:191], v[60:63]
	v_mfma_f32_16x16x32_bf16 v[56:59], v[164:167], v[188:191], v[56:59]
	v_mfma_f32_16x16x32_bf16 v[44:47], v[156:159], v[196:199], v[44:47]
	v_mfma_f32_16x16x32_bf16 v[40:43], v[164:167], v[196:199], v[40:43]
	v_mfma_f32_16x16x32_bf16 v[28:31], v[156:159], v[204:207], v[28:31]
	v_mfma_f32_16x16x32_bf16 v[24:27], v[164:167], v[204:207], v[24:27]
	v_mfma_f32_16x16x32_bf16 v[12:15], v[156:159], v[212:215], v[12:15]
	v_mfma_f32_16x16x32_bf16 v[8:11], v[164:167], v[212:215], v[8:11]
	s_setprio 0
	s_setprio 1
	v_mfma_f32_16x16x32_bf16 v[52:55], v[168:171], v[184:187], v[52:55]
	v_mfma_f32_16x16x32_bf16 v[48:51], v[176:179], v[184:187], v[48:51]
	v_mfma_f32_16x16x32_bf16 v[36:39], v[168:171], v[192:195], v[36:39]
	v_mfma_f32_16x16x32_bf16 v[32:35], v[176:179], v[192:195], v[32:35]
	v_mfma_f32_16x16x32_bf16 v[20:23], v[168:171], v[200:203], v[20:23]
	v_mfma_f32_16x16x32_bf16 v[16:19], v[176:179], v[200:203], v[16:19]
	v_mfma_f32_16x16x32_bf16 v[4:7], v[168:171], v[208:211], v[4:7]
	v_mfma_f32_16x16x32_bf16 v[0:3], v[176:179], v[208:211], v[0:3]
	v_mfma_f32_16x16x32_bf16 v[52:55], v[172:175], v[188:191], v[52:55]
	v_mfma_f32_16x16x32_bf16 v[48:51], v[180:183], v[188:191], v[48:51]
	v_mfma_f32_16x16x32_bf16 v[36:39], v[172:175], v[196:199], v[36:39]
	v_mfma_f32_16x16x32_bf16 v[32:35], v[180:183], v[196:199], v[32:35]
	v_mfma_f32_16x16x32_bf16 v[20:23], v[172:175], v[204:207], v[20:23]
	v_mfma_f32_16x16x32_bf16 v[16:19], v[180:183], v[204:207], v[16:19]
	v_mfma_f32_16x16x32_bf16 v[4:7], v[172:175], v[212:215], v[4:7]
	v_mfma_f32_16x16x32_bf16 v[0:3], v[180:183], v[212:215], v[0:3]
	s_setprio 0
	s_barrier
	s_add_i32 s59, 0, 0x18000
	s_add_i32 s60, 0, 0x1c000
	v_add_u32_e32 v164, s59, v148
	v_add_u32_e32 v180, s60, v148
	s_add_u32 s26, s26, 0x40000
	s_addc_u32 s27, s27, 0
	s_mov_b32 m0, s38
	v_lshl_add_u64 v[222:223], s[26:27], 0, v[134:135]
	global_load_lds_dwordx4 v[222:223], off
	v_lshl_add_u64 v[222:223], s[26:27], 0, v[130:131]
	s_mov_b32 m0, s39
	s_nop 0
	global_load_lds_dwordx4 v[222:223], off
	ds_read_b128 v[152:155], v164
	ds_read_b128 v[156:159], v164 offset:1024
	ds_read_b128 v[160:163], v164 offset:2048
	ds_read_b128 v[164:167], v164 offset:3072
	ds_read_b128 v[168:171], v180
	ds_read_b128 v[172:175], v180 offset:1024
	ds_read_b128 v[176:179], v180 offset:2048
	ds_read_b128 v[180:183], v180 offset:3072
	ds_read_b128 v[184:187], v151 offset:32768
	ds_read_b128 v[188:191], v151 offset:33792
	ds_read_b128 v[192:195], v151 offset:34816
	ds_read_b128 v[196:199], v151 offset:35840
	ds_read_b128 v[200:203], v151 offset:36864
	ds_read_b128 v[204:207], v151 offset:37888
	ds_read_b128 v[208:211], v151 offset:38912
	ds_read_b128 v[212:215], v151 offset:39936
	s_waitcnt vmcnt(8)
	s_waitcnt lgkmcnt(0)
	s_barrier
	s_setprio 1
	s_waitcnt lgkmcnt(0)
	v_mfma_f32_16x16x32_bf16 v[124:127], v[152:155], v[184:187], v[124:127]
	v_mfma_f32_16x16x32_bf16 v[120:123], v[160:163], v[184:187], v[120:123]
	v_mfma_f32_16x16x32_bf16 v[108:111], v[152:155], v[192:195], v[108:111]
	v_mfma_f32_16x16x32_bf16 v[104:107], v[160:163], v[192:195], v[104:107]
	v_mfma_f32_16x16x32_bf16 v[92:95], v[152:155], v[200:203], v[92:95]
	v_mfma_f32_16x16x32_bf16 v[88:91], v[160:163], v[200:203], v[88:91]
	v_mfma_f32_16x16x32_bf16 v[76:79], v[152:155], v[208:211], v[76:79]
	v_mfma_f32_16x16x32_bf16 v[72:75], v[160:163], v[208:211], v[72:75]
	v_mfma_f32_16x16x32_bf16 v[124:127], v[156:159], v[188:191], v[124:127]
	v_mfma_f32_16x16x32_bf16 v[120:123], v[164:167], v[188:191], v[120:123]
	v_mfma_f32_16x16x32_bf16 v[108:111], v[156:159], v[196:199], v[108:111]
	v_mfma_f32_16x16x32_bf16 v[104:107], v[164:167], v[196:199], v[104:107]
	v_mfma_f32_16x16x32_bf16 v[92:95], v[156:159], v[204:207], v[92:95]
	v_mfma_f32_16x16x32_bf16 v[88:91], v[164:167], v[204:207], v[88:91]
	v_mfma_f32_16x16x32_bf16 v[76:79], v[156:159], v[212:215], v[76:79]
	v_mfma_f32_16x16x32_bf16 v[72:75], v[164:167], v[212:215], v[72:75]
	s_setprio 0
	s_setprio 1
	v_mfma_f32_16x16x32_bf16 v[116:119], v[168:171], v[184:187], v[116:119]
	v_mfma_f32_16x16x32_bf16 v[112:115], v[176:179], v[184:187], v[112:115]
	v_mfma_f32_16x16x32_bf16 v[100:103], v[168:171], v[192:195], v[100:103]
	v_mfma_f32_16x16x32_bf16 v[96:99], v[176:179], v[192:195], v[96:99]
	v_mfma_f32_16x16x32_bf16 v[84:87], v[168:171], v[200:203], v[84:87]
	v_mfma_f32_16x16x32_bf16 v[80:83], v[176:179], v[200:203], v[80:83]
	v_mfma_f32_16x16x32_bf16 v[68:71], v[168:171], v[208:211], v[68:71]
	v_mfma_f32_16x16x32_bf16 v[64:67], v[176:179], v[208:211], v[64:67]
	v_mfma_f32_16x16x32_bf16 v[116:119], v[172:175], v[188:191], v[116:119]
	v_mfma_f32_16x16x32_bf16 v[112:115], v[180:183], v[188:191], v[112:115]
	v_mfma_f32_16x16x32_bf16 v[100:103], v[172:175], v[196:199], v[100:103]
	v_mfma_f32_16x16x32_bf16 v[96:99], v[180:183], v[196:199], v[96:99]
	v_mfma_f32_16x16x32_bf16 v[84:87], v[172:175], v[204:207], v[84:87]
	v_mfma_f32_16x16x32_bf16 v[80:83], v[180:183], v[204:207], v[80:83]
	v_mfma_f32_16x16x32_bf16 v[68:71], v[172:175], v[212:215], v[68:71]
	v_mfma_f32_16x16x32_bf16 v[64:67], v[180:183], v[212:215], v[64:67]
	s_setprio 0
	s_barrier
	s_add_i32 s26, s59, s33
	v_lshl_add_u64 v[146:147], v[146:147], 0, s[8:9]
	s_mov_b32 m0, s26
	s_nop 0
	global_load_lds_dwordx4 v[146:147], off
	s_add_i32 m0, s26, 0x2000
	s_add_u32 s24, s24, 0x40080
	v_lshl_add_u64 v[146:147], v[216:217], 0, s[8:9]
	s_addc_u32 s25, s25, 0
	s_add_i32 s26, s60, s33
	global_load_lds_dwordx4 v[146:147], off
	v_lshl_add_u64 v[146:147], s[24:25], 0, v[132:133]
	s_mov_b32 m0, s26
	s_nop 0
	global_load_lds_dwordx4 v[146:147], off
	v_lshl_add_u64 v[146:147], s[24:25], 0, v[128:129]
	s_add_i32 m0, s26, 0x2000
	s_nop 0
	global_load_lds_dwordx4 v[146:147], off
	v_lshl_add_u64 v[146:147], v[218:219], 0, s[8:9]
	s_mov_b32 m0, s41
	s_nop 0
	global_load_lds_dwordx4 v[146:147], off
	v_lshl_add_u64 v[146:147], v[220:221], 0, s[8:9]
	s_mov_b32 m0, s42
	s_nop 0
	global_load_lds_dwordx4 v[146:147], off
	ds_read_b128 v[184:187], v151 offset:49152
	ds_read_b128 v[188:191], v151 offset:50176
	ds_read_b128 v[192:195], v151 offset:51200
	ds_read_b128 v[196:199], v151 offset:52224
	ds_read_b128 v[200:203], v151 offset:53248
	ds_read_b128 v[204:207], v151 offset:54272
	ds_read_b128 v[208:211], v151 offset:55296
	ds_read_b128 v[212:215], v151 offset:56320
	s_waitcnt vmcnt(8)
	s_waitcnt lgkmcnt(0)
	s_barrier
	s_setprio 1
	s_waitcnt lgkmcnt(0)
	v_mfma_f32_16x16x32_bf16 v[60:63], v[152:155], v[184:187], v[60:63]
	v_mfma_f32_16x16x32_bf16 v[56:59], v[160:163], v[184:187], v[56:59]
	v_mfma_f32_16x16x32_bf16 v[44:47], v[152:155], v[192:195], v[44:47]
	v_mfma_f32_16x16x32_bf16 v[40:43], v[160:163], v[192:195], v[40:43]
	v_mfma_f32_16x16x32_bf16 v[28:31], v[152:155], v[200:203], v[28:31]
	v_mfma_f32_16x16x32_bf16 v[24:27], v[160:163], v[200:203], v[24:27]
	v_mfma_f32_16x16x32_bf16 v[12:15], v[152:155], v[208:211], v[12:15]
	v_mfma_f32_16x16x32_bf16 v[8:11], v[160:163], v[208:211], v[8:11]
	v_mfma_f32_16x16x32_bf16 v[60:63], v[156:159], v[188:191], v[60:63]
	v_mfma_f32_16x16x32_bf16 v[56:59], v[164:167], v[188:191], v[56:59]
	v_mfma_f32_16x16x32_bf16 v[44:47], v[156:159], v[196:199], v[44:47]
	v_mfma_f32_16x16x32_bf16 v[40:43], v[164:167], v[196:199], v[40:43]
	v_mfma_f32_16x16x32_bf16 v[28:31], v[156:159], v[204:207], v[28:31]
	v_mfma_f32_16x16x32_bf16 v[24:27], v[164:167], v[204:207], v[24:27]
	v_mfma_f32_16x16x32_bf16 v[12:15], v[156:159], v[212:215], v[12:15]
	v_mfma_f32_16x16x32_bf16 v[8:11], v[164:167], v[212:215], v[8:11]
	s_setprio 0
	s_setprio 1
	v_mfma_f32_16x16x32_bf16 v[52:55], v[168:171], v[184:187], v[52:55]
	v_mfma_f32_16x16x32_bf16 v[48:51], v[176:179], v[184:187], v[48:51]
	v_mfma_f32_16x16x32_bf16 v[36:39], v[168:171], v[192:195], v[36:39]
	v_mfma_f32_16x16x32_bf16 v[32:35], v[176:179], v[192:195], v[32:35]
	v_mfma_f32_16x16x32_bf16 v[20:23], v[168:171], v[200:203], v[20:23]
	v_mfma_f32_16x16x32_bf16 v[16:19], v[176:179], v[200:203], v[16:19]
	v_mfma_f32_16x16x32_bf16 v[4:7], v[168:171], v[208:211], v[4:7]
	v_mfma_f32_16x16x32_bf16 v[0:3], v[176:179], v[208:211], v[0:3]
	v_mfma_f32_16x16x32_bf16 v[52:55], v[172:175], v[188:191], v[52:55]
	v_mfma_f32_16x16x32_bf16 v[48:51], v[180:183], v[188:191], v[48:51]
	v_mfma_f32_16x16x32_bf16 v[36:39], v[172:175], v[196:199], v[36:39]
	v_mfma_f32_16x16x32_bf16 v[32:35], v[180:183], v[196:199], v[32:35]
	v_mfma_f32_16x16x32_bf16 v[20:23], v[172:175], v[204:207], v[20:23]
	v_mfma_f32_16x16x32_bf16 v[16:19], v[180:183], v[204:207], v[16:19]
	v_mfma_f32_16x16x32_bf16 v[4:7], v[172:175], v[212:215], v[4:7]
	v_mfma_f32_16x16x32_bf16 v[0:3], v[180:183], v[212:215], v[0:3]
	s_setprio 0
	s_barrier
	s_add_i32 s58, s58, 2
	s_add_u32 s56, s56, 0x100
	s_addc_u32 s57, s57, 0
	s_add_u32 s22, s22, 0x100
	s_addc_u32 s23, s23, 0
	s_cmp_lt_u32 s58, 14
	s_cbranch_scc1 .LBB12_9
	s_andn2_b64 vcc, exec, s[10:11]
	s_cbranch_vccnz .LBB12_12
	s_barrier

.LBB13_19:
	s_ashr_i32 s17, s16, 31
	v_cmp_lt_i64_e32 vcc, s[0:1], v[142:143]
	s_lshl_b64 s[0:1], s[16:17], 21
	s_add_u32 s18, s33, s0
	s_addc_u32 s19, s34, s1
	s_and_b64 s[0:1], vcc, exec
	s_cselect_b32 s17, s19, s27
	s_cselect_b32 s53, s18, s26
	s_ashr_i32 s15, s14, 31
	s_lshl_b64 s[0:1], s[14:15], 21
	s_add_u32 s20, s4, s0
	s_addc_u32 s21, s5, s1
	s_and_b64 s[0:1], vcc, exec
	s_cselect_b32 s15, s21, s25
	s_cselect_b32 s54, s20, s24
	s_add_u32 s55, s24, 0x100
	s_addc_u32 s56, s25, 0
	s_add_u32 s24, s26, 0x100080
	s_addc_u32 s25, s27, 0
	s_mov_b32 s57, -2
	s_add_u32 s26, s24, 0xfff00080
	s_addc_u32 s27, s25, -1
	s_cmp_eq_u32 s57, 60
	s_cselect_b32 s29, s17, s27
	s_cselect_b32 s28, s53, s26
	s_cselect_b32 s27, s15, s56
	s_cselect_b32 s26, s54, s55
	v_lshl_add_u64 v[146:147], s[24:25], 0, v[140:141]
	s_add_i32 m0, s35, 0xc000
	s_nop 0
	global_load_lds_dwordx4 v[146:147], off
	v_lshl_add_u64 v[146:147], s[24:25], 0, v[138:139]
	s_add_i32 m0, s35, 0xe000
	s_nop 0
	global_load_lds_dwordx4 v[146:147], off
	ds_read_b128 v[152:155], v149
	ds_read_b128 v[156:159], v149 offset:1024
	ds_read_b128 v[160:163], v149 offset:2048
	ds_read_b128 v[164:167], v149 offset:3072
	ds_read_b128 v[168:171], v150
	ds_read_b128 v[172:175], v150 offset:1024
	ds_read_b128 v[176:179], v150 offset:2048
	ds_read_b128 v[180:183], v150 offset:3072
	ds_read_b128 v[184:187], v151
	ds_read_b128 v[188:191], v151 offset:1024
	ds_read_b128 v[192:195], v151 offset:2048
	ds_read_b128 v[196:199], v151 offset:3072
	ds_read_b128 v[200:203], v151 offset:4096
	ds_read_b128 v[204:207], v151 offset:5120
	ds_read_b128 v[208:211], v151 offset:6144
	ds_read_b128 v[212:215], v151 offset:7168
	s_waitcnt vmcnt(8)
	s_waitcnt lgkmcnt(0)
	s_barrier
	s_setprio 1
	s_waitcnt lgkmcnt(0)
	v_mfma_f32_16x16x32_bf16 v[124:127], v[152:155], v[184:187], 0
	v_mfma_f32_16x16x32_bf16 v[120:123], v[160:163], v[184:187], 0
	v_mfma_f32_16x16x32_bf16 v[116:119], v[152:155], v[192:195], 0
	v_mfma_f32_16x16x32_bf16 v[108:111], v[160:163], v[192:195], 0
	v_mfma_f32_16x16x32_bf16 v[100:103], v[152:155], v[200:203], 0
	v_mfma_f32_16x16x32_bf16 v[92:95], v[160:163], v[200:203], 0
	v_mfma_f32_16x16x32_bf16 v[84:87], v[152:155], v[208:211], 0
	v_mfma_f32_16x16x32_bf16 v[76:79], v[160:163], v[208:211], 0
	v_mfma_f32_16x16x32_bf16 v[124:127], v[156:159], v[188:191], v[124:127]
	v_mfma_f32_16x16x32_bf16 v[120:123], v[164:167], v[188:191], v[120:123]
	v_mfma_f32_16x16x32_bf16 v[116:119], v[156:159], v[196:199], v[116:119]
	v_mfma_f32_16x16x32_bf16 v[108:111], v[164:167], v[196:199], v[108:111]
	v_mfma_f32_16x16x32_bf16 v[100:103], v[156:159], v[204:207], v[100:103]
	v_mfma_f32_16x16x32_bf16 v[92:95], v[164:167], v[204:207], v[92:95]
	v_mfma_f32_16x16x32_bf16 v[84:87], v[156:159], v[212:215], v[84:87]
	v_mfma_f32_16x16x32_bf16 v[76:79], v[164:167], v[212:215], v[76:79]
	s_setprio 0
	s_setprio 1
	v_mfma_f32_16x16x32_bf16 v[112:115], v[168:171], v[184:187], 0
	v_mfma_f32_16x16x32_bf16 v[104:107], v[176:179], v[184:187], 0
	v_mfma_f32_16x16x32_bf16 v[96:99], v[168:171], v[192:195], 0
	v_mfma_f32_16x16x32_bf16 v[88:91], v[176:179], v[192:195], 0
	v_mfma_f32_16x16x32_bf16 v[80:83], v[168:171], v[200:203], 0
	v_mfma_f32_16x16x32_bf16 v[72:75], v[176:179], v[200:203], 0
	v_mfma_f32_16x16x32_bf16 v[68:71], v[168:171], v[208:211], 0
	v_mfma_f32_16x16x32_bf16 v[64:67], v[176:179], v[208:211], 0
	v_mfma_f32_16x16x32_bf16 v[112:115], v[172:175], v[188:191], v[112:115]
	v_mfma_f32_16x16x32_bf16 v[104:107], v[180:183], v[188:191], v[104:107]
	v_mfma_f32_16x16x32_bf16 v[96:99], v[172:175], v[196:199], v[96:99]
	v_mfma_f32_16x16x32_bf16 v[88:91], v[180:183], v[196:199], v[88:91]
	v_mfma_f32_16x16x32_bf16 v[80:83], v[172:175], v[204:207], v[80:83]
	v_mfma_f32_16x16x32_bf16 v[72:75], v[180:183], v[204:207], v[72:75]
	v_mfma_f32_16x16x32_bf16 v[68:71], v[172:175], v[212:215], v[68:71]
	v_mfma_f32_16x16x32_bf16 v[64:67], v[180:183], v[212:215], v[64:67]
	s_setprio 0
	s_barrier
	s_add_i32 s58, s46, s31
	v_lshl_add_u64 v[146:147], s[26:27], 0, v[130:131]
	s_mov_b32 m0, s58
	s_nop 0
	global_load_lds_dwordx4 v[146:147], off
	s_add_i32 m0, s58, 0x2000
	s_add_u32 s58, s26, 0x100000
	v_lshl_add_u64 v[216:217], s[26:27], 0, v[134:135]
	s_addc_u32 s59, s27, 0
	s_add_i32 s60, s47, s31
	global_load_lds_dwordx4 v[216:217], off
	v_lshl_add_u64 v[218:219], s[58:59], 0, v[130:131]
	s_mov_b32 m0, s60
	v_lshl_add_u64 v[220:221], s[28:29], 0, v[132:133]
	global_load_lds_dwordx4 v[218:219], off
	v_lshl_add_u64 v[218:219], s[58:59], 0, v[134:135]
	s_add_i32 m0, s60, 0x2000
	s_nop 0
	global_load_lds_dwordx4 v[218:219], off
	v_lshl_add_u64 v[218:219], s[28:29], 0, v[128:129]
	s_mov_b32 m0, s35
	s_nop 0
	global_load_lds_dwordx4 v[218:219], off
	s_mov_b32 m0, s36
	s_nop 0
	global_load_lds_dwordx4 v[220:221], off
	ds_read_b128 v[184:187], v151 offset:16384
	ds_read_b128 v[188:191], v151 offset:17408
	ds_read_b128 v[192:195], v151 offset:18432
	ds_read_b128 v[196:199], v151 offset:19456
	ds_read_b128 v[200:203], v151 offset:20480
	ds_read_b128 v[204:207], v151 offset:21504
	ds_read_b128 v[208:211], v151 offset:22528
	ds_read_b128 v[212:215], v151 offset:23552
	s_waitcnt vmcnt(8)
	s_waitcnt lgkmcnt(0)
	s_barrier
	s_setprio 1
	s_waitcnt lgkmcnt(0)
	v_mfma_f32_16x16x32_bf16 v[60:63], v[152:155], v[184:187], 0
	v_mfma_f32_16x16x32_bf16 v[56:59], v[160:163], v[184:187], 0
	v_mfma_f32_16x16x32_bf16 v[52:55], v[152:155], v[192:195], 0
	v_mfma_f32_16x16x32_bf16 v[44:47], v[160:163], v[192:195], 0
	v_mfma_f32_16x16x32_bf16 v[36:39], v[152:155], v[200:203], 0
	v_mfma_f32_16x16x32_bf16 v[28:31], v[160:163], v[200:203], 0
	v_mfma_f32_16x16x32_bf16 v[20:23], v[152:155], v[208:211], 0
	v_mfma_f32_16x16x32_bf16 v[12:15], v[160:163], v[208:211], 0
	v_mfma_f32_16x16x32_bf16 v[60:63], v[156:159], v[188:191], v[60:63]
	v_mfma_f32_16x16x32_bf16 v[56:59], v[164:167], v[188:191], v[56:59]
	v_mfma_f32_16x16x32_bf16 v[52:55], v[156:159], v[196:199], v[52:55]
	v_mfma_f32_16x16x32_bf16 v[44:47], v[164:167], v[196:199], v[44:47]
	v_mfma_f32_16x16x32_bf16 v[36:39], v[156:159], v[204:207], v[36:39]
	v_mfma_f32_16x16x32_bf16 v[28:31], v[164:167], v[204:207], v[28:31]
	v_mfma_f32_16x16x32_bf16 v[20:23], v[156:159], v[212:215], v[20:23]
	v_mfma_f32_16x16x32_bf16 v[12:15], v[164:167], v[212:215], v[12:15]
	s_setprio 0
	s_setprio 1
	v_mfma_f32_16x16x32_bf16 v[48:51], v[168:171], v[184:187], 0
	v_mfma_f32_16x16x32_bf16 v[40:43], v[176:179], v[184:187], 0
	v_mfma_f32_16x16x32_bf16 v[32:35], v[168:171], v[192:195], 0
	v_mfma_f32_16x16x32_bf16 v[24:27], v[176:179], v[192:195], 0
	v_mfma_f32_16x16x32_bf16 v[16:19], v[168:171], v[200:203], 0
	v_mfma_f32_16x16x32_bf16 v[8:11], v[176:179], v[200:203], 0
	v_mfma_f32_16x16x32_bf16 v[4:7], v[168:171], v[208:211], 0
	v_mfma_f32_16x16x32_bf16 v[0:3], v[176:179], v[208:211], 0
	v_mfma_f32_16x16x32_bf16 v[48:51], v[172:175], v[188:191], v[48:51]
	v_mfma_f32_16x16x32_bf16 v[40:43], v[180:183], v[188:191], v[40:43]
	v_mfma_f32_16x16x32_bf16 v[32:35], v[172:175], v[196:199], v[32:35]
	v_mfma_f32_16x16x32_bf16 v[24:27], v[180:183], v[196:199], v[24:27]
	v_mfma_f32_16x16x32_bf16 v[16:19], v[172:175], v[204:207], v[16:19]
	v_mfma_f32_16x16x32_bf16 v[8:11], v[180:183], v[204:207], v[8:11]
	v_mfma_f32_16x16x32_bf16 v[4:7], v[172:175], v[212:215], v[4:7]
	v_mfma_f32_16x16x32_bf16 v[0:3], v[180:183], v[212:215], v[0:3]
	s_setprio 0
	s_barrier
	s_add_i32 s58, 0, 0x18000
	s_add_i32 s59, 0, 0x1c000
	v_add_u32_e32 v164, s58, v148
	v_add_u32_e32 v180, s59, v148
	s_add_u32 s28, s28, 0x100000
	s_addc_u32 s29, s29, 0
	s_mov_b32 m0, s37
	v_lshl_add_u64 v[222:223], s[28:29], 0, v[128:129]
	global_load_lds_dwordx4 v[222:223], off
	v_lshl_add_u64 v[222:223], s[28:29], 0, v[132:133]
	s_mov_b32 m0, s38
	s_nop 0
	global_load_lds_dwordx4 v[222:223], off
	ds_read_b128 v[152:155], v164
	ds_read_b128 v[156:159], v164 offset:1024
	ds_read_b128 v[160:163], v164 offset:2048
	ds_read_b128 v[164:167], v164 offset:3072
	ds_read_b128 v[168:171], v180
	ds_read_b128 v[172:175], v180 offset:1024
	ds_read_b128 v[176:179], v180 offset:2048
	ds_read_b128 v[180:183], v180 offset:3072
	ds_read_b128 v[184:187], v151 offset:32768
	ds_read_b128 v[188:191], v151 offset:33792
	ds_read_b128 v[192:195], v151 offset:34816
	ds_read_b128 v[196:199], v151 offset:35840
	ds_read_b128 v[200:203], v151 offset:36864
	ds_read_b128 v[204:207], v151 offset:37888
	ds_read_b128 v[208:211], v151 offset:38912
	ds_read_b128 v[212:215], v151 offset:39936
	s_waitcnt vmcnt(8)
	s_waitcnt lgkmcnt(0)
	s_barrier
	s_setprio 1
	s_waitcnt lgkmcnt(0)
	v_mfma_f32_16x16x32_bf16 v[124:127], v[152:155], v[184:187], v[124:127]
	v_mfma_f32_16x16x32_bf16 v[120:123], v[160:163], v[184:187], v[120:123]
	v_mfma_f32_16x16x32_bf16 v[116:119], v[152:155], v[192:195], v[116:119]
	v_mfma_f32_16x16x32_bf16 v[108:111], v[160:163], v[192:195], v[108:111]
	v_mfma_f32_16x16x32_bf16 v[100:103], v[152:155], v[200:203], v[100:103]
	v_mfma_f32_16x16x32_bf16 v[92:95], v[160:163], v[200:203], v[92:95]
	v_mfma_f32_16x16x32_bf16 v[84:87], v[152:155], v[208:211], v[84:87]
	v_mfma_f32_16x16x32_bf16 v[76:79], v[160:163], v[208:211], v[76:79]
	v_mfma_f32_16x16x32_bf16 v[124:127], v[156:159], v[188:191], v[124:127]
	v_mfma_f32_16x16x32_bf16 v[120:123], v[164:167], v[188:191], v[120:123]
	v_mfma_f32_16x16x32_bf16 v[116:119], v[156:159], v[196:199], v[116:119]
	v_mfma_f32_16x16x32_bf16 v[108:111], v[164:167], v[196:199], v[108:111]
	v_mfma_f32_16x16x32_bf16 v[100:103], v[156:159], v[204:207], v[100:103]
	v_mfma_f32_16x16x32_bf16 v[92:95], v[164:167], v[204:207], v[92:95]
	v_mfma_f32_16x16x32_bf16 v[84:87], v[156:159], v[212:215], v[84:87]
	v_mfma_f32_16x16x32_bf16 v[76:79], v[164:167], v[212:215], v[76:79]
	s_setprio 0
	s_setprio 1
	v_mfma_f32_16x16x32_bf16 v[112:115], v[168:171], v[184:187], v[112:115]
	v_mfma_f32_16x16x32_bf16 v[104:107], v[176:179], v[184:187], v[104:107]
	v_mfma_f32_16x16x32_bf16 v[96:99], v[168:171], v[192:195], v[96:99]
	v_mfma_f32_16x16x32_bf16 v[88:91], v[176:179], v[192:195], v[88:91]
	v_mfma_f32_16x16x32_bf16 v[80:83], v[168:171], v[200:203], v[80:83]
	v_mfma_f32_16x16x32_bf16 v[72:75], v[176:179], v[200:203], v[72:75]
	v_mfma_f32_16x16x32_bf16 v[68:71], v[168:171], v[208:211], v[68:71]
	v_mfma_f32_16x16x32_bf16 v[64:67], v[176:179], v[208:211], v[64:67]
	v_mfma_f32_16x16x32_bf16 v[112:115], v[172:175], v[188:191], v[112:115]
	v_mfma_f32_16x16x32_bf16 v[104:107], v[180:183], v[188:191], v[104:107]
	v_mfma_f32_16x16x32_bf16 v[96:99], v[172:175], v[196:199], v[96:99]
	v_mfma_f32_16x16x32_bf16 v[88:91], v[180:183], v[196:199], v[88:91]
	v_mfma_f32_16x16x32_bf16 v[80:83], v[172:175], v[204:207], v[80:83]
	v_mfma_f32_16x16x32_bf16 v[72:75], v[180:183], v[204:207], v[72:75]
	v_mfma_f32_16x16x32_bf16 v[68:71], v[172:175], v[212:215], v[68:71]
	v_mfma_f32_16x16x32_bf16 v[64:67], v[180:183], v[212:215], v[64:67]
	s_setprio 0
	s_barrier
	s_add_i32 s28, s58, s31
	v_lshl_add_u64 v[146:147], v[146:147], 0, s[10:11]
	s_mov_b32 m0, s28
	s_nop 0
	global_load_lds_dwordx4 v[146:147], off
	s_add_i32 m0, s28, 0x2000
	s_add_u32 s26, s26, 0x100080
	v_lshl_add_u64 v[146:147], v[216:217], 0, s[10:11]
	s_addc_u32 s27, s27, 0
	s_add_i32 s28, s59, s31
	global_load_lds_dwordx4 v[146:147], off
	v_lshl_add_u64 v[146:147], s[26:27], 0, v[130:131]
	s_mov_b32 m0, s28
	s_nop 0
	global_load_lds_dwordx4 v[146:147], off
	v_lshl_add_u64 v[146:147], s[26:27], 0, v[134:135]
	s_add_i32 m0, s28, 0x2000
	s_nop 0
	global_load_lds_dwordx4 v[146:147], off
	v_lshl_add_u64 v[146:147], v[218:219], 0, s[10:11]
	s_mov_b32 m0, s41
	s_nop 0
	global_load_lds_dwordx4 v[146:147], off
	v_lshl_add_u64 v[146:147], v[220:221], 0, s[10:11]
	s_mov_b32 m0, s42
	s_nop 0
	global_load_lds_dwordx4 v[146:147], off
	ds_read_b128 v[184:187], v151 offset:49152
	ds_read_b128 v[188:191], v151 offset:50176
	ds_read_b128 v[192:195], v151 offset:51200
	ds_read_b128 v[196:199], v151 offset:52224
	ds_read_b128 v[200:203], v151 offset:53248
	ds_read_b128 v[204:207], v151 offset:54272
	ds_read_b128 v[208:211], v151 offset:55296
	ds_read_b128 v[212:215], v151 offset:56320
	s_waitcnt vmcnt(8)
	s_waitcnt lgkmcnt(0)
	s_barrier
	s_setprio 1
	s_waitcnt lgkmcnt(0)
	v_mfma_f32_16x16x32_bf16 v[60:63], v[152:155], v[184:187], v[60:63]
	v_mfma_f32_16x16x32_bf16 v[56:59], v[160:163], v[184:187], v[56:59]
	v_mfma_f32_16x16x32_bf16 v[52:55], v[152:155], v[192:195], v[52:55]
	v_mfma_f32_16x16x32_bf16 v[44:47], v[160:163], v[192:195], v[44:47]
	v_mfma_f32_16x16x32_bf16 v[36:39], v[152:155], v[200:203], v[36:39]
	v_mfma_f32_16x16x32_bf16 v[28:31], v[160:163], v[200:203], v[28:31]
	v_mfma_f32_16x16x32_bf16 v[20:23], v[152:155], v[208:211], v[20:23]
	v_mfma_f32_16x16x32_bf16 v[12:15], v[160:163], v[208:211], v[12:15]
	v_mfma_f32_16x16x32_bf16 v[60:63], v[156:159], v[188:191], v[60:63]
	v_mfma_f32_16x16x32_bf16 v[56:59], v[164:167], v[188:191], v[56:59]
	v_mfma_f32_16x16x32_bf16 v[52:55], v[156:159], v[196:199], v[52:55]
	v_mfma_f32_16x16x32_bf16 v[44:47], v[164:167], v[196:199], v[44:47]
	v_mfma_f32_16x16x32_bf16 v[36:39], v[156:159], v[204:207], v[36:39]
	v_mfma_f32_16x16x32_bf16 v[28:31], v[164:167], v[204:207], v[28:31]
	v_mfma_f32_16x16x32_bf16 v[20:23], v[156:159], v[212:215], v[20:23]
	v_mfma_f32_16x16x32_bf16 v[12:15], v[164:167], v[212:215], v[12:15]
	s_setprio 0
	s_setprio 1
	v_mfma_f32_16x16x32_bf16 v[48:51], v[168:171], v[184:187], v[48:51]
	v_mfma_f32_16x16x32_bf16 v[40:43], v[176:179], v[184:187], v[40:43]
	v_mfma_f32_16x16x32_bf16 v[32:35], v[168:171], v[192:195], v[32:35]
	v_mfma_f32_16x16x32_bf16 v[24:27], v[176:179], v[192:195], v[24:27]
	v_mfma_f32_16x16x32_bf16 v[16:19], v[168:171], v[200:203], v[16:19]
	v_mfma_f32_16x16x32_bf16 v[8:11], v[176:179], v[200:203], v[8:11]
	v_mfma_f32_16x16x32_bf16 v[4:7], v[168:171], v[208:211], v[4:7]
	v_mfma_f32_16x16x32_bf16 v[0:3], v[176:179], v[208:211], v[0:3]
	v_mfma_f32_16x16x32_bf16 v[48:51], v[172:175], v[188:191], v[48:51]
	v_mfma_f32_16x16x32_bf16 v[40:43], v[180:183], v[188:191], v[40:43]
	v_mfma_f32_16x16x32_bf16 v[32:35], v[172:175], v[196:199], v[32:35]
	v_mfma_f32_16x16x32_bf16 v[24:27], v[180:183], v[196:199], v[24:27]
	v_mfma_f32_16x16x32_bf16 v[16:19], v[172:175], v[204:207], v[16:19]
	v_mfma_f32_16x16x32_bf16 v[8:11], v[180:183], v[204:207], v[8:11]
	v_mfma_f32_16x16x32_bf16 v[4:7], v[172:175], v[212:215], v[4:7]
	v_mfma_f32_16x16x32_bf16 v[0:3], v[180:183], v[212:215], v[0:3]
	s_setprio 0
	s_barrier
	s_add_i32 s57, s57, 2
	s_add_u32 s55, s55, 0x100
	s_addc_u32 s56, s56, 0
	s_add_u32 s24, s24, 0x100
	s_addc_u32 s25, s25, 0
	s_cmp_lt_u32 s57, 62
.LBB13_20:
	s_add_u32 s26, s24, 0xfff00080
	s_addc_u32 s27, s25, -1
	s_cmp_eq_u32 s57, 60
	s_cselect_b32 s29, s17, s27
	s_cselect_b32 s28, s53, s26
	s_cselect_b32 s27, s15, s56
	s_cselect_b32 s26, s54, s55
	v_lshl_add_u64 v[146:147], s[24:25], 0, v[140:141]
	s_add_i32 m0, s35, 0xc000
	s_nop 0
	global_load_lds_dwordx4 v[146:147], off
	v_lshl_add_u64 v[146:147], s[24:25], 0, v[138:139]
	s_add_i32 m0, s35, 0xe000
	s_nop 0
	global_load_lds_dwordx4 v[146:147], off
	ds_read_b128 v[152:155], v149
	ds_read_b128 v[156:159], v149 offset:1024
	ds_read_b128 v[160:163], v149 offset:2048
	ds_read_b128 v[164:167], v149 offset:3072
	ds_read_b128 v[168:171], v150
	ds_read_b128 v[172:175], v150 offset:1024
	ds_read_b128 v[176:179], v150 offset:2048
	ds_read_b128 v[180:183], v150 offset:3072
	ds_read_b128 v[184:187], v151
	ds_read_b128 v[188:191], v151 offset:1024
	ds_read_b128 v[192:195], v151 offset:2048
	ds_read_b128 v[196:199], v151 offset:3072
	ds_read_b128 v[200:203], v151 offset:4096
	ds_read_b128 v[204:207], v151 offset:5120
	ds_read_b128 v[208:211], v151 offset:6144
	ds_read_b128 v[212:215], v151 offset:7168
	s_waitcnt vmcnt(8)
	s_waitcnt lgkmcnt(0)
	s_barrier
	s_setprio 1
	s_waitcnt lgkmcnt(0)
	v_mfma_f32_16x16x32_bf16 v[124:127], v[152:155], v[184:187], v[124:127]
	v_mfma_f32_16x16x32_bf16 v[120:123], v[160:163], v[184:187], v[120:123]
	v_mfma_f32_16x16x32_bf16 v[116:119], v[152:155], v[192:195], v[116:119]
	v_mfma_f32_16x16x32_bf16 v[108:111], v[160:163], v[192:195], v[108:111]
	v_mfma_f32_16x16x32_bf16 v[100:103], v[152:155], v[200:203], v[100:103]
	v_mfma_f32_16x16x32_bf16 v[92:95], v[160:163], v[200:203], v[92:95]
	v_mfma_f32_16x16x32_bf16 v[84:87], v[152:155], v[208:211], v[84:87]
	v_mfma_f32_16x16x32_bf16 v[76:79], v[160:163], v[208:211], v[76:79]
	v_mfma_f32_16x16x32_bf16 v[124:127], v[156:159], v[188:191], v[124:127]
	v_mfma_f32_16x16x32_bf16 v[120:123], v[164:167], v[188:191], v[120:123]
	v_mfma_f32_16x16x32_bf16 v[116:119], v[156:159], v[196:199], v[116:119]
	v_mfma_f32_16x16x32_bf16 v[108:111], v[164:167], v[196:199], v[108:111]
	v_mfma_f32_16x16x32_bf16 v[100:103], v[156:159], v[204:207], v[100:103]
	v_mfma_f32_16x16x32_bf16 v[92:95], v[164:167], v[204:207], v[92:95]
	v_mfma_f32_16x16x32_bf16 v[84:87], v[156:159], v[212:215], v[84:87]
	v_mfma_f32_16x16x32_bf16 v[76:79], v[164:167], v[212:215], v[76:79]
	s_setprio 0
	s_setprio 1
	v_mfma_f32_16x16x32_bf16 v[112:115], v[168:171], v[184:187], v[112:115]
	v_mfma_f32_16x16x32_bf16 v[104:107], v[176:179], v[184:187], v[104:107]
	v_mfma_f32_16x16x32_bf16 v[96:99], v[168:171], v[192:195], v[96:99]
	v_mfma_f32_16x16x32_bf16 v[88:91], v[176:179], v[192:195], v[88:91]
	v_mfma_f32_16x16x32_bf16 v[80:83], v[168:171], v[200:203], v[80:83]
	v_mfma_f32_16x16x32_bf16 v[72:75], v[176:179], v[200:203], v[72:75]
	v_mfma_f32_16x16x32_bf16 v[68:71], v[168:171], v[208:211], v[68:71]
	v_mfma_f32_16x16x32_bf16 v[64:67], v[176:179], v[208:211], v[64:67]
	v_mfma_f32_16x16x32_bf16 v[112:115], v[172:175], v[188:191], v[112:115]
	v_mfma_f32_16x16x32_bf16 v[104:107], v[180:183], v[188:191], v[104:107]
	v_mfma_f32_16x16x32_bf16 v[96:99], v[172:175], v[196:199], v[96:99]
	v_mfma_f32_16x16x32_bf16 v[88:91], v[180:183], v[196:199], v[88:91]
	v_mfma_f32_16x16x32_bf16 v[80:83], v[172:175], v[204:207], v[80:83]
	v_mfma_f32_16x16x32_bf16 v[72:75], v[180:183], v[204:207], v[72:75]
	v_mfma_f32_16x16x32_bf16 v[68:71], v[172:175], v[212:215], v[68:71]
	v_mfma_f32_16x16x32_bf16 v[64:67], v[180:183], v[212:215], v[64:67]
	s_setprio 0
	s_barrier
	s_add_i32 s58, s46, s31
	v_lshl_add_u64 v[146:147], s[26:27], 0, v[130:131]
	s_mov_b32 m0, s58
	s_nop 0
	global_load_lds_dwordx4 v[146:147], off
	s_add_i32 m0, s58, 0x2000
	s_add_u32 s58, s26, 0x100000
	v_lshl_add_u64 v[216:217], s[26:27], 0, v[134:135]
	s_addc_u32 s59, s27, 0
	s_add_i32 s60, s47, s31
	global_load_lds_dwordx4 v[216:217], off
	v_lshl_add_u64 v[218:219], s[58:59], 0, v[130:131]
	s_mov_b32 m0, s60
	v_lshl_add_u64 v[220:221], s[28:29], 0, v[132:133]
	global_load_lds_dwordx4 v[218:219], off
	v_lshl_add_u64 v[218:219], s[58:59], 0, v[134:135]
	s_add_i32 m0, s60, 0x2000
	s_nop 0
	global_load_lds_dwordx4 v[218:219], off
	v_lshl_add_u64 v[218:219], s[28:29], 0, v[128:129]
	s_mov_b32 m0, s35
	s_nop 0
	global_load_lds_dwordx4 v[218:219], off
	s_mov_b32 m0, s36
	s_nop 0
	global_load_lds_dwordx4 v[220:221], off
	ds_read_b128 v[184:187], v151 offset:16384
	ds_read_b128 v[188:191], v151 offset:17408
	ds_read_b128 v[192:195], v151 offset:18432
	ds_read_b128 v[196:199], v151 offset:19456
	ds_read_b128 v[200:203], v151 offset:20480
	ds_read_b128 v[204:207], v151 offset:21504
	ds_read_b128 v[208:211], v151 offset:22528
	ds_read_b128 v[212:215], v151 offset:23552
	s_waitcnt vmcnt(8)
	s_waitcnt lgkmcnt(0)
	s_barrier
	s_setprio 1
	s_waitcnt lgkmcnt(0)
	v_mfma_f32_16x16x32_bf16 v[60:63], v[152:155], v[184:187], v[60:63]
	v_mfma_f32_16x16x32_bf16 v[56:59], v[160:163], v[184:187], v[56:59]
	v_mfma_f32_16x16x32_bf16 v[52:55], v[152:155], v[192:195], v[52:55]
	v_mfma_f32_16x16x32_bf16 v[44:47], v[160:163], v[192:195], v[44:47]
	v_mfma_f32_16x16x32_bf16 v[36:39], v[152:155], v[200:203], v[36:39]
	v_mfma_f32_16x16x32_bf16 v[28:31], v[160:163], v[200:203], v[28:31]
	v_mfma_f32_16x16x32_bf16 v[20:23], v[152:155], v[208:211], v[20:23]
	v_mfma_f32_16x16x32_bf16 v[12:15], v[160:163], v[208:211], v[12:15]
	v_mfma_f32_16x16x32_bf16 v[60:63], v[156:159], v[188:191], v[60:63]
	v_mfma_f32_16x16x32_bf16 v[56:59], v[164:167], v[188:191], v[56:59]
	v_mfma_f32_16x16x32_bf16 v[52:55], v[156:159], v[196:199], v[52:55]
	v_mfma_f32_16x16x32_bf16 v[44:47], v[164:167], v[196:199], v[44:47]
	v_mfma_f32_16x16x32_bf16 v[36:39], v[156:159], v[204:207], v[36:39]
	v_mfma_f32_16x16x32_bf16 v[28:31], v[164:167], v[204:207], v[28:31]
	v_mfma_f32_16x16x32_bf16 v[20:23], v[156:159], v[212:215], v[20:23]
	v_mfma_f32_16x16x32_bf16 v[12:15], v[164:167], v[212:215], v[12:15]
	s_setprio 0
	s_setprio 1
	v_mfma_f32_16x16x32_bf16 v[48:51], v[168:171], v[184:187], v[48:51]
	v_mfma_f32_16x16x32_bf16 v[40:43], v[176:179], v[184:187], v[40:43]
	v_mfma_f32_16x16x32_bf16 v[32:35], v[168:171], v[192:195], v[32:35]
	v_mfma_f32_16x16x32_bf16 v[24:27], v[176:179], v[192:195], v[24:27]
	v_mfma_f32_16x16x32_bf16 v[16:19], v[168:171], v[200:203], v[16:19]
	v_mfma_f32_16x16x32_bf16 v[8:11], v[176:179], v[200:203], v[8:11]
	v_mfma_f32_16x16x32_bf16 v[4:7], v[168:171], v[208:211], v[4:7]
	v_mfma_f32_16x16x32_bf16 v[0:3], v[176:179], v[208:211], v[0:3]
	v_mfma_f32_16x16x32_bf16 v[48:51], v[172:175], v[188:191], v[48:51]
	v_mfma_f32_16x16x32_bf16 v[40:43], v[180:183], v[188:191], v[40:43]
	v_mfma_f32_16x16x32_bf16 v[32:35], v[172:175], v[196:199], v[32:35]
	v_mfma_f32_16x16x32_bf16 v[24:27], v[180:183], v[196:199], v[24:27]
	v_mfma_f32_16x16x32_bf16 v[16:19], v[172:175], v[204:207], v[16:19]
	v_mfma_f32_16x16x32_bf16 v[8:11], v[180:183], v[204:207], v[8:11]
	v_mfma_f32_16x16x32_bf16 v[4:7], v[172:175], v[212:215], v[4:7]
	v_mfma_f32_16x16x32_bf16 v[0:3], v[180:183], v[212:215], v[0:3]
	s_setprio 0
	s_barrier
	s_add_i32 s58, 0, 0x18000
	s_add_i32 s59, 0, 0x1c000
	v_add_u32_e32 v164, s58, v148
	v_add_u32_e32 v180, s59, v148
	s_add_u32 s28, s28, 0x100000
	s_addc_u32 s29, s29, 0
	s_mov_b32 m0, s37
	v_lshl_add_u64 v[222:223], s[28:29], 0, v[128:129]
	global_load_lds_dwordx4 v[222:223], off
	v_lshl_add_u64 v[222:223], s[28:29], 0, v[132:133]
	s_mov_b32 m0, s38
	s_nop 0
	global_load_lds_dwordx4 v[222:223], off
	ds_read_b128 v[152:155], v164
	ds_read_b128 v[156:159], v164 offset:1024
	ds_read_b128 v[160:163], v164 offset:2048
	ds_read_b128 v[164:167], v164 offset:3072
	ds_read_b128 v[168:171], v180
	ds_read_b128 v[172:175], v180 offset:1024
	ds_read_b128 v[176:179], v180 offset:2048
	ds_read_b128 v[180:183], v180 offset:3072
	ds_read_b128 v[184:187], v151 offset:32768
	ds_read_b128 v[188:191], v151 offset:33792
	ds_read_b128 v[192:195], v151 offset:34816
	ds_read_b128 v[196:199], v151 offset:35840
	ds_read_b128 v[200:203], v151 offset:36864
	ds_read_b128 v[204:207], v151 offset:37888
	ds_read_b128 v[208:211], v151 offset:38912
	ds_read_b128 v[212:215], v151 offset:39936
	s_waitcnt vmcnt(8)
	s_waitcnt lgkmcnt(0)
	s_barrier
	s_setprio 1
	s_waitcnt lgkmcnt(0)
	v_mfma_f32_16x16x32_bf16 v[124:127], v[152:155], v[184:187], v[124:127]
	v_mfma_f32_16x16x32_bf16 v[120:123], v[160:163], v[184:187], v[120:123]
	v_mfma_f32_16x16x32_bf16 v[116:119], v[152:155], v[192:195], v[116:119]
	v_mfma_f32_16x16x32_bf16 v[108:111], v[160:163], v[192:195], v[108:111]
	v_mfma_f32_16x16x32_bf16 v[100:103], v[152:155], v[200:203], v[100:103]
	v_mfma_f32_16x16x32_bf16 v[92:95], v[160:163], v[200:203], v[92:95]
	v_mfma_f32_16x16x32_bf16 v[84:87], v[152:155], v[208:211], v[84:87]
	v_mfma_f32_16x16x32_bf16 v[76:79], v[160:163], v[208:211], v[76:79]
	v_mfma_f32_16x16x32_bf16 v[124:127], v[156:159], v[188:191], v[124:127]
	v_mfma_f32_16x16x32_bf16 v[120:123], v[164:167], v[188:191], v[120:123]
	v_mfma_f32_16x16x32_bf16 v[116:119], v[156:159], v[196:199], v[116:119]
	v_mfma_f32_16x16x32_bf16 v[108:111], v[164:167], v[196:199], v[108:111]
	v_mfma_f32_16x16x32_bf16 v[100:103], v[156:159], v[204:207], v[100:103]
	v_mfma_f32_16x16x32_bf16 v[92:95], v[164:167], v[204:207], v[92:95]
	v_mfma_f32_16x16x32_bf16 v[84:87], v[156:159], v[212:215], v[84:87]
	v_mfma_f32_16x16x32_bf16 v[76:79], v[164:167], v[212:215], v[76:79]
	s_setprio 0
	s_setprio 1
	v_mfma_f32_16x16x32_bf16 v[112:115], v[168:171], v[184:187], v[112:115]
	v_mfma_f32_16x16x32_bf16 v[104:107], v[176:179], v[184:187], v[104:107]
	v_mfma_f32_16x16x32_bf16 v[96:99], v[168:171], v[192:195], v[96:99]
	v_mfma_f32_16x16x32_bf16 v[88:91], v[176:179], v[192:195], v[88:91]
	v_mfma_f32_16x16x32_bf16 v[80:83], v[168:171], v[200:203], v[80:83]
	v_mfma_f32_16x16x32_bf16 v[72:75], v[176:179], v[200:203], v[72:75]
	v_mfma_f32_16x16x32_bf16 v[68:71], v[168:171], v[208:211], v[68:71]
	v_mfma_f32_16x16x32_bf16 v[64:67], v[176:179], v[208:211], v[64:67]
	v_mfma_f32_16x16x32_bf16 v[112:115], v[172:175], v[188:191], v[112:115]
	v_mfma_f32_16x16x32_bf16 v[104:107], v[180:183], v[188:191], v[104:107]
	v_mfma_f32_16x16x32_bf16 v[96:99], v[172:175], v[196:199], v[96:99]
	v_mfma_f32_16x16x32_bf16 v[88:91], v[180:183], v[196:199], v[88:91]
	v_mfma_f32_16x16x32_bf16 v[80:83], v[172:175], v[204:207], v[80:83]
	v_mfma_f32_16x16x32_bf16 v[72:75], v[180:183], v[204:207], v[72:75]
	v_mfma_f32_16x16x32_bf16 v[68:71], v[172:175], v[212:215], v[68:71]
	v_mfma_f32_16x16x32_bf16 v[64:67], v[180:183], v[212:215], v[64:67]
	s_setprio 0
	s_barrier
	s_add_i32 s28, s58, s31
	v_lshl_add_u64 v[146:147], v[146:147], 0, s[10:11]
	s_mov_b32 m0, s28
	s_nop 0
	global_load_lds_dwordx4 v[146:147], off
	s_add_i32 m0, s28, 0x2000
	s_add_u32 s26, s26, 0x100080
	v_lshl_add_u64 v[146:147], v[216:217], 0, s[10:11]
	s_addc_u32 s27, s27, 0
	s_add_i32 s28, s59, s31
	global_load_lds_dwordx4 v[146:147], off
	v_lshl_add_u64 v[146:147], s[26:27], 0, v[130:131]
	s_mov_b32 m0, s28
	s_nop 0
	global_load_lds_dwordx4 v[146:147], off
	v_lshl_add_u64 v[146:147], s[26:27], 0, v[134:135]
	s_add_i32 m0, s28, 0x2000
	s_nop 0
	global_load_lds_dwordx4 v[146:147], off
	v_lshl_add_u64 v[146:147], v[218:219], 0, s[10:11]
	s_mov_b32 m0, s41
	s_nop 0
	global_load_lds_dwordx4 v[146:147], off
	v_lshl_add_u64 v[146:147], v[220:221], 0, s[10:11]
	s_mov_b32 m0, s42
	s_nop 0
	global_load_lds_dwordx4 v[146:147], off
	ds_read_b128 v[184:187], v151 offset:49152
	ds_read_b128 v[188:191], v151 offset:50176
	ds_read_b128 v[192:195], v151 offset:51200
	ds_read_b128 v[196:199], v151 offset:52224
	ds_read_b128 v[200:203], v151 offset:53248
	ds_read_b128 v[204:207], v151 offset:54272
	ds_read_b128 v[208:211], v151 offset:55296
	ds_read_b128 v[212:215], v151 offset:56320
	s_waitcnt vmcnt(8)
	s_waitcnt lgkmcnt(0)
	s_barrier
	s_setprio 1
	s_waitcnt lgkmcnt(0)
	v_mfma_f32_16x16x32_bf16 v[60:63], v[152:155], v[184:187], v[60:63]
	v_mfma_f32_16x16x32_bf16 v[56:59], v[160:163], v[184:187], v[56:59]
	v_mfma_f32_16x16x32_bf16 v[52:55], v[152:155], v[192:195], v[52:55]
	v_mfma_f32_16x16x32_bf16 v[44:47], v[160:163], v[192:195], v[44:47]
	v_mfma_f32_16x16x32_bf16 v[36:39], v[152:155], v[200:203], v[36:39]
	v_mfma_f32_16x16x32_bf16 v[28:31], v[160:163], v[200:203], v[28:31]
	v_mfma_f32_16x16x32_bf16 v[20:23], v[152:155], v[208:211], v[20:23]
	v_mfma_f32_16x16x32_bf16 v[12:15], v[160:163], v[208:211], v[12:15]
	v_mfma_f32_16x16x32_bf16 v[60:63], v[156:159], v[188:191], v[60:63]
	v_mfma_f32_16x16x32_bf16 v[56:59], v[164:167], v[188:191], v[56:59]
	v_mfma_f32_16x16x32_bf16 v[52:55], v[156:159], v[196:199], v[52:55]
	v_mfma_f32_16x16x32_bf16 v[44:47], v[164:167], v[196:199], v[44:47]
	v_mfma_f32_16x16x32_bf16 v[36:39], v[156:159], v[204:207], v[36:39]
	v_mfma_f32_16x16x32_bf16 v[28:31], v[164:167], v[204:207], v[28:31]
	v_mfma_f32_16x16x32_bf16 v[20:23], v[156:159], v[212:215], v[20:23]
	v_mfma_f32_16x16x32_bf16 v[12:15], v[164:167], v[212:215], v[12:15]
	s_setprio 0
	s_setprio 1
	v_mfma_f32_16x16x32_bf16 v[48:51], v[168:171], v[184:187], v[48:51]
	v_mfma_f32_16x16x32_bf16 v[40:43], v[176:179], v[184:187], v[40:43]
	v_mfma_f32_16x16x32_bf16 v[32:35], v[168:171], v[192:195], v[32:35]
	v_mfma_f32_16x16x32_bf16 v[24:27], v[176:179], v[192:195], v[24:27]
	v_mfma_f32_16x16x32_bf16 v[16:19], v[168:171], v[200:203], v[16:19]
	v_mfma_f32_16x16x32_bf16 v[8:11], v[176:179], v[200:203], v[8:11]
	v_mfma_f32_16x16x32_bf16 v[4:7], v[168:171], v[208:211], v[4:7]
	v_mfma_f32_16x16x32_bf16 v[0:3], v[176:179], v[208:211], v[0:3]
	v_mfma_f32_16x16x32_bf16 v[48:51], v[172:175], v[188:191], v[48:51]
	v_mfma_f32_16x16x32_bf16 v[40:43], v[180:183], v[188:191], v[40:43]
	v_mfma_f32_16x16x32_bf16 v[32:35], v[172:175], v[196:199], v[32:35]
	v_mfma_f32_16x16x32_bf16 v[24:27], v[180:183], v[196:199], v[24:27]
	v_mfma_f32_16x16x32_bf16 v[16:19], v[172:175], v[204:207], v[16:19]
	v_mfma_f32_16x16x32_bf16 v[8:11], v[180:183], v[204:207], v[8:11]
	v_mfma_f32_16x16x32_bf16 v[4:7], v[172:175], v[212:215], v[4:7]
	v_mfma_f32_16x16x32_bf16 v[0:3], v[180:183], v[212:215], v[0:3]
	s_setprio 0
	s_barrier
	s_add_i32 s57, s57, 2
	s_add_u32 s55, s55, 0x100
	s_addc_u32 s56, s56, 0
	s_add_u32 s24, s24, 0x100
	s_addc_u32 s25, s25, 0
	s_cmp_lt_u32 s57, 62
	s_cbranch_scc1 .LBB13_20
	s_andn2_b64 vcc, exec, s[12:13]
	s_cbranch_vccnz .LBB13_23
	s_barrier
